# full-line (8 rows x 128B) epilogue stores for G1/G5/G8/G14 via B-tile row remap + DPP half-row swap; on top of barrier hoist + g2 rewrite
# speedup vs baseline: 1.0202x; 1.0063x over previous
.LBB0_147:
	s_or_b64 exec, exec, s[0:1]
	v_readlane_b32 s0, v248, 10
	s_ashr_i32 s0, s0, 31
	v_readlane_b32 s1, v248, 11
	v_writelane_b32 v247, s0, 11
	s_ashr_i32 s0, s42, 31
	v_writelane_b32 v247, s0, 8
	s_add_u32 s0, s58, 0x12900000
	s_addc_u32 s1, s59, 0
	v_writelane_b32 v247, s0, 9
	v_mov_b32_e32 v8, v202
	s_waitcnt lgkmcnt(0)
	v_writelane_b32 v247, s1, 10
	s_add_u32 s0, s58, 0x17100000
	s_addc_u32 s1, s59, 0
	s_barrier
	s_cmpk_lt_i32 s42, 0x360
	v_writelane_b32 v248, s0, 63
	v_readfirstlane_b32 s22, v8
	s_nop 0
	v_writelane_b32 v247, s1, 0
	s_cbranch_scc0 .LBB0_159
	v_lshlrev_b32_e32 v0, 4, v8
	v_add_u32_e32 v1, 0x2000, v0
	v_readlane_b32 s1, v247, 8
	v_ashrrev_i32_e32 v2, 31, v1
	s_lshr_b32 s1, s1, 29
	v_lshrrev_b32_e32 v2, 22, v2
	s_add_i32 s1, s42, s1
	v_add_u32_e32 v2, v1, v2
	s_ashr_i32 s0, s22, 6
	s_ashr_i32 s2, s1, 3
	s_and_b32 s1, s1, -8
	v_ashrrev_i32_e32 v9, 10, v2
	s_ashr_i32 s3, s22, 8
	s_lshl_b32 s23, s0, 10
	s_sub_i32 s1, s42, s1
	v_mul_i32_i24_e32 v2, 0x400, v9
	s_cmp_lt_i32 s1, 0
	s_movk_i32 s24, 0x6d
	v_sub_u32_e32 v1, v1, v2
	s_cselect_b32 s6, s24, 0x6c
	v_lshrrev_b32_e32 v2, 4, v1
	s_mul_i32 s1, s6, s1
	v_bitop3_b32 v1, v2, v1, 32 bitop3:0x6c
	s_add_i32 s1, s1, s2
	v_ashrrev_i32_e32 v2, 31, v1
	s_mul_hi_i32 s2, s1, 0x2aaaaaab
	v_lshrrev_b32_e32 v2, 26, v2
	s_lshr_b32 s6, s2, 31
	s_ashr_i32 s2, s2, 5
	v_add_u32_e32 v2, v1, v2
	v_lshlrev_b32_e32 v3, 3, v9
	s_add_i32 s2, s2, s6
	v_ashrrev_i32_e32 v10, 6, v2
	v_and_b32_e32 v3, -16, v3
	s_lshl_b32 s8, s2, 3
	s_mulk_i32 s2, 0xc0
	v_add_u32_e32 v3, v10, v3
	s_sub_i32 s1, s1, s2
	v_and_b32_e32 v4, 3, v10
	s_mov_b32 s2, 0xfffe0
	v_lshrrev_b32_e32 v5, 2, v3
	v_lshlrev_b32_e32 v6, 1, v3
	v_and_b32_e32 v2, 0xc0, v2
	v_and_or_b32 v4, v3, s2, v4
	v_and_b32_e32 v5, 4, v5
	v_and_b32_e32 v6, 24, v6
	v_sub_u32_e32 v1, v1, v2
	v_mov_b32_e32 v2, 1
	v_or3_b32 v4, v4, v5, v6
	v_lshlrev_b32_e32 v5, 5, v9
	v_ashrrev_i16_sdwa v1, v2, sext(v1) dst_sel:DWORD dst_unused:UNUSED_PAD src0_sel:DWORD src1_sel:BYTE_0
	v_and_b32_e32 v5, 32, v5
	v_bfe_i32 v11, v1, 0, 16
	v_add_lshl_u32 v1, v5, v11, 1
	v_lshl_add_u32 v128, v4, 12, v1
	v_lshl_add_u32 v130, v3, 12, v1
	v_bfe_i32 v1, v8, 27, 1
	v_lshrrev_b32_e32 v1, 22, v1
	v_add_u32_e32 v1, v0, v1
	v_and_b32_e32 v1, 0xfffffc00, v1
	v_sub_u32_e32 v0, v0, v1
	v_lshrrev_b32_e32 v1, 4, v0
	v_ashrrev_i32_e32 v3, 31, v8
	v_bitop3_b32 v0, v1, v0, 32 bitop3:0x6c
	v_lshrrev_b32_e32 v3, 26, v3
	v_ashrrev_i32_e32 v1, 31, v0
	v_add_u32_e32 v3, v8, v3
	v_lshrrev_b32_e32 v1, 26, v1
	v_ashrrev_i32_e32 v13, 6, v3
	v_add_u32_e32 v1, v0, v1
	v_lshlrev_b32_e32 v3, 3, v13
	v_ashrrev_i32_e32 v12, 6, v1
	v_and_b32_e32 v3, -16, v3
	v_add_u32_e32 v3, v12, v3
	v_and_b32_e32 v4, 3, v12
	v_lshrrev_b32_e32 v5, 2, v3
	v_lshlrev_b32_e32 v6, 1, v3
	v_and_b32_e32 v1, 0xc0, v1
	v_and_or_b32 v4, v3, s2, v4
	v_and_b32_e32 v5, 4, v5
	v_and_b32_e32 v6, 24, v6
	v_sub_u32_e32 v0, v0, v1
	s_sub_i32 s6, 36, s8
	v_or3_b32 v4, v4, v5, v6
	v_lshlrev_b32_e32 v5, 5, v13
	v_ashrrev_i16_sdwa v0, v2, sext(v0) dst_sel:DWORD dst_unused:UNUSED_PAD src0_sel:DWORD src1_sel:BYTE_0
	s_min_u32 s9, s6, 8
	v_and_b32_e32 v5, 32, v5
	v_bfe_i32 v14, v0, 0, 16
	v_add_lshl_u32 v0, v5, v14, 1
	v_cvt_f32_ubyte0_e32 v2, s9
	v_lshl_add_u32 v132, v4, 12, v0
	v_cvt_f32_i32_e32 v1, s1
	v_rcp_iflag_f32_e32 v4, v2
	v_lshl_add_u32 v134, v3, 12, v0
	s_ashr_i32 s2, s1, 30
	s_or_b32 s2, s2, 1
	v_mul_f32_e32 v0, v1, v4
	v_trunc_f32_e32 v0, v0
	v_fma_f32 v1, -v0, v2, v1
	v_cvt_i32_f32_e32 v0, v0
	v_cmp_ge_f32_e64 s[6:7], |v1|, v2
	s_and_b64 s[6:7], s[6:7], exec
	s_cselect_b32 s2, s2, 0
	v_readfirstlane_b32 s6, v0
	s_add_i32 s2, s6, s2
	s_mul_i32 s6, s2, s9
	s_sub_i32 s1, s1, s6
	s_sext_i32_i16 s1, s1
	s_add_i32 s6, s8, s1
	s_ashr_i32 s7, s6, 31
	s_bfe_i64 s[10:11], s[2:3], 0x100000
	s_lshl_b64 s[8:9], s[6:7], 20
	s_lshl_b64 s[10:11], s[10:11], 20
	s_add_u32 s18, s58, s10
	s_addc_u32 s19, s59, s11
	s_add_i32 s7, s23, 0
	s_add_i32 m0, s7, 0x10000
	v_readlane_b32 s10, v247, 9
	v_mov_b32_e32 v230, s3
	v_lshlrev_b32_e32 v230, 17, v230
	v_add_u32_e32 v132, v132, v230
	v_add_u32_e32 v230, 0x40000, v230
	v_add_u32_e32 v128, v128, v230
	global_load_lds_dwordx4 v132, s[18:19]
	s_add_i32 m0, s7, 0x12000
	v_readlane_b32 s11, v247, 10
	s_add_u32 s16, s10, s8
	global_load_lds_dwordx4 v128, s[18:19]
	s_addc_u32 s17, s11, s9
	s_mov_b32 m0, s7
	s_add_i32 s25, s7, 0x2000
	global_load_lds_dwordx4 v134, s[16:17]
	s_mov_b32 m0, s25
	s_add_u32 s8, s18, 0x20000
	global_load_lds_dwordx4 v130, s[16:17]
	s_addc_u32 s9, s19, 0
	s_add_i32 m0, s7, 0x14000
	v_mov_b32_e32 v133, 0
	global_load_lds_dwordx4 v132, s[8:9]
	s_add_i32 m0, s7, 0x16000
	v_mov_b32_e32 v129, v133
	global_load_lds_dwordx4 v128, s[8:9]
	s_add_u32 s8, s16, 0x80000
	s_addc_u32 s9, s17, 0
	s_add_i32 s26, s7, 0x4000
	s_mov_b32 m0, s26
	s_add_i32 s27, s7, 0x6000
	global_load_lds_dwordx4 v134, s[8:9]
	s_mov_b32 m0, s27
	v_mov_b32_e32 v135, v133
	global_load_lds_dwordx4 v130, s[8:9]
	v_mov_b32_e32 v131, v133
	s_mov_b32 s28, 0
	v_lshl_add_u64 v[6:7], s[18:19], 0, v[132:133]
	v_lshl_add_u64 v[4:5], s[18:19], 0, v[128:129]
	v_lshl_add_u64 v[2:3], s[16:17], 0, v[134:135]
	s_cmp_lg_u32 s3, 1
	v_lshl_add_u64 v[0:1], s[16:17], 0, v[130:131]
	s_cbranch_scc1 .LBB0_150
	s_barrier
.LBB0_150:
	s_lshl_b32 s0, s0, 5
	s_and_b32 s11, s0, 0x60
	s_mov_b64 s[0:1], 0x80
	s_add_i32 m0, s7, 0x18000
	v_lshl_add_u64 v[6:7], v[6:7], 0, s[0:1]
	s_lshl_b32 s10, s3, 13
	s_lshl_b32 s12, s11, 7
	s_waitcnt vmcnt(4)
	s_barrier
	global_load_lds_dwordx4 v[6:7], off
	v_lshl_add_u64 v[4:5], v[4:5], 0, s[0:1]
	s_add_i32 m0, s7, 0x1a000
	s_add_i32 s29, s7, 0x8000
	s_add_i32 s30, s7, 0xa000
	global_load_lds_dwordx4 v[4:5], off
	v_lshl_add_u64 v[2:3], v[2:3], 0, s[0:1]
	s_mov_b32 m0, s29
	s_add_u32 s8, s18, 0x20080
	global_load_lds_dwordx4 v[2:3], off
	v_lshl_add_u64 v[0:1], v[0:1], 0, s[0:1]
	s_mov_b32 m0, s30
	s_addc_u32 s9, s19, 0
	global_load_lds_dwordx4 v[0:1], off
	s_add_i32 m0, s7, 0x1c000
	v_lshl_add_u64 v[0:1], s[8:9], 0, v[132:133]
	global_load_lds_dwordx4 v[0:1], off
	v_lshl_add_u64 v[0:1], s[8:9], 0, v[128:129]
	s_add_i32 m0, s7, 0x1e000
	s_add_i32 s31, 0, 0x10000
	global_load_lds_dwordx4 v[0:1], off
	v_lshrrev_b32_e32 v1, 1, v8
	v_and_b32_e32 v1, 24, v1
	v_and_b32_e32 v0, 15, v8
	v_lshlrev_b32_e32 v2, 1, v1
	v_lshl_or_b32 v144, s3, 6, v0
	v_lshl_or_b32 v0, v0, 6, v2
	v_lshlrev_b32_e32 v2, 2, v8
	v_and_b32_e32 v2, 32, v2
	v_bitop3_b32 v3, v0, s10, v2 bitop3:0xde
	v_bitop3_b32 v145, v0, s12, v2 bitop3:0xde
	v_lshlrev_b32_e32 v0, 15, v13
	v_and_b32_e32 v0, 0xffff0000, v0
	v_or_b32_e32 v146, s11, v1
	v_lshl_add_u32 v0, v12, 12, v0
	v_and_b32_e32 v1, 1, v13
	v_lshl_or_b32 v0, v1, 6, v0
	v_lshl_add_u32 v136, v14, 1, v0
	v_lshlrev_b32_e32 v0, 15, v9
	v_and_b32_e32 v0, 0xffff0000, v0
	s_waitcnt vmcnt(6)
	v_lshl_add_u32 v0, v10, 12, v0
	v_and_b32_e32 v1, 1, v9
	v_lshl_or_b32 v0, v1, 6, v0
	s_add_i32 s33, 0, 0x14000
	s_sext_i32_i16 s35, s2
	v_mov_b32_e32 v137, v133
	v_lshl_add_u32 v138, v11, 1, v0
	v_mov_b32_e32 v139, v133
	v_mov_b64_e32 v[140:141], 0x360
	v_mov_b64_e32 v[142:143], 0x35f
	v_add_u32_e32 v147, s31, v145
	v_add_u32_e32 v148, 0, v3
	v_add_u32_e32 v149, s33, v145
	s_movk_i32 s34, 0x3000
	s_barrier
	s_waitcnt vmcnt(0)

.LBB0_154:
	ds_read_b128 v[150:153], v147
	ds_read_b128 v[154:157], v147 offset:1024
	ds_read_b128 v[158:161], v147 offset:2048
	ds_read_b128 v[162:165], v147 offset:3072
	s_add_u32 s18, s16, 0xfff80080
	s_addc_u32 s19, s17, -1
	s_cmp_eq_u32 s40, 28
	s_cselect_b32 s21, s11, s19
	s_cselect_b32 s20, s36, s18
	s_cselect_b32 s19, s9, s39
	s_cselect_b32 s18, s37, s38
	v_lshl_add_u64 v[198:199], s[16:17], 0, v[136:137]
	s_add_i32 m0, s7, 0xc000
	ds_read_b128 v[166:169], v148
	ds_read_b128 v[170:173], v148 offset:1024
	ds_read_b128 v[174:177], v148 offset:2048
	ds_read_b128 v[178:181], v148 offset:3072
	ds_read_b128 v[182:185], v148 offset:4096
	ds_read_b128 v[186:189], v148 offset:5120
	ds_read_b128 v[190:193], v148 offset:6144
	ds_read_b128 v[194:197], v148 offset:7168
	global_load_lds_dwordx4 v[198:199], off
	v_lshl_add_u64 v[198:199], s[16:17], 0, v[138:139]
	s_add_i32 m0, s7, 0xe000
	s_nop 0
	global_load_lds_dwordx4 v[198:199], off
	s_waitcnt lgkmcnt(8)
	s_barrier
	s_waitcnt lgkmcnt(0)
	s_setprio 1
	s_waitcnt lgkmcnt(0)
	v_mfma_f32_16x16x32_bf16 v[124:127], v[150:153], v[166:169], v[124:127]
	v_mfma_f32_16x16x32_bf16 v[120:123], v[158:161], v[166:169], v[120:123]
	v_mfma_f32_16x16x32_bf16 v[116:119], v[150:153], v[174:177], v[116:119]
	v_mfma_f32_16x16x32_bf16 v[112:115], v[158:161], v[174:177], v[112:115]
	v_mfma_f32_16x16x32_bf16 v[100:103], v[150:153], v[182:185], v[100:103]
	v_mfma_f32_16x16x32_bf16 v[96:99], v[158:161], v[182:185], v[96:99]
	v_mfma_f32_16x16x32_bf16 v[84:87], v[150:153], v[190:193], v[84:87]
	v_mfma_f32_16x16x32_bf16 v[80:83], v[158:161], v[190:193], v[80:83]
	v_mfma_f32_16x16x32_bf16 v[124:127], v[154:157], v[170:173], v[124:127]
	v_mfma_f32_16x16x32_bf16 v[120:123], v[162:165], v[170:173], v[120:123]
	v_mfma_f32_16x16x32_bf16 v[116:119], v[154:157], v[178:181], v[116:119]
	v_mfma_f32_16x16x32_bf16 v[112:115], v[162:165], v[178:181], v[112:115]
	v_mfma_f32_16x16x32_bf16 v[100:103], v[154:157], v[186:189], v[100:103]
	v_mfma_f32_16x16x32_bf16 v[96:99], v[162:165], v[186:189], v[96:99]
	v_mfma_f32_16x16x32_bf16 v[84:87], v[154:157], v[194:197], v[84:87]
	v_mfma_f32_16x16x32_bf16 v[80:83], v[162:165], v[194:197], v[80:83]
	s_setprio 0
	s_barrier
	s_add_i32 s41, s31, s23
	v_lshl_add_u64 v[216:217], s[18:19], 0, v[132:133]
	s_mov_b32 m0, s41
	ds_read_b128 v[198:201], v149
	ds_read_b128 v[204:207], v149 offset:1024
	ds_read_b128 v[208:211], v149 offset:2048
	ds_read_b128 v[212:215], v149 offset:3072
	global_load_lds_dwordx4 v[216:217], off
	v_lshl_add_u64 v[218:219], s[18:19], 0, v[128:129]
	s_add_i32 m0, s41, 0x2000
	s_nop 0
	global_load_lds_dwordx4 v[218:219], off
	s_barrier
	s_waitcnt lgkmcnt(0)
	s_setprio 1
	s_waitcnt lgkmcnt(0)
	v_mfma_f32_16x16x32_bf16 v[108:111], v[198:201], v[166:169], v[108:111]
	v_mfma_f32_16x16x32_bf16 v[104:107], v[208:211], v[166:169], v[104:107]
	v_mfma_f32_16x16x32_bf16 v[92:95], v[198:201], v[174:177], v[92:95]
	v_mfma_f32_16x16x32_bf16 v[88:91], v[208:211], v[174:177], v[88:91]
	v_mfma_f32_16x16x32_bf16 v[76:79], v[198:201], v[182:185], v[76:79]
	v_mfma_f32_16x16x32_bf16 v[72:75], v[208:211], v[182:185], v[72:75]
	v_mfma_f32_16x16x32_bf16 v[68:71], v[198:201], v[190:193], v[68:71]
	v_mfma_f32_16x16x32_bf16 v[64:67], v[208:211], v[190:193], v[64:67]
	v_mfma_f32_16x16x32_bf16 v[108:111], v[204:207], v[170:173], v[108:111]
	v_mfma_f32_16x16x32_bf16 v[104:107], v[212:215], v[170:173], v[104:107]
	v_mfma_f32_16x16x32_bf16 v[92:95], v[204:207], v[178:181], v[92:95]
	v_mfma_f32_16x16x32_bf16 v[88:91], v[212:215], v[178:181], v[88:91]
	v_mfma_f32_16x16x32_bf16 v[76:79], v[204:207], v[186:189], v[76:79]
	v_mfma_f32_16x16x32_bf16 v[72:75], v[212:215], v[186:189], v[72:75]
	v_mfma_f32_16x16x32_bf16 v[68:71], v[204:207], v[194:197], v[68:71]
	v_mfma_f32_16x16x32_bf16 v[64:67], v[212:215], v[194:197], v[64:67]
	s_setprio 0
	s_mov_b32 m0, s7
	v_lshl_add_u64 v[220:221], s[20:21], 0, v[134:135]
	s_barrier
	ds_read_b128 v[166:169], v148 offset:16384
	ds_read_b128 v[170:173], v148 offset:17408
	ds_read_b128 v[174:177], v148 offset:18432
	ds_read_b128 v[178:181], v148 offset:19456
	ds_read_b128 v[182:185], v148 offset:20480
	ds_read_b128 v[186:189], v148 offset:21504
	ds_read_b128 v[190:193], v148 offset:22528
	ds_read_b128 v[194:197], v148 offset:23552
	global_load_lds_dwordx4 v[220:221], off
	v_lshl_add_u64 v[222:223], s[20:21], 0, v[130:131]
	s_mov_b32 m0, s25
	s_nop 0
	global_load_lds_dwordx4 v[222:223], off
	s_barrier
	s_waitcnt lgkmcnt(0)
	s_setprio 1
	s_waitcnt lgkmcnt(0)
	v_mfma_f32_16x16x32_bf16 v[60:63], v[150:153], v[166:169], v[60:63]
	v_mfma_f32_16x16x32_bf16 v[56:59], v[158:161], v[166:169], v[56:59]
	v_mfma_f32_16x16x32_bf16 v[52:55], v[150:153], v[174:177], v[52:55]
	v_mfma_f32_16x16x32_bf16 v[48:51], v[158:161], v[174:177], v[48:51]
	v_mfma_f32_16x16x32_bf16 v[36:39], v[150:153], v[182:185], v[36:39]
	v_mfma_f32_16x16x32_bf16 v[32:35], v[158:161], v[182:185], v[32:35]
	v_mfma_f32_16x16x32_bf16 v[20:23], v[150:153], v[190:193], v[20:23]
	v_mfma_f32_16x16x32_bf16 v[16:19], v[158:161], v[190:193], v[16:19]
	v_mfma_f32_16x16x32_bf16 v[60:63], v[154:157], v[170:173], v[60:63]
	v_mfma_f32_16x16x32_bf16 v[56:59], v[162:165], v[170:173], v[56:59]
	v_mfma_f32_16x16x32_bf16 v[52:55], v[154:157], v[178:181], v[52:55]
	v_mfma_f32_16x16x32_bf16 v[48:51], v[162:165], v[178:181], v[48:51]
	v_mfma_f32_16x16x32_bf16 v[36:39], v[154:157], v[186:189], v[36:39]
	v_mfma_f32_16x16x32_bf16 v[32:35], v[162:165], v[186:189], v[32:35]
	v_mfma_f32_16x16x32_bf16 v[20:23], v[154:157], v[194:197], v[20:23]
	v_mfma_f32_16x16x32_bf16 v[16:19], v[162:165], v[194:197], v[16:19]
	s_setprio 0
	s_barrier
	s_add_u32 s42, s18, 0x20000
	s_addc_u32 s43, s19, 0
	s_add_i32 s41, s33, s23
	v_lshl_add_u64 v[150:151], s[42:43], 0, v[132:133]
	s_mov_b32 m0, s41
	s_nop 0
	global_load_lds_dwordx4 v[150:151], off
	v_lshl_add_u64 v[150:151], s[42:43], 0, v[128:129]
	s_add_i32 m0, s41, 0x2000
	s_nop 0
	global_load_lds_dwordx4 v[150:151], off
	s_waitcnt vmcnt(6)
	s_barrier
	s_setprio 1
	v_mfma_f32_16x16x32_bf16 v[44:47], v[198:201], v[166:169], v[44:47]
	v_mfma_f32_16x16x32_bf16 v[40:43], v[208:211], v[166:169], v[40:43]
	v_mfma_f32_16x16x32_bf16 v[28:31], v[198:201], v[174:177], v[28:31]
	v_mfma_f32_16x16x32_bf16 v[24:27], v[208:211], v[174:177], v[24:27]
	v_mfma_f32_16x16x32_bf16 v[12:15], v[198:201], v[182:185], v[12:15]
	v_mfma_f32_16x16x32_bf16 v[8:11], v[208:211], v[182:185], v[8:11]
	v_mfma_f32_16x16x32_bf16 v[4:7], v[198:201], v[190:193], v[4:7]
	v_mfma_f32_16x16x32_bf16 v[0:3], v[208:211], v[190:193], v[0:3]
	v_mfma_f32_16x16x32_bf16 v[44:47], v[204:207], v[170:173], v[44:47]
	v_mfma_f32_16x16x32_bf16 v[40:43], v[212:215], v[170:173], v[40:43]
	v_mfma_f32_16x16x32_bf16 v[28:31], v[204:207], v[178:181], v[28:31]
	v_mfma_f32_16x16x32_bf16 v[24:27], v[212:215], v[178:181], v[24:27]
	v_mfma_f32_16x16x32_bf16 v[12:15], v[204:207], v[186:189], v[12:15]
	v_mfma_f32_16x16x32_bf16 v[8:11], v[212:215], v[186:189], v[8:11]
	v_mfma_f32_16x16x32_bf16 v[4:7], v[204:207], v[194:197], v[4:7]
	v_mfma_f32_16x16x32_bf16 v[0:3], v[212:215], v[194:197], v[0:3]
	s_setprio 0
	s_add_i32 s41, 0, 0x18000
	v_add_u32_e32 v162, s41, v145
	s_barrier
	ds_read_b128 v[150:153], v162
	ds_read_b128 v[154:157], v162 offset:1024
	ds_read_b128 v[158:161], v162 offset:2048
	ds_read_b128 v[162:165], v162 offset:3072
	s_add_u32 s20, s20, 0x80000
	s_addc_u32 s21, s21, 0
	s_mov_b32 m0, s26
	v_lshl_add_u64 v[198:199], s[20:21], 0, v[134:135]
	ds_read_b128 v[166:169], v148 offset:32768
	ds_read_b128 v[170:173], v148 offset:33792
	ds_read_b128 v[174:177], v148 offset:34816
	ds_read_b128 v[178:181], v148 offset:35840
	ds_read_b128 v[182:185], v148 offset:36864
	ds_read_b128 v[186:189], v148 offset:37888
	ds_read_b128 v[190:193], v148 offset:38912
	ds_read_b128 v[194:197], v148 offset:39936
	global_load_lds_dwordx4 v[198:199], off
	v_lshl_add_u64 v[198:199], s[20:21], 0, v[130:131]
	s_mov_b32 m0, s27
	s_nop 0
	global_load_lds_dwordx4 v[198:199], off
	s_waitcnt lgkmcnt(8)
	s_barrier
	s_waitcnt lgkmcnt(0)
	s_setprio 1
	s_waitcnt lgkmcnt(0)
	v_mfma_f32_16x16x32_bf16 v[124:127], v[150:153], v[166:169], v[124:127]
	v_mfma_f32_16x16x32_bf16 v[120:123], v[158:161], v[166:169], v[120:123]
	v_mfma_f32_16x16x32_bf16 v[116:119], v[150:153], v[174:177], v[116:119]
	v_mfma_f32_16x16x32_bf16 v[112:115], v[158:161], v[174:177], v[112:115]
	v_mfma_f32_16x16x32_bf16 v[100:103], v[150:153], v[182:185], v[100:103]
	v_mfma_f32_16x16x32_bf16 v[96:99], v[158:161], v[182:185], v[96:99]
	v_mfma_f32_16x16x32_bf16 v[84:87], v[150:153], v[190:193], v[84:87]
	v_mfma_f32_16x16x32_bf16 v[80:83], v[158:161], v[190:193], v[80:83]
	v_mfma_f32_16x16x32_bf16 v[124:127], v[154:157], v[170:173], v[124:127]
	v_mfma_f32_16x16x32_bf16 v[120:123], v[162:165], v[170:173], v[120:123]
	v_mfma_f32_16x16x32_bf16 v[116:119], v[154:157], v[178:181], v[116:119]
	v_mfma_f32_16x16x32_bf16 v[112:115], v[162:165], v[178:181], v[112:115]
	v_mfma_f32_16x16x32_bf16 v[100:103], v[154:157], v[186:189], v[100:103]
	v_mfma_f32_16x16x32_bf16 v[96:99], v[162:165], v[186:189], v[96:99]
	v_mfma_f32_16x16x32_bf16 v[84:87], v[154:157], v[194:197], v[84:87]
	v_mfma_f32_16x16x32_bf16 v[80:83], v[162:165], v[194:197], v[80:83]
	s_setprio 0
	s_barrier
	s_add_i32 s20, 0, 0x1c000
	s_add_i32 s21, s41, s23
	v_add_u32_e32 v212, s20, v145
	v_lshl_add_u64 v[216:217], v[216:217], 0, s[0:1]
	s_mov_b32 m0, s21
	ds_read_b128 v[198:201], v212
	ds_read_b128 v[204:207], v212 offset:1024
	ds_read_b128 v[208:211], v212 offset:2048
	ds_read_b128 v[212:215], v212 offset:3072
	global_load_lds_dwordx4 v[216:217], off
	v_lshl_add_u64 v[216:217], v[218:219], 0, s[0:1]
	s_add_i32 m0, s21, 0x2000
	s_nop 0
	global_load_lds_dwordx4 v[216:217], off
	s_barrier
	s_waitcnt lgkmcnt(0)
	s_setprio 1
	s_waitcnt lgkmcnt(0)
	v_mfma_f32_16x16x32_bf16 v[108:111], v[198:201], v[166:169], v[108:111]
	v_mfma_f32_16x16x32_bf16 v[104:107], v[208:211], v[166:169], v[104:107]
	v_mfma_f32_16x16x32_bf16 v[92:95], v[198:201], v[174:177], v[92:95]
	v_mfma_f32_16x16x32_bf16 v[88:91], v[208:211], v[174:177], v[88:91]
	v_mfma_f32_16x16x32_bf16 v[76:79], v[198:201], v[182:185], v[76:79]
	v_mfma_f32_16x16x32_bf16 v[72:75], v[208:211], v[182:185], v[72:75]
	v_mfma_f32_16x16x32_bf16 v[68:71], v[198:201], v[190:193], v[68:71]
	v_mfma_f32_16x16x32_bf16 v[64:67], v[208:211], v[190:193], v[64:67]
	v_mfma_f32_16x16x32_bf16 v[108:111], v[204:207], v[170:173], v[108:111]
	v_mfma_f32_16x16x32_bf16 v[104:107], v[212:215], v[170:173], v[104:107]
	v_mfma_f32_16x16x32_bf16 v[92:95], v[204:207], v[178:181], v[92:95]
	v_mfma_f32_16x16x32_bf16 v[88:91], v[212:215], v[178:181], v[88:91]
	v_mfma_f32_16x16x32_bf16 v[76:79], v[204:207], v[186:189], v[76:79]
	v_mfma_f32_16x16x32_bf16 v[72:75], v[212:215], v[186:189], v[72:75]
	v_mfma_f32_16x16x32_bf16 v[68:71], v[204:207], v[194:197], v[68:71]
	v_mfma_f32_16x16x32_bf16 v[64:67], v[212:215], v[194:197], v[64:67]
	s_setprio 0
	s_mov_b32 m0, s29
	v_lshl_add_u64 v[216:217], v[220:221], 0, s[0:1]
	s_barrier
	ds_read_b128 v[166:169], v148 offset:49152
	ds_read_b128 v[170:173], v148 offset:50176
	ds_read_b128 v[174:177], v148 offset:51200
	ds_read_b128 v[178:181], v148 offset:52224
	ds_read_b128 v[182:185], v148 offset:53248
	ds_read_b128 v[186:189], v148 offset:54272
	ds_read_b128 v[190:193], v148 offset:55296
	ds_read_b128 v[194:197], v148 offset:56320
	global_load_lds_dwordx4 v[216:217], off
	v_lshl_add_u64 v[216:217], v[222:223], 0, s[0:1]
	s_mov_b32 m0, s30
	s_nop 0
	global_load_lds_dwordx4 v[216:217], off
	s_barrier
	s_waitcnt lgkmcnt(0)
	s_setprio 1
	s_waitcnt lgkmcnt(0)
	v_mfma_f32_16x16x32_bf16 v[60:63], v[150:153], v[166:169], v[60:63]
	v_mfma_f32_16x16x32_bf16 v[56:59], v[158:161], v[166:169], v[56:59]
	v_mfma_f32_16x16x32_bf16 v[52:55], v[150:153], v[174:177], v[52:55]
	v_mfma_f32_16x16x32_bf16 v[48:51], v[158:161], v[174:177], v[48:51]
	v_mfma_f32_16x16x32_bf16 v[36:39], v[150:153], v[182:185], v[36:39]
	v_mfma_f32_16x16x32_bf16 v[32:35], v[158:161], v[182:185], v[32:35]
	v_mfma_f32_16x16x32_bf16 v[20:23], v[150:153], v[190:193], v[20:23]
	v_mfma_f32_16x16x32_bf16 v[16:19], v[158:161], v[190:193], v[16:19]
	v_mfma_f32_16x16x32_bf16 v[60:63], v[154:157], v[170:173], v[60:63]
	v_mfma_f32_16x16x32_bf16 v[56:59], v[162:165], v[170:173], v[56:59]
	v_mfma_f32_16x16x32_bf16 v[52:55], v[154:157], v[178:181], v[52:55]
	v_mfma_f32_16x16x32_bf16 v[48:51], v[162:165], v[178:181], v[48:51]
	v_mfma_f32_16x16x32_bf16 v[36:39], v[154:157], v[186:189], v[36:39]
	v_mfma_f32_16x16x32_bf16 v[32:35], v[162:165], v[186:189], v[32:35]
	v_mfma_f32_16x16x32_bf16 v[20:23], v[154:157], v[194:197], v[20:23]
	v_mfma_f32_16x16x32_bf16 v[16:19], v[162:165], v[194:197], v[16:19]
	s_setprio 0
	s_barrier
	s_add_u32 s18, s18, 0x20080
	s_addc_u32 s19, s19, 0
	s_add_i32 s20, s20, s23
	v_lshl_add_u64 v[150:151], s[18:19], 0, v[132:133]
	s_mov_b32 m0, s20
	s_nop 0
	global_load_lds_dwordx4 v[150:151], off
	v_lshl_add_u64 v[150:151], s[18:19], 0, v[128:129]
	s_add_i32 m0, s20, 0x2000
	s_nop 0
	global_load_lds_dwordx4 v[150:151], off
	s_waitcnt vmcnt(6)
	s_barrier
	s_setprio 1
	v_mfma_f32_16x16x32_bf16 v[44:47], v[198:201], v[166:169], v[44:47]
	v_mfma_f32_16x16x32_bf16 v[40:43], v[208:211], v[166:169], v[40:43]
	v_mfma_f32_16x16x32_bf16 v[28:31], v[198:201], v[174:177], v[28:31]
	v_mfma_f32_16x16x32_bf16 v[24:27], v[208:211], v[174:177], v[24:27]
	v_mfma_f32_16x16x32_bf16 v[12:15], v[198:201], v[182:185], v[12:15]
	v_mfma_f32_16x16x32_bf16 v[8:11], v[208:211], v[182:185], v[8:11]
	v_mfma_f32_16x16x32_bf16 v[4:7], v[198:201], v[190:193], v[4:7]
	v_mfma_f32_16x16x32_bf16 v[0:3], v[208:211], v[190:193], v[0:3]
	v_mfma_f32_16x16x32_bf16 v[44:47], v[204:207], v[170:173], v[44:47]
	v_mfma_f32_16x16x32_bf16 v[40:43], v[212:215], v[170:173], v[40:43]
	v_mfma_f32_16x16x32_bf16 v[28:31], v[204:207], v[178:181], v[28:31]
	v_mfma_f32_16x16x32_bf16 v[24:27], v[212:215], v[178:181], v[24:27]
	v_mfma_f32_16x16x32_bf16 v[12:15], v[204:207], v[186:189], v[12:15]
	v_mfma_f32_16x16x32_bf16 v[8:11], v[212:215], v[186:189], v[8:11]
	v_mfma_f32_16x16x32_bf16 v[4:7], v[204:207], v[194:197], v[4:7]
	v_mfma_f32_16x16x32_bf16 v[0:3], v[212:215], v[194:197], v[0:3]
	s_setprio 0
	s_add_i32 s40, s40, 2
	s_add_u32 s16, s16, 0x100
	s_addc_u32 s17, s17, 0
	s_add_u32 s38, s38, 0x100
	s_addc_u32 s39, s39, 0
	s_cmp_gt_u32 s40, 29
	s_barrier
	s_cbranch_scc0 .LBB0_154
	v_readlane_b32 s100, v248, 63
	v_readlane_b32 s101, v247, 0
	v_and_b32_e32 v242, 15, v202
	v_bfe_u32 v243, v202, 4, 2
	v_bfe_u32 v244, v202, 6, 2
	v_lshrrev_b32_e32 v245, 8, v202
	v_and_b32_e32 v240, 7, v242
	v_lshl_add_u32 v240, v245, 6, v240
	v_lshl_add_u32 v240, s6, 8, v240
	v_mul_u32_u24_e32 v240, 0x3000, v240
	v_lshrrev_b32_e32 v241, 3, v242
	v_lshlrev_b32_e32 v241, 6, v241
	v_lshl_add_u32 v241, v244, 7, v241
	v_lshl_add_u32 v241, v243, 4, v241
	v_add_u32_e32 v240, v240, v241
	s_lshl_b32 s98, s35, 9
	v_add_u32_e32 v240, s98, v240
	v_cvt_pk_bf16_f32 v228, v124, v125
	v_cvt_pk_bf16_f32 v229, v126, v127
	v_cvt_pk_bf16_f32 v230, v120, v121
	v_cvt_pk_bf16_f32 v231, v122, v123
	v_cvt_pk_bf16_f32 v232, v108, v109
	v_cvt_pk_bf16_f32 v233, v110, v111
	v_cvt_pk_bf16_f32 v234, v104, v105
	v_cvt_pk_bf16_f32 v235, v106, v107
	v_mov_b32_e32 v236, v228
	v_mov_b32_e32 v237, v229
	v_mov_b32_e32 v238, v230
	v_mov_b32_e32 v239, v231
	v_mov_b32_dpp v228, v232 row_ror:8 row_mask:0xf bank_mask:0xc
	v_mov_b32_dpp v229, v233 row_ror:8 row_mask:0xf bank_mask:0xc
	v_mov_b32_dpp v230, v234 row_ror:8 row_mask:0xf bank_mask:0xc
	v_mov_b32_dpp v231, v235 row_ror:8 row_mask:0xf bank_mask:0xc
	v_mov_b32_dpp v232, v236 row_ror:8 row_mask:0xf bank_mask:0x3
	v_mov_b32_dpp v233, v237 row_ror:8 row_mask:0xf bank_mask:0x3
	v_mov_b32_dpp v234, v238 row_ror:8 row_mask:0xf bank_mask:0x3
	v_mov_b32_dpp v235, v239 row_ror:8 row_mask:0xf bank_mask:0x3
	global_store_dwordx4 v240, v[228:231], s[100:101]
	s_add_u32 s100, s100, 0x18000
	s_addc_u32 s101, s101, 0
	global_store_dwordx4 v240, v[232:235], s[100:101]
	v_cvt_pk_bf16_f32 v228, v116, v117
	v_cvt_pk_bf16_f32 v229, v118, v119
	v_cvt_pk_bf16_f32 v230, v112, v113
	v_cvt_pk_bf16_f32 v231, v114, v115
	v_cvt_pk_bf16_f32 v232, v92, v93
	v_cvt_pk_bf16_f32 v233, v94, v95
	v_cvt_pk_bf16_f32 v234, v88, v89
	v_cvt_pk_bf16_f32 v235, v90, v91
	v_mov_b32_e32 v236, v228
	v_mov_b32_e32 v237, v229
	v_mov_b32_e32 v238, v230
	v_mov_b32_e32 v239, v231
	v_mov_b32_dpp v228, v232 row_ror:8 row_mask:0xf bank_mask:0xc
	v_mov_b32_dpp v229, v233 row_ror:8 row_mask:0xf bank_mask:0xc
	v_mov_b32_dpp v230, v234 row_ror:8 row_mask:0xf bank_mask:0xc
	v_mov_b32_dpp v231, v235 row_ror:8 row_mask:0xf bank_mask:0xc
	v_mov_b32_dpp v232, v236 row_ror:8 row_mask:0xf bank_mask:0x3
	v_mov_b32_dpp v233, v237 row_ror:8 row_mask:0xf bank_mask:0x3
	v_mov_b32_dpp v234, v238 row_ror:8 row_mask:0xf bank_mask:0x3
	v_mov_b32_dpp v235, v239 row_ror:8 row_mask:0xf bank_mask:0x3
	s_add_u32 s100, s100, 0x18000
	s_addc_u32 s101, s101, 0
	global_store_dwordx4 v240, v[228:231], s[100:101]
	s_add_u32 s100, s100, 0x18000
	s_addc_u32 s101, s101, 0
	global_store_dwordx4 v240, v[232:235], s[100:101]
	v_cvt_pk_bf16_f32 v228, v100, v101
	v_cvt_pk_bf16_f32 v229, v102, v103
	v_cvt_pk_bf16_f32 v230, v96, v97
	v_cvt_pk_bf16_f32 v231, v98, v99
	v_cvt_pk_bf16_f32 v232, v76, v77
	v_cvt_pk_bf16_f32 v233, v78, v79
	v_cvt_pk_bf16_f32 v234, v72, v73
	v_cvt_pk_bf16_f32 v235, v74, v75
	v_mov_b32_e32 v236, v228
	v_mov_b32_e32 v237, v229
	v_mov_b32_e32 v238, v230
	v_mov_b32_e32 v239, v231
	v_mov_b32_dpp v228, v232 row_ror:8 row_mask:0xf bank_mask:0xc
	v_mov_b32_dpp v229, v233 row_ror:8 row_mask:0xf bank_mask:0xc
	v_mov_b32_dpp v230, v234 row_ror:8 row_mask:0xf bank_mask:0xc
	v_mov_b32_dpp v231, v235 row_ror:8 row_mask:0xf bank_mask:0xc
	v_mov_b32_dpp v232, v236 row_ror:8 row_mask:0xf bank_mask:0x3
	v_mov_b32_dpp v233, v237 row_ror:8 row_mask:0xf bank_mask:0x3
	v_mov_b32_dpp v234, v238 row_ror:8 row_mask:0xf bank_mask:0x3
	v_mov_b32_dpp v235, v239 row_ror:8 row_mask:0xf bank_mask:0x3
	s_add_u32 s100, s100, 0x18000
	s_addc_u32 s101, s101, 0
	global_store_dwordx4 v240, v[228:231], s[100:101]
	s_add_u32 s100, s100, 0x18000
	s_addc_u32 s101, s101, 0
	global_store_dwordx4 v240, v[232:235], s[100:101]
	v_cvt_pk_bf16_f32 v228, v84, v85
	v_cvt_pk_bf16_f32 v229, v86, v87
	v_cvt_pk_bf16_f32 v230, v80, v81
	v_cvt_pk_bf16_f32 v231, v82, v83
	v_cvt_pk_bf16_f32 v232, v68, v69
	v_cvt_pk_bf16_f32 v233, v70, v71
	v_cvt_pk_bf16_f32 v234, v64, v65
	v_cvt_pk_bf16_f32 v235, v66, v67
	v_mov_b32_e32 v236, v228
	v_mov_b32_e32 v237, v229
	v_mov_b32_e32 v238, v230
	v_mov_b32_e32 v239, v231
	v_mov_b32_dpp v228, v232 row_ror:8 row_mask:0xf bank_mask:0xc
	v_mov_b32_dpp v229, v233 row_ror:8 row_mask:0xf bank_mask:0xc
	v_mov_b32_dpp v230, v234 row_ror:8 row_mask:0xf bank_mask:0xc
	v_mov_b32_dpp v231, v235 row_ror:8 row_mask:0xf bank_mask:0xc
	v_mov_b32_dpp v232, v236 row_ror:8 row_mask:0xf bank_mask:0x3
	v_mov_b32_dpp v233, v237 row_ror:8 row_mask:0xf bank_mask:0x3
	v_mov_b32_dpp v234, v238 row_ror:8 row_mask:0xf bank_mask:0x3
	v_mov_b32_dpp v235, v239 row_ror:8 row_mask:0xf bank_mask:0x3
	s_add_u32 s100, s100, 0x18000
	s_addc_u32 s101, s101, 0
	global_store_dwordx4 v240, v[228:231], s[100:101]
	s_add_u32 s100, s100, 0x18000
	s_addc_u32 s101, s101, 0
	global_store_dwordx4 v240, v[232:235], s[100:101]
	v_cvt_pk_bf16_f32 v228, v60, v61
	v_cvt_pk_bf16_f32 v229, v62, v63
	v_cvt_pk_bf16_f32 v230, v56, v57
	v_cvt_pk_bf16_f32 v231, v58, v59
	v_cvt_pk_bf16_f32 v232, v44, v45
	v_cvt_pk_bf16_f32 v233, v46, v47
	v_cvt_pk_bf16_f32 v234, v40, v41
	v_cvt_pk_bf16_f32 v235, v42, v43
	v_mov_b32_e32 v236, v228
	v_mov_b32_e32 v237, v229
	v_mov_b32_e32 v238, v230
	v_mov_b32_e32 v239, v231
	v_mov_b32_dpp v228, v232 row_ror:8 row_mask:0xf bank_mask:0xc
	v_mov_b32_dpp v229, v233 row_ror:8 row_mask:0xf bank_mask:0xc
	v_mov_b32_dpp v230, v234 row_ror:8 row_mask:0xf bank_mask:0xc
	v_mov_b32_dpp v231, v235 row_ror:8 row_mask:0xf bank_mask:0xc
	v_mov_b32_dpp v232, v236 row_ror:8 row_mask:0xf bank_mask:0x3
	v_mov_b32_dpp v233, v237 row_ror:8 row_mask:0xf bank_mask:0x3
	v_mov_b32_dpp v234, v238 row_ror:8 row_mask:0xf bank_mask:0x3
	v_mov_b32_dpp v235, v239 row_ror:8 row_mask:0xf bank_mask:0x3
	s_add_u32 s100, s100, 0xd8000
	s_addc_u32 s101, s101, 0
	global_store_dwordx4 v240, v[228:231], s[100:101]
	s_add_u32 s100, s100, 0x18000
	s_addc_u32 s101, s101, 0
	global_store_dwordx4 v240, v[232:235], s[100:101]
	v_cvt_pk_bf16_f32 v228, v52, v53
	v_cvt_pk_bf16_f32 v229, v54, v55
	v_cvt_pk_bf16_f32 v230, v48, v49
	v_cvt_pk_bf16_f32 v231, v50, v51
	v_cvt_pk_bf16_f32 v232, v28, v29
	v_cvt_pk_bf16_f32 v233, v30, v31
	v_cvt_pk_bf16_f32 v234, v24, v25
	v_cvt_pk_bf16_f32 v235, v26, v27
	v_mov_b32_e32 v236, v228
	v_mov_b32_e32 v237, v229
	v_mov_b32_e32 v238, v230
	v_mov_b32_e32 v239, v231
	v_mov_b32_dpp v228, v232 row_ror:8 row_mask:0xf bank_mask:0xc
	v_mov_b32_dpp v229, v233 row_ror:8 row_mask:0xf bank_mask:0xc
	v_mov_b32_dpp v230, v234 row_ror:8 row_mask:0xf bank_mask:0xc
	v_mov_b32_dpp v231, v235 row_ror:8 row_mask:0xf bank_mask:0xc
	v_mov_b32_dpp v232, v236 row_ror:8 row_mask:0xf bank_mask:0x3
	v_mov_b32_dpp v233, v237 row_ror:8 row_mask:0xf bank_mask:0x3
	v_mov_b32_dpp v234, v238 row_ror:8 row_mask:0xf bank_mask:0x3
	v_mov_b32_dpp v235, v239 row_ror:8 row_mask:0xf bank_mask:0x3
	s_add_u32 s100, s100, 0x18000
	s_addc_u32 s101, s101, 0
	global_store_dwordx4 v240, v[228:231], s[100:101]
	s_add_u32 s100, s100, 0x18000
	s_addc_u32 s101, s101, 0
	global_store_dwordx4 v240, v[232:235], s[100:101]
	v_cvt_pk_bf16_f32 v228, v36, v37
	v_cvt_pk_bf16_f32 v229, v38, v39
	v_cvt_pk_bf16_f32 v230, v32, v33
	v_cvt_pk_bf16_f32 v231, v34, v35
	v_cvt_pk_bf16_f32 v232, v12, v13
	v_cvt_pk_bf16_f32 v233, v14, v15
	v_cvt_pk_bf16_f32 v234, v8, v9
	v_cvt_pk_bf16_f32 v235, v10, v11
	v_mov_b32_e32 v236, v228
	v_mov_b32_e32 v237, v229
	v_mov_b32_e32 v238, v230
	v_mov_b32_e32 v239, v231
	v_mov_b32_dpp v228, v232 row_ror:8 row_mask:0xf bank_mask:0xc
	v_mov_b32_dpp v229, v233 row_ror:8 row_mask:0xf bank_mask:0xc
	v_mov_b32_dpp v230, v234 row_ror:8 row_mask:0xf bank_mask:0xc
	v_mov_b32_dpp v231, v235 row_ror:8 row_mask:0xf bank_mask:0xc
	v_mov_b32_dpp v232, v236 row_ror:8 row_mask:0xf bank_mask:0x3
	v_mov_b32_dpp v233, v237 row_ror:8 row_mask:0xf bank_mask:0x3
	v_mov_b32_dpp v234, v238 row_ror:8 row_mask:0xf bank_mask:0x3
	v_mov_b32_dpp v235, v239 row_ror:8 row_mask:0xf bank_mask:0x3
	s_add_u32 s100, s100, 0x18000
	s_addc_u32 s101, s101, 0
	global_store_dwordx4 v240, v[228:231], s[100:101]
	s_add_u32 s100, s100, 0x18000
	s_addc_u32 s101, s101, 0
	global_store_dwordx4 v240, v[232:235], s[100:101]
	v_cvt_pk_bf16_f32 v228, v20, v21
	v_cvt_pk_bf16_f32 v229, v22, v23
	v_cvt_pk_bf16_f32 v230, v16, v17
	v_cvt_pk_bf16_f32 v231, v18, v19
	v_cvt_pk_bf16_f32 v232, v4, v5
	v_cvt_pk_bf16_f32 v233, v6, v7
	v_cvt_pk_bf16_f32 v234, v0, v1
	v_cvt_pk_bf16_f32 v235, v2, v3
	v_mov_b32_e32 v236, v228
	v_mov_b32_e32 v237, v229
	v_mov_b32_e32 v238, v230
	v_mov_b32_e32 v239, v231
	v_mov_b32_dpp v228, v232 row_ror:8 row_mask:0xf bank_mask:0xc
	v_mov_b32_dpp v229, v233 row_ror:8 row_mask:0xf bank_mask:0xc
	v_mov_b32_dpp v230, v234 row_ror:8 row_mask:0xf bank_mask:0xc
	v_mov_b32_dpp v231, v235 row_ror:8 row_mask:0xf bank_mask:0xc
	v_mov_b32_dpp v232, v236 row_ror:8 row_mask:0xf bank_mask:0x3
	v_mov_b32_dpp v233, v237 row_ror:8 row_mask:0xf bank_mask:0x3
	v_mov_b32_dpp v234, v238 row_ror:8 row_mask:0xf bank_mask:0x3
	v_mov_b32_dpp v235, v239 row_ror:8 row_mask:0xf bank_mask:0x3
	s_add_u32 s100, s100, 0x18000
	s_addc_u32 s101, s101, 0
	global_store_dwordx4 v240, v[228:231], s[100:101]
	s_add_u32 s100, s100, 0x18000
	s_addc_u32 s101, s101, 0
	global_store_dwordx4 v240, v[232:235], s[100:101]
	s_and_b64 vcc, exec, s[2:3]
	s_mov_b32 s35, s8
	s_mov_b32 s6, s10
	s_mov_b64 s[18:19], s[14:15]
	s_mov_b64 s[16:17], s[12:13]
	s_cbranch_vccz .LBB0_151
	s_waitcnt vmcnt(0)
	s_cmpk_gt_u32 s22, 0xff
	s_cbranch_scc1 .LBB0_158
	s_barrier

.LBB0_524:
	s_or_b64 exec, exec, s[0:1]
	s_cmpk_lt_i32 s42, 0x480
	s_cselect_b64 s[2:3], -1, 0
	s_add_u32 s0, s58, 0x2000000
	v_mov_b32_e32 v10, v202
	s_waitcnt lgkmcnt(0)
	s_barrier
	s_addc_u32 s1, s59, 0
	v_writelane_b32 v247, s2, 14
	v_readfirstlane_b32 s28, v10
	s_and_b64 vcc, exec, s[2:3]
	v_writelane_b32 v247, s3, 15
	s_cbranch_vccz .LBB0_536
	v_lshlrev_b32_e32 v0, 4, v10
	v_readlane_b32 s2, v247, 8
	v_add_u32_e32 v1, 0x2000, v0
	s_lshr_b32 s2, s2, 29
	v_ashrrev_i32_e32 v2, 31, v1
	s_add_i32 s2, s42, s2
	v_lshrrev_b32_e32 v2, 22, v2
	s_ashr_i32 s6, s28, 6
	s_and_b32 s7, s2, -8
	v_add_u32_e32 v2, v1, v2
	s_ashr_i32 s3, s28, 8
	s_lshl_b32 s29, s6, 10
	s_sub_i32 s7, s42, s7
	v_ashrrev_i32_e32 v8, 10, v2
	s_cmp_lt_i32 s7, 0
	s_movk_i32 s30, 0x91
	v_mul_i32_i24_e32 v2, 0x400, v8
	s_cselect_b32 s8, s30, 0x90
	v_sub_u32_e32 v1, v1, v2
	s_mul_i32 s7, s8, s7
	s_ashr_i32 s2, s2, 3
	v_lshrrev_b32_e32 v2, 4, v1
	s_add_i32 s2, s7, s2
	v_bitop3_b32 v1, v2, v1, 32 bitop3:0x6c
	s_ashr_i32 s7, s2, 31
	v_ashrrev_i32_e32 v2, 31, v1
	s_lshr_b32 s7, s7, 24
	v_lshrrev_b32_e32 v2, 26, v2
	s_add_i32 s7, s2, s7
	v_add_u32_e32 v2, v1, v2
	v_lshlrev_b32_e32 v3, 3, v8
	s_ashr_i32 s7, s7, 8
	v_ashrrev_i32_e32 v9, 6, v2
	v_and_b32_e32 v3, -16, v3
	s_lshl_b32 s14, s7, 3
	s_lshl_b32 s7, s7, 8
	v_add_u32_e32 v3, v9, v3
	s_sub_i32 s7, s2, s7
	v_and_b32_e32 v4, 3, v9
	s_mov_b32 s2, 0xfffe0
	v_lshrrev_b32_e32 v5, 2, v3
	v_lshlrev_b32_e32 v6, 1, v3
	v_and_b32_e32 v2, 0xc0, v2
	v_and_or_b32 v4, v3, s2, v4
	v_and_b32_e32 v5, 4, v5
	v_and_b32_e32 v6, 24, v6
	v_sub_u32_e32 v1, v1, v2
	v_mov_b32_e32 v2, 1
	v_or3_b32 v4, v4, v5, v6
	v_lshlrev_b32_e32 v5, 5, v8
	v_ashrrev_i16_sdwa v1, v2, sext(v1) dst_sel:DWORD dst_unused:UNUSED_PAD src0_sel:DWORD src1_sel:BYTE_0
	v_and_b32_e32 v5, 32, v5
	v_bfe_i32 v11, v1, 0, 16
	v_add_lshl_u32 v1, v5, v11, 1
	v_lshl_add_u32 v128, v4, 12, v1
	v_lshl_add_u32 v130, v3, 12, v1
	v_bfe_i32 v1, v10, 27, 1
	v_lshrrev_b32_e32 v1, 22, v1
	v_add_u32_e32 v1, v0, v1
	v_and_b32_e32 v1, 0xfffffc00, v1
	v_sub_u32_e32 v0, v0, v1
	v_lshrrev_b32_e32 v1, 4, v0
	v_ashrrev_i32_e32 v3, 31, v10
	v_bitop3_b32 v0, v1, v0, 32 bitop3:0x6c
	v_lshrrev_b32_e32 v3, 26, v3
	v_ashrrev_i32_e32 v1, 31, v0
	v_add_u32_e32 v3, v10, v3
	v_lshrrev_b32_e32 v1, 26, v1
	v_ashrrev_i32_e32 v13, 6, v3
	v_add_u32_e32 v1, v0, v1
	v_lshlrev_b32_e32 v3, 3, v13
	v_ashrrev_i32_e32 v12, 6, v1
	v_and_b32_e32 v3, -16, v3
	v_add_u32_e32 v3, v12, v3
	v_and_b32_e32 v4, 3, v12
	v_lshrrev_b32_e32 v5, 2, v3
	v_lshlrev_b32_e32 v6, 1, v3
	v_and_b32_e32 v1, 0xc0, v1
	v_and_or_b32 v4, v3, s2, v4
	v_and_b32_e32 v5, 4, v5
	v_and_b32_e32 v6, 24, v6
	v_sub_u32_e32 v0, v0, v1
	s_sub_i32 s8, 36, s14
	v_or3_b32 v4, v4, v5, v6
	v_lshlrev_b32_e32 v5, 5, v13
	v_ashrrev_i16_sdwa v0, v2, sext(v0) dst_sel:DWORD dst_unused:UNUSED_PAD src0_sel:DWORD src1_sel:BYTE_0
	s_min_u32 s15, s8, 8
	v_and_b32_e32 v5, 32, v5
	v_bfe_i32 v14, v0, 0, 16
	v_add_lshl_u32 v0, v5, v14, 1
	s_sext_i32_i16 s2, s7
	v_cvt_f32_ubyte0_e32 v2, s15
	v_lshl_add_u32 v132, v4, 12, v0
	v_cvt_f32_i32_e32 v1, s2
	v_rcp_iflag_f32_e32 v4, v2
	v_lshl_add_u32 v134, v3, 12, v0
	s_ashr_i32 s2, s2, 30
	s_or_b32 s2, s2, 1
	v_mul_f32_e32 v0, v1, v4
	v_trunc_f32_e32 v0, v0
	v_fma_f32 v1, -v0, v2, v1
	v_cvt_i32_f32_e32 v0, v0
	v_cmp_ge_f32_e64 s[8:9], |v1|, v2
	s_and_b64 s[8:9], s[8:9], exec
	s_cselect_b32 s2, s2, 0
	v_readfirstlane_b32 s8, v0
	s_add_i32 s2, s8, s2
	s_mul_i32 s8, s2, s15
	s_sub_i32 s7, s7, s8
	s_sext_i32_i16 s7, s7
	s_add_i32 s20, s14, s7
	s_ashr_i32 s21, s20, 31
	s_bfe_i64 s[14:15], s[2:3], 0x100000
	s_lshl_b64 s[8:9], s[20:21], 20
	s_lshl_b64 s[14:15], s[14:15], 20
	s_add_u32 s24, s0, s14
	s_addc_u32 s25, s1, s15
	s_add_i32 s21, s29, 0
	s_add_i32 m0, s21, 0x10000
	v_readlane_b32 s14, v247, 9
	v_mov_b32_e32 v230, s3
	v_lshlrev_b32_e32 v230, 17, v230
	v_add_u32_e32 v132, v132, v230
	v_add_u32_e32 v230, 0x40000, v230
	v_add_u32_e32 v128, v128, v230
	global_load_lds_dwordx4 v132, s[24:25]
	s_add_i32 m0, s21, 0x12000
	v_readlane_b32 s15, v247, 10
	s_add_u32 s22, s14, s8
	global_load_lds_dwordx4 v128, s[24:25]
	s_addc_u32 s23, s15, s9
	s_mov_b32 m0, s21
	s_add_i32 s31, s21, 0x2000
	global_load_lds_dwordx4 v134, s[22:23]
	s_mov_b32 m0, s31
	s_add_u32 s8, s24, 0x20000
	global_load_lds_dwordx4 v130, s[22:23]
	s_addc_u32 s9, s25, 0
	s_add_i32 m0, s21, 0x14000
	v_mov_b32_e32 v133, 0
	global_load_lds_dwordx4 v132, s[8:9]
	s_add_i32 m0, s21, 0x16000
	v_mov_b32_e32 v129, v133
	global_load_lds_dwordx4 v128, s[8:9]
	s_add_u32 s8, s22, 0x80000
	s_addc_u32 s9, s23, 0
	s_add_i32 s33, s21, 0x4000
	s_mov_b32 m0, s33
	s_add_i32 s34, s21, 0x6000
	global_load_lds_dwordx4 v134, s[8:9]
	s_mov_b32 m0, s34
	v_mov_b32_e32 v135, v133
	global_load_lds_dwordx4 v130, s[8:9]
	v_mov_b32_e32 v131, v133
	s_mov_b32 s35, 0
	v_lshl_add_u64 v[6:7], s[24:25], 0, v[132:133]
	v_lshl_add_u64 v[4:5], s[24:25], 0, v[128:129]
	v_lshl_add_u64 v[2:3], s[22:23], 0, v[134:135]
	s_cmp_lg_u32 s3, 1
	v_lshl_add_u64 v[0:1], s[22:23], 0, v[130:131]
	s_cbranch_scc1 .LBB0_527
	s_barrier
.LBB0_527:
	s_lshl_b32 s6, s6, 5
	s_and_b32 s15, s6, 0x60
	s_mov_b64 s[6:7], 0x80
	s_add_i32 m0, s21, 0x18000
	v_lshl_add_u64 v[6:7], v[6:7], 0, s[6:7]
	s_lshl_b32 s14, s3, 13
	s_lshl_b32 s16, s15, 7
	s_waitcnt vmcnt(4)
	s_barrier
	global_load_lds_dwordx4 v[6:7], off
	v_lshl_add_u64 v[4:5], v[4:5], 0, s[6:7]
	s_add_i32 m0, s21, 0x1a000
	s_add_i32 s36, s21, 0x8000
	s_add_i32 s37, s21, 0xa000
	global_load_lds_dwordx4 v[4:5], off
	v_lshl_add_u64 v[2:3], v[2:3], 0, s[6:7]
	s_mov_b32 m0, s36
	s_add_u32 s8, s24, 0x20080
	global_load_lds_dwordx4 v[2:3], off
	v_lshl_add_u64 v[0:1], v[0:1], 0, s[6:7]
	s_mov_b32 m0, s37
	s_addc_u32 s9, s25, 0
	global_load_lds_dwordx4 v[0:1], off
	s_add_i32 m0, s21, 0x1c000
	v_lshl_add_u64 v[0:1], s[8:9], 0, v[132:133]
	global_load_lds_dwordx4 v[0:1], off
	v_lshl_add_u64 v[0:1], s[8:9], 0, v[128:129]
	s_add_i32 m0, s21, 0x1e000
	s_add_i32 s38, 0, 0x10000
	global_load_lds_dwordx4 v[0:1], off
	v_lshrrev_b32_e32 v1, 1, v10
	v_and_b32_e32 v1, 24, v1
	v_and_b32_e32 v0, 15, v10
	v_lshlrev_b32_e32 v2, 1, v1
	v_lshl_or_b32 v146, s3, 6, v0
	v_lshl_or_b32 v0, v0, 6, v2
	v_lshlrev_b32_e32 v2, 2, v10
	v_and_b32_e32 v2, 32, v2
	v_bitop3_b32 v3, v0, s14, v2 bitop3:0xde
	v_bitop3_b32 v147, v0, s16, v2 bitop3:0xde
	v_lshlrev_b32_e32 v0, 15, v13
	v_and_b32_e32 v0, 0xffff0000, v0
	v_or_b32_e32 v148, s15, v1
	v_lshl_add_u32 v0, v12, 12, v0
	v_and_b32_e32 v1, 1, v13
	v_lshl_or_b32 v0, v1, 6, v0
	v_lshl_add_u32 v136, v14, 1, v0
	v_lshlrev_b32_e32 v0, 15, v8
	v_and_b32_e32 v0, 0xffff0000, v0
	s_waitcnt vmcnt(6)
	v_lshl_add_u32 v0, v9, 12, v0
	v_and_b32_e32 v1, 1, v8
	v_lshl_or_b32 v0, v1, 6, v0
	s_add_i32 s39, 0, 0x14000
	s_sext_i32_i16 s40, s2
	v_mov_b32_e32 v137, v133
	v_lshl_add_u32 v138, v11, 1, v0
	v_mov_b32_e32 v139, v133
	v_mov_b64_e32 v[140:141], 0x480
	v_mov_b64_e32 v[142:143], 0x47f
	v_add_u32_e32 v149, s38, v147
	v_add_u32_e32 v150, 0, v3
	v_add_u32_e32 v151, s39, v147
	s_barrier

.LBB0_531:
	ds_read_b128 v[152:155], v149
	ds_read_b128 v[156:159], v149 offset:1024
	ds_read_b128 v[160:163], v149 offset:2048
	ds_read_b128 v[164:167], v149 offset:3072
	s_add_u32 s24, s22, 0xfff80080
	s_addc_u32 s25, s23, -1
	s_cmp_eq_u32 s45, 28
	s_cselect_b32 s27, s15, s25
	s_cselect_b32 s26, s41, s24
	s_cselect_b32 s25, s9, s44
	s_cselect_b32 s24, s42, s43
	v_lshl_add_u64 v[144:145], s[22:23], 0, v[136:137]
	s_add_i32 m0, s21, 0xc000
	ds_read_b128 v[168:171], v150
	ds_read_b128 v[172:175], v150 offset:1024
	ds_read_b128 v[176:179], v150 offset:2048
	ds_read_b128 v[180:183], v150 offset:3072
	ds_read_b128 v[184:187], v150 offset:4096
	ds_read_b128 v[188:191], v150 offset:5120
	ds_read_b128 v[192:195], v150 offset:6144
	ds_read_b128 v[196:199], v150 offset:7168
	global_load_lds_dwordx4 v[144:145], off
	v_lshl_add_u64 v[144:145], s[22:23], 0, v[138:139]
	s_add_i32 m0, s21, 0xe000
	s_nop 0
	global_load_lds_dwordx4 v[144:145], off
	s_waitcnt lgkmcnt(8)
	s_barrier
	s_waitcnt lgkmcnt(0)
	s_setprio 1
	s_waitcnt lgkmcnt(0)
	v_mfma_f32_16x16x32_bf16 v[124:127], v[152:155], v[168:171], v[124:127]
	v_mfma_f32_16x16x32_bf16 v[120:123], v[160:163], v[168:171], v[120:123]
	v_mfma_f32_16x16x32_bf16 v[108:111], v[152:155], v[176:179], v[108:111]
	v_mfma_f32_16x16x32_bf16 v[104:107], v[160:163], v[176:179], v[104:107]
	v_mfma_f32_16x16x32_bf16 v[92:95], v[152:155], v[184:187], v[92:95]
	v_mfma_f32_16x16x32_bf16 v[88:91], v[160:163], v[184:187], v[88:91]
	v_mfma_f32_16x16x32_bf16 v[76:79], v[152:155], v[192:195], v[76:79]
	v_mfma_f32_16x16x32_bf16 v[72:75], v[160:163], v[192:195], v[72:75]
	v_mfma_f32_16x16x32_bf16 v[124:127], v[156:159], v[172:175], v[124:127]
	v_mfma_f32_16x16x32_bf16 v[120:123], v[164:167], v[172:175], v[120:123]
	v_mfma_f32_16x16x32_bf16 v[108:111], v[156:159], v[180:183], v[108:111]
	v_mfma_f32_16x16x32_bf16 v[104:107], v[164:167], v[180:183], v[104:107]
	v_mfma_f32_16x16x32_bf16 v[92:95], v[156:159], v[188:191], v[92:95]
	v_mfma_f32_16x16x32_bf16 v[88:91], v[164:167], v[188:191], v[88:91]
	v_mfma_f32_16x16x32_bf16 v[76:79], v[156:159], v[196:199], v[76:79]
	v_mfma_f32_16x16x32_bf16 v[72:75], v[164:167], v[196:199], v[72:75]
	s_setprio 0
	s_barrier
	s_add_i32 s46, s38, s29
	v_lshl_add_u64 v[144:145], s[24:25], 0, v[132:133]
	s_mov_b32 m0, s46
	ds_read_b128 v[204:207], v151
	ds_read_b128 v[208:211], v151 offset:1024
	ds_read_b128 v[212:215], v151 offset:2048
	ds_read_b128 v[216:219], v151 offset:3072
	global_load_lds_dwordx4 v[144:145], off
	v_lshl_add_u64 v[200:201], s[24:25], 0, v[128:129]
	s_add_i32 m0, s46, 0x2000
	s_nop 0
	global_load_lds_dwordx4 v[200:201], off
	s_barrier
	s_waitcnt lgkmcnt(0)
	s_setprio 1
	s_waitcnt lgkmcnt(0)
	v_mfma_f32_16x16x32_bf16 v[116:119], v[204:207], v[168:171], v[116:119]
	v_mfma_f32_16x16x32_bf16 v[112:115], v[212:215], v[168:171], v[112:115]
	v_mfma_f32_16x16x32_bf16 v[100:103], v[204:207], v[176:179], v[100:103]
	v_mfma_f32_16x16x32_bf16 v[96:99], v[212:215], v[176:179], v[96:99]
	v_mfma_f32_16x16x32_bf16 v[84:87], v[204:207], v[184:187], v[84:87]
	v_mfma_f32_16x16x32_bf16 v[80:83], v[212:215], v[184:187], v[80:83]
	v_mfma_f32_16x16x32_bf16 v[68:71], v[204:207], v[192:195], v[68:71]
	v_mfma_f32_16x16x32_bf16 v[64:67], v[212:215], v[192:195], v[64:67]
	v_mfma_f32_16x16x32_bf16 v[116:119], v[208:211], v[172:175], v[116:119]
	v_mfma_f32_16x16x32_bf16 v[112:115], v[216:219], v[172:175], v[112:115]
	v_mfma_f32_16x16x32_bf16 v[100:103], v[208:211], v[180:183], v[100:103]
	v_mfma_f32_16x16x32_bf16 v[96:99], v[216:219], v[180:183], v[96:99]
	v_mfma_f32_16x16x32_bf16 v[84:87], v[208:211], v[188:191], v[84:87]
	v_mfma_f32_16x16x32_bf16 v[80:83], v[216:219], v[188:191], v[80:83]
	v_mfma_f32_16x16x32_bf16 v[68:71], v[208:211], v[196:199], v[68:71]
	v_mfma_f32_16x16x32_bf16 v[64:67], v[216:219], v[196:199], v[64:67]
	s_setprio 0
	s_mov_b32 m0, s21
	v_lshl_add_u64 v[220:221], s[26:27], 0, v[134:135]
	s_barrier
	ds_read_b128 v[168:171], v150 offset:16384
	ds_read_b128 v[172:175], v150 offset:17408
	ds_read_b128 v[176:179], v150 offset:18432
	ds_read_b128 v[180:183], v150 offset:19456
	ds_read_b128 v[184:187], v150 offset:20480
	ds_read_b128 v[188:191], v150 offset:21504
	ds_read_b128 v[192:195], v150 offset:22528
	ds_read_b128 v[196:199], v150 offset:23552
	global_load_lds_dwordx4 v[220:221], off
	v_lshl_add_u64 v[222:223], s[26:27], 0, v[130:131]
	s_mov_b32 m0, s31
	s_nop 0
	global_load_lds_dwordx4 v[222:223], off
	s_barrier
	s_waitcnt lgkmcnt(0)
	s_setprio 1
	s_waitcnt lgkmcnt(0)
	v_mfma_f32_16x16x32_bf16 v[60:63], v[152:155], v[168:171], v[60:63]
	v_mfma_f32_16x16x32_bf16 v[56:59], v[160:163], v[168:171], v[56:59]
	v_mfma_f32_16x16x32_bf16 v[44:47], v[152:155], v[176:179], v[44:47]
	v_mfma_f32_16x16x32_bf16 v[40:43], v[160:163], v[176:179], v[40:43]
	v_mfma_f32_16x16x32_bf16 v[28:31], v[152:155], v[184:187], v[28:31]
	v_mfma_f32_16x16x32_bf16 v[24:27], v[160:163], v[184:187], v[24:27]
	v_mfma_f32_16x16x32_bf16 v[12:15], v[152:155], v[192:195], v[12:15]
	v_mfma_f32_16x16x32_bf16 v[8:11], v[160:163], v[192:195], v[8:11]
	v_mfma_f32_16x16x32_bf16 v[60:63], v[156:159], v[172:175], v[60:63]
	v_mfma_f32_16x16x32_bf16 v[56:59], v[164:167], v[172:175], v[56:59]
	v_mfma_f32_16x16x32_bf16 v[44:47], v[156:159], v[180:183], v[44:47]
	v_mfma_f32_16x16x32_bf16 v[40:43], v[164:167], v[180:183], v[40:43]
	v_mfma_f32_16x16x32_bf16 v[28:31], v[156:159], v[188:191], v[28:31]
	v_mfma_f32_16x16x32_bf16 v[24:27], v[164:167], v[188:191], v[24:27]
	v_mfma_f32_16x16x32_bf16 v[12:15], v[156:159], v[196:199], v[12:15]
	v_mfma_f32_16x16x32_bf16 v[8:11], v[164:167], v[196:199], v[8:11]
	s_setprio 0
	s_barrier
	s_add_u32 s46, s24, 0x20000
	s_addc_u32 s47, s25, 0
	s_add_i32 s48, s39, s29
	v_lshl_add_u64 v[152:153], s[46:47], 0, v[132:133]
	s_mov_b32 m0, s48
	s_nop 0
	global_load_lds_dwordx4 v[152:153], off
	v_lshl_add_u64 v[152:153], s[46:47], 0, v[128:129]
	s_add_i32 m0, s48, 0x2000
	s_nop 0
	global_load_lds_dwordx4 v[152:153], off
	s_waitcnt vmcnt(6)
	s_barrier
	s_setprio 1
	v_mfma_f32_16x16x32_bf16 v[52:55], v[204:207], v[168:171], v[52:55]
	v_mfma_f32_16x16x32_bf16 v[48:51], v[212:215], v[168:171], v[48:51]
	v_mfma_f32_16x16x32_bf16 v[36:39], v[204:207], v[176:179], v[36:39]
	v_mfma_f32_16x16x32_bf16 v[32:35], v[212:215], v[176:179], v[32:35]
	v_mfma_f32_16x16x32_bf16 v[20:23], v[204:207], v[184:187], v[20:23]
	v_mfma_f32_16x16x32_bf16 v[16:19], v[212:215], v[184:187], v[16:19]
	v_mfma_f32_16x16x32_bf16 v[4:7], v[204:207], v[192:195], v[4:7]
	v_mfma_f32_16x16x32_bf16 v[0:3], v[212:215], v[192:195], v[0:3]
	v_mfma_f32_16x16x32_bf16 v[52:55], v[208:211], v[172:175], v[52:55]
	v_mfma_f32_16x16x32_bf16 v[48:51], v[216:219], v[172:175], v[48:51]
	v_mfma_f32_16x16x32_bf16 v[36:39], v[208:211], v[180:183], v[36:39]
	v_mfma_f32_16x16x32_bf16 v[32:35], v[216:219], v[180:183], v[32:35]
	v_mfma_f32_16x16x32_bf16 v[20:23], v[208:211], v[188:191], v[20:23]
	v_mfma_f32_16x16x32_bf16 v[16:19], v[216:219], v[188:191], v[16:19]
	v_mfma_f32_16x16x32_bf16 v[4:7], v[208:211], v[196:199], v[4:7]
	v_mfma_f32_16x16x32_bf16 v[0:3], v[216:219], v[196:199], v[0:3]
	s_setprio 0
	s_add_i32 s46, 0, 0x18000
	v_add_u32_e32 v164, s46, v147
	s_barrier
	ds_read_b128 v[152:155], v164
	ds_read_b128 v[156:159], v164 offset:1024
	ds_read_b128 v[160:163], v164 offset:2048
	ds_read_b128 v[164:167], v164 offset:3072
	s_add_u32 s26, s26, 0x80000
	s_addc_u32 s27, s27, 0
	s_mov_b32 m0, s33
	v_lshl_add_u64 v[204:205], s[26:27], 0, v[134:135]
	ds_read_b128 v[168:171], v150 offset:32768
	ds_read_b128 v[172:175], v150 offset:33792
	ds_read_b128 v[176:179], v150 offset:34816
	ds_read_b128 v[180:183], v150 offset:35840
	ds_read_b128 v[184:187], v150 offset:36864
	ds_read_b128 v[188:191], v150 offset:37888
	ds_read_b128 v[192:195], v150 offset:38912
	ds_read_b128 v[196:199], v150 offset:39936
	global_load_lds_dwordx4 v[204:205], off
	v_lshl_add_u64 v[204:205], s[26:27], 0, v[130:131]
	s_mov_b32 m0, s34
	s_nop 0
	global_load_lds_dwordx4 v[204:205], off
	s_waitcnt lgkmcnt(8)
	s_barrier
	s_waitcnt lgkmcnt(0)
	s_setprio 1
	s_waitcnt lgkmcnt(0)
	v_mfma_f32_16x16x32_bf16 v[124:127], v[152:155], v[168:171], v[124:127]
	v_mfma_f32_16x16x32_bf16 v[120:123], v[160:163], v[168:171], v[120:123]
	v_mfma_f32_16x16x32_bf16 v[108:111], v[152:155], v[176:179], v[108:111]
	v_mfma_f32_16x16x32_bf16 v[104:107], v[160:163], v[176:179], v[104:107]
	v_mfma_f32_16x16x32_bf16 v[92:95], v[152:155], v[184:187], v[92:95]
	v_mfma_f32_16x16x32_bf16 v[88:91], v[160:163], v[184:187], v[88:91]
	v_mfma_f32_16x16x32_bf16 v[76:79], v[152:155], v[192:195], v[76:79]
	v_mfma_f32_16x16x32_bf16 v[72:75], v[160:163], v[192:195], v[72:75]
	v_mfma_f32_16x16x32_bf16 v[124:127], v[156:159], v[172:175], v[124:127]
	v_mfma_f32_16x16x32_bf16 v[120:123], v[164:167], v[172:175], v[120:123]
	v_mfma_f32_16x16x32_bf16 v[108:111], v[156:159], v[180:183], v[108:111]
	v_mfma_f32_16x16x32_bf16 v[104:107], v[164:167], v[180:183], v[104:107]
	v_mfma_f32_16x16x32_bf16 v[92:95], v[156:159], v[188:191], v[92:95]
	v_mfma_f32_16x16x32_bf16 v[88:91], v[164:167], v[188:191], v[88:91]
	v_mfma_f32_16x16x32_bf16 v[76:79], v[156:159], v[196:199], v[76:79]
	v_mfma_f32_16x16x32_bf16 v[72:75], v[164:167], v[196:199], v[72:75]
	s_setprio 0
	s_barrier
	s_add_i32 s26, 0, 0x1c000
	s_add_i32 s27, s46, s29
	v_add_u32_e32 v216, s26, v147
	v_lshl_add_u64 v[144:145], v[144:145], 0, s[6:7]
	s_mov_b32 m0, s27
	ds_read_b128 v[204:207], v216
	ds_read_b128 v[208:211], v216 offset:1024
	ds_read_b128 v[212:215], v216 offset:2048
	ds_read_b128 v[216:219], v216 offset:3072
	global_load_lds_dwordx4 v[144:145], off
	v_lshl_add_u64 v[144:145], v[200:201], 0, s[6:7]
	s_add_i32 m0, s27, 0x2000
	s_nop 0
	global_load_lds_dwordx4 v[144:145], off
	s_barrier
	s_waitcnt lgkmcnt(0)
	s_setprio 1
	s_waitcnt lgkmcnt(0)
	v_mfma_f32_16x16x32_bf16 v[116:119], v[204:207], v[168:171], v[116:119]
	v_mfma_f32_16x16x32_bf16 v[112:115], v[212:215], v[168:171], v[112:115]
	v_mfma_f32_16x16x32_bf16 v[100:103], v[204:207], v[176:179], v[100:103]
	v_mfma_f32_16x16x32_bf16 v[96:99], v[212:215], v[176:179], v[96:99]
	v_mfma_f32_16x16x32_bf16 v[84:87], v[204:207], v[184:187], v[84:87]
	v_mfma_f32_16x16x32_bf16 v[80:83], v[212:215], v[184:187], v[80:83]
	v_mfma_f32_16x16x32_bf16 v[68:71], v[204:207], v[192:195], v[68:71]
	v_mfma_f32_16x16x32_bf16 v[64:67], v[212:215], v[192:195], v[64:67]
	v_mfma_f32_16x16x32_bf16 v[116:119], v[208:211], v[172:175], v[116:119]
	v_mfma_f32_16x16x32_bf16 v[112:115], v[216:219], v[172:175], v[112:115]
	v_mfma_f32_16x16x32_bf16 v[100:103], v[208:211], v[180:183], v[100:103]
	v_mfma_f32_16x16x32_bf16 v[96:99], v[216:219], v[180:183], v[96:99]
	v_mfma_f32_16x16x32_bf16 v[84:87], v[208:211], v[188:191], v[84:87]
	v_mfma_f32_16x16x32_bf16 v[80:83], v[216:219], v[188:191], v[80:83]
	v_mfma_f32_16x16x32_bf16 v[68:71], v[208:211], v[196:199], v[68:71]
	v_mfma_f32_16x16x32_bf16 v[64:67], v[216:219], v[196:199], v[64:67]
	s_setprio 0
	s_mov_b32 m0, s36
	v_lshl_add_u64 v[144:145], v[220:221], 0, s[6:7]
	s_barrier
	ds_read_b128 v[168:171], v150 offset:49152
	ds_read_b128 v[172:175], v150 offset:50176
	ds_read_b128 v[176:179], v150 offset:51200
	ds_read_b128 v[180:183], v150 offset:52224
	ds_read_b128 v[184:187], v150 offset:53248
	ds_read_b128 v[188:191], v150 offset:54272
	ds_read_b128 v[192:195], v150 offset:55296
	ds_read_b128 v[196:199], v150 offset:56320
	global_load_lds_dwordx4 v[144:145], off
	v_lshl_add_u64 v[144:145], v[222:223], 0, s[6:7]
	s_mov_b32 m0, s37
	s_nop 0
	global_load_lds_dwordx4 v[144:145], off
	s_barrier
	s_waitcnt lgkmcnt(0)
	s_setprio 1
	s_waitcnt lgkmcnt(0)
	v_mfma_f32_16x16x32_bf16 v[60:63], v[152:155], v[168:171], v[60:63]
	v_mfma_f32_16x16x32_bf16 v[56:59], v[160:163], v[168:171], v[56:59]
	v_mfma_f32_16x16x32_bf16 v[44:47], v[152:155], v[176:179], v[44:47]
	v_mfma_f32_16x16x32_bf16 v[40:43], v[160:163], v[176:179], v[40:43]
	v_mfma_f32_16x16x32_bf16 v[28:31], v[152:155], v[184:187], v[28:31]
	v_mfma_f32_16x16x32_bf16 v[24:27], v[160:163], v[184:187], v[24:27]
	v_mfma_f32_16x16x32_bf16 v[12:15], v[152:155], v[192:195], v[12:15]
	v_mfma_f32_16x16x32_bf16 v[8:11], v[160:163], v[192:195], v[8:11]
	v_mfma_f32_16x16x32_bf16 v[60:63], v[156:159], v[172:175], v[60:63]
	v_mfma_f32_16x16x32_bf16 v[56:59], v[164:167], v[172:175], v[56:59]
	v_mfma_f32_16x16x32_bf16 v[44:47], v[156:159], v[180:183], v[44:47]
	v_mfma_f32_16x16x32_bf16 v[40:43], v[164:167], v[180:183], v[40:43]
	v_mfma_f32_16x16x32_bf16 v[28:31], v[156:159], v[188:191], v[28:31]
	v_mfma_f32_16x16x32_bf16 v[24:27], v[164:167], v[188:191], v[24:27]
	v_mfma_f32_16x16x32_bf16 v[12:15], v[156:159], v[196:199], v[12:15]
	v_mfma_f32_16x16x32_bf16 v[8:11], v[164:167], v[196:199], v[8:11]
	s_setprio 0
	s_barrier
	s_add_u32 s24, s24, 0x20080
	s_addc_u32 s25, s25, 0
	s_add_i32 s26, s26, s29
	v_lshl_add_u64 v[144:145], s[24:25], 0, v[132:133]
	s_mov_b32 m0, s26
	s_nop 0
	global_load_lds_dwordx4 v[144:145], off
	v_lshl_add_u64 v[144:145], s[24:25], 0, v[128:129]
	s_add_i32 m0, s26, 0x2000
	s_nop 0
	global_load_lds_dwordx4 v[144:145], off
	s_waitcnt vmcnt(6)
	s_barrier
	s_setprio 1
	v_mfma_f32_16x16x32_bf16 v[52:55], v[204:207], v[168:171], v[52:55]
	v_mfma_f32_16x16x32_bf16 v[48:51], v[212:215], v[168:171], v[48:51]
	v_mfma_f32_16x16x32_bf16 v[36:39], v[204:207], v[176:179], v[36:39]
	v_mfma_f32_16x16x32_bf16 v[32:35], v[212:215], v[176:179], v[32:35]
	v_mfma_f32_16x16x32_bf16 v[20:23], v[204:207], v[184:187], v[20:23]
	v_mfma_f32_16x16x32_bf16 v[16:19], v[212:215], v[184:187], v[16:19]
	v_mfma_f32_16x16x32_bf16 v[4:7], v[204:207], v[192:195], v[4:7]
	v_mfma_f32_16x16x32_bf16 v[0:3], v[212:215], v[192:195], v[0:3]
	v_mfma_f32_16x16x32_bf16 v[52:55], v[208:211], v[172:175], v[52:55]
	v_mfma_f32_16x16x32_bf16 v[48:51], v[216:219], v[172:175], v[48:51]
	v_mfma_f32_16x16x32_bf16 v[36:39], v[208:211], v[180:183], v[36:39]
	v_mfma_f32_16x16x32_bf16 v[32:35], v[216:219], v[180:183], v[32:35]
	v_mfma_f32_16x16x32_bf16 v[20:23], v[208:211], v[188:191], v[20:23]
	v_mfma_f32_16x16x32_bf16 v[16:19], v[216:219], v[188:191], v[16:19]
	v_mfma_f32_16x16x32_bf16 v[4:7], v[208:211], v[196:199], v[4:7]
	v_mfma_f32_16x16x32_bf16 v[0:3], v[216:219], v[196:199], v[0:3]
	s_setprio 0
	s_add_i32 s45, s45, 2
	s_add_u32 s22, s22, 0x100
	s_addc_u32 s23, s23, 0
	s_add_u32 s43, s43, 0x100
	s_addc_u32 s44, s44, 0
	s_cmp_gt_u32 s45, 29
	s_barrier
	s_cbranch_scc0 .LBB0_531
	v_readlane_b32 s100, v248, 63
	v_readlane_b32 s101, v247, 0
	v_and_b32_e32 v242, 15, v202
	v_bfe_u32 v243, v202, 4, 2
	v_bfe_u32 v244, v202, 6, 2
	v_lshrrev_b32_e32 v245, 8, v202
	v_and_b32_e32 v240, 7, v242
	v_lshl_add_u32 v240, v245, 6, v240
	v_lshl_add_u32 v240, s20, 8, v240
	v_lshlrev_b32_e32 v240, 14, v240
	v_lshrrev_b32_e32 v241, 3, v242
	v_lshlrev_b32_e32 v241, 6, v241
	v_lshl_add_u32 v241, v244, 7, v241
	v_lshl_add_u32 v241, v243, 4, v241
	v_add_u32_e32 v240, v240, v241
	s_lshl_b32 s98, s40, 9
	v_add_u32_e32 v240, s98, v240
	v_max_f32_e32 v124, 0, v124
	v_max_f32_e32 v125, 0, v125
	v_max_f32_e32 v126, 0, v126
	v_max_f32_e32 v127, 0, v127
	v_max_f32_e32 v120, 0, v120
	v_max_f32_e32 v121, 0, v121
	v_max_f32_e32 v122, 0, v122
	v_max_f32_e32 v123, 0, v123
	v_pk_mul_f32 v[124:125], v[124:125], v[124:125]
	v_pk_mul_f32 v[126:127], v[126:127], v[126:127]
	v_pk_mul_f32 v[120:121], v[120:121], v[120:121]
	v_pk_mul_f32 v[122:123], v[122:123], v[122:123]
	v_cvt_pk_bf16_f32 v228, v124, v125
	v_cvt_pk_bf16_f32 v229, v126, v127
	v_cvt_pk_bf16_f32 v230, v120, v121
	v_cvt_pk_bf16_f32 v231, v122, v123
	v_max_f32_e32 v116, 0, v116
	v_max_f32_e32 v117, 0, v117
	v_max_f32_e32 v118, 0, v118
	v_max_f32_e32 v119, 0, v119
	v_max_f32_e32 v112, 0, v112
	v_max_f32_e32 v113, 0, v113
	v_max_f32_e32 v114, 0, v114
	v_max_f32_e32 v115, 0, v115
	v_pk_mul_f32 v[116:117], v[116:117], v[116:117]
	v_pk_mul_f32 v[118:119], v[118:119], v[118:119]
	v_pk_mul_f32 v[112:113], v[112:113], v[112:113]
	v_pk_mul_f32 v[114:115], v[114:115], v[114:115]
	v_cvt_pk_bf16_f32 v232, v116, v117
	v_cvt_pk_bf16_f32 v233, v118, v119
	v_cvt_pk_bf16_f32 v234, v112, v113
	v_cvt_pk_bf16_f32 v235, v114, v115
	v_mov_b32_e32 v236, v228
	v_mov_b32_e32 v237, v229
	v_mov_b32_e32 v238, v230
	v_mov_b32_e32 v239, v231
	v_mov_b32_dpp v228, v232 row_ror:8 row_mask:0xf bank_mask:0xc
	v_mov_b32_dpp v229, v233 row_ror:8 row_mask:0xf bank_mask:0xc
	v_mov_b32_dpp v230, v234 row_ror:8 row_mask:0xf bank_mask:0xc
	v_mov_b32_dpp v231, v235 row_ror:8 row_mask:0xf bank_mask:0xc
	v_mov_b32_dpp v232, v236 row_ror:8 row_mask:0xf bank_mask:0x3
	v_mov_b32_dpp v233, v237 row_ror:8 row_mask:0xf bank_mask:0x3
	v_mov_b32_dpp v234, v238 row_ror:8 row_mask:0xf bank_mask:0x3
	v_mov_b32_dpp v235, v239 row_ror:8 row_mask:0xf bank_mask:0x3
	global_store_dwordx4 v240, v[228:231], s[100:101]
	s_add_u32 s100, s100, 0x20000
	s_addc_u32 s101, s101, 0
	global_store_dwordx4 v240, v[232:235], s[100:101]
	v_max_f32_e32 v108, 0, v108
	v_max_f32_e32 v109, 0, v109
	v_max_f32_e32 v110, 0, v110
	v_max_f32_e32 v111, 0, v111
	v_max_f32_e32 v104, 0, v104
	v_max_f32_e32 v105, 0, v105
	v_max_f32_e32 v106, 0, v106
	v_max_f32_e32 v107, 0, v107
	v_pk_mul_f32 v[108:109], v[108:109], v[108:109]
	v_pk_mul_f32 v[110:111], v[110:111], v[110:111]
	v_pk_mul_f32 v[104:105], v[104:105], v[104:105]
	v_pk_mul_f32 v[106:107], v[106:107], v[106:107]
	v_cvt_pk_bf16_f32 v228, v108, v109
	v_cvt_pk_bf16_f32 v229, v110, v111
	v_cvt_pk_bf16_f32 v230, v104, v105
	v_cvt_pk_bf16_f32 v231, v106, v107
	v_max_f32_e32 v100, 0, v100
	v_max_f32_e32 v101, 0, v101
	v_max_f32_e32 v102, 0, v102
	v_max_f32_e32 v103, 0, v103
	v_max_f32_e32 v96, 0, v96
	v_max_f32_e32 v97, 0, v97
	v_max_f32_e32 v98, 0, v98
	v_max_f32_e32 v99, 0, v99
	v_pk_mul_f32 v[100:101], v[100:101], v[100:101]
	v_pk_mul_f32 v[102:103], v[102:103], v[102:103]
	v_pk_mul_f32 v[96:97], v[96:97], v[96:97]
	v_pk_mul_f32 v[98:99], v[98:99], v[98:99]
	v_cvt_pk_bf16_f32 v232, v100, v101
	v_cvt_pk_bf16_f32 v233, v102, v103
	v_cvt_pk_bf16_f32 v234, v96, v97
	v_cvt_pk_bf16_f32 v235, v98, v99
	v_mov_b32_e32 v236, v228
	v_mov_b32_e32 v237, v229
	v_mov_b32_e32 v238, v230
	v_mov_b32_e32 v239, v231
	v_mov_b32_dpp v228, v232 row_ror:8 row_mask:0xf bank_mask:0xc
	v_mov_b32_dpp v229, v233 row_ror:8 row_mask:0xf bank_mask:0xc
	v_mov_b32_dpp v230, v234 row_ror:8 row_mask:0xf bank_mask:0xc
	v_mov_b32_dpp v231, v235 row_ror:8 row_mask:0xf bank_mask:0xc
	v_mov_b32_dpp v232, v236 row_ror:8 row_mask:0xf bank_mask:0x3
	v_mov_b32_dpp v233, v237 row_ror:8 row_mask:0xf bank_mask:0x3
	v_mov_b32_dpp v234, v238 row_ror:8 row_mask:0xf bank_mask:0x3
	v_mov_b32_dpp v235, v239 row_ror:8 row_mask:0xf bank_mask:0x3
	s_add_u32 s100, s100, 0x20000
	s_addc_u32 s101, s101, 0
	global_store_dwordx4 v240, v[228:231], s[100:101]
	s_add_u32 s100, s100, 0x20000
	s_addc_u32 s101, s101, 0
	global_store_dwordx4 v240, v[232:235], s[100:101]
	v_max_f32_e32 v92, 0, v92
	v_max_f32_e32 v93, 0, v93
	v_max_f32_e32 v94, 0, v94
	v_max_f32_e32 v95, 0, v95
	v_max_f32_e32 v88, 0, v88
	v_max_f32_e32 v89, 0, v89
	v_max_f32_e32 v90, 0, v90
	v_max_f32_e32 v91, 0, v91
	v_pk_mul_f32 v[92:93], v[92:93], v[92:93]
	v_pk_mul_f32 v[94:95], v[94:95], v[94:95]
	v_pk_mul_f32 v[88:89], v[88:89], v[88:89]
	v_pk_mul_f32 v[90:91], v[90:91], v[90:91]
	v_cvt_pk_bf16_f32 v228, v92, v93
	v_cvt_pk_bf16_f32 v229, v94, v95
	v_cvt_pk_bf16_f32 v230, v88, v89
	v_cvt_pk_bf16_f32 v231, v90, v91
	v_max_f32_e32 v84, 0, v84
	v_max_f32_e32 v85, 0, v85
	v_max_f32_e32 v86, 0, v86
	v_max_f32_e32 v87, 0, v87
	v_max_f32_e32 v80, 0, v80
	v_max_f32_e32 v81, 0, v81
	v_max_f32_e32 v82, 0, v82
	v_max_f32_e32 v83, 0, v83
	v_pk_mul_f32 v[84:85], v[84:85], v[84:85]
	v_pk_mul_f32 v[86:87], v[86:87], v[86:87]
	v_pk_mul_f32 v[80:81], v[80:81], v[80:81]
	v_pk_mul_f32 v[82:83], v[82:83], v[82:83]
	v_cvt_pk_bf16_f32 v232, v84, v85
	v_cvt_pk_bf16_f32 v233, v86, v87
	v_cvt_pk_bf16_f32 v234, v80, v81
	v_cvt_pk_bf16_f32 v235, v82, v83
	v_mov_b32_e32 v236, v228
	v_mov_b32_e32 v237, v229
	v_mov_b32_e32 v238, v230
	v_mov_b32_e32 v239, v231
	v_mov_b32_dpp v228, v232 row_ror:8 row_mask:0xf bank_mask:0xc
	v_mov_b32_dpp v229, v233 row_ror:8 row_mask:0xf bank_mask:0xc
	v_mov_b32_dpp v230, v234 row_ror:8 row_mask:0xf bank_mask:0xc
	v_mov_b32_dpp v231, v235 row_ror:8 row_mask:0xf bank_mask:0xc
	v_mov_b32_dpp v232, v236 row_ror:8 row_mask:0xf bank_mask:0x3
	v_mov_b32_dpp v233, v237 row_ror:8 row_mask:0xf bank_mask:0x3
	v_mov_b32_dpp v234, v238 row_ror:8 row_mask:0xf bank_mask:0x3
	v_mov_b32_dpp v235, v239 row_ror:8 row_mask:0xf bank_mask:0x3
	s_add_u32 s100, s100, 0x20000
	s_addc_u32 s101, s101, 0
	global_store_dwordx4 v240, v[228:231], s[100:101]
	s_add_u32 s100, s100, 0x20000
	s_addc_u32 s101, s101, 0
	global_store_dwordx4 v240, v[232:235], s[100:101]
	v_max_f32_e32 v76, 0, v76
	v_max_f32_e32 v77, 0, v77
	v_max_f32_e32 v78, 0, v78
	v_max_f32_e32 v79, 0, v79
	v_max_f32_e32 v72, 0, v72
	v_max_f32_e32 v73, 0, v73
	v_max_f32_e32 v74, 0, v74
	v_max_f32_e32 v75, 0, v75
	v_pk_mul_f32 v[76:77], v[76:77], v[76:77]
	v_pk_mul_f32 v[78:79], v[78:79], v[78:79]
	v_pk_mul_f32 v[72:73], v[72:73], v[72:73]
	v_pk_mul_f32 v[74:75], v[74:75], v[74:75]
	v_cvt_pk_bf16_f32 v228, v76, v77
	v_cvt_pk_bf16_f32 v229, v78, v79
	v_cvt_pk_bf16_f32 v230, v72, v73
	v_cvt_pk_bf16_f32 v231, v74, v75
	v_max_f32_e32 v68, 0, v68
	v_max_f32_e32 v69, 0, v69
	v_max_f32_e32 v70, 0, v70
	v_max_f32_e32 v71, 0, v71
	v_max_f32_e32 v64, 0, v64
	v_max_f32_e32 v65, 0, v65
	v_max_f32_e32 v66, 0, v66
	v_max_f32_e32 v67, 0, v67
	v_pk_mul_f32 v[68:69], v[68:69], v[68:69]
	v_pk_mul_f32 v[70:71], v[70:71], v[70:71]
	v_pk_mul_f32 v[64:65], v[64:65], v[64:65]
	v_pk_mul_f32 v[66:67], v[66:67], v[66:67]
	v_cvt_pk_bf16_f32 v232, v68, v69
	v_cvt_pk_bf16_f32 v233, v70, v71
	v_cvt_pk_bf16_f32 v234, v64, v65
	v_cvt_pk_bf16_f32 v235, v66, v67
	v_mov_b32_e32 v236, v228
	v_mov_b32_e32 v237, v229
	v_mov_b32_e32 v238, v230
	v_mov_b32_e32 v239, v231
	v_mov_b32_dpp v228, v232 row_ror:8 row_mask:0xf bank_mask:0xc
	v_mov_b32_dpp v229, v233 row_ror:8 row_mask:0xf bank_mask:0xc
	v_mov_b32_dpp v230, v234 row_ror:8 row_mask:0xf bank_mask:0xc
	v_mov_b32_dpp v231, v235 row_ror:8 row_mask:0xf bank_mask:0xc
	v_mov_b32_dpp v232, v236 row_ror:8 row_mask:0xf bank_mask:0x3
	v_mov_b32_dpp v233, v237 row_ror:8 row_mask:0xf bank_mask:0x3
	v_mov_b32_dpp v234, v238 row_ror:8 row_mask:0xf bank_mask:0x3
	v_mov_b32_dpp v235, v239 row_ror:8 row_mask:0xf bank_mask:0x3
	s_add_u32 s100, s100, 0x20000
	s_addc_u32 s101, s101, 0
	global_store_dwordx4 v240, v[228:231], s[100:101]
	s_add_u32 s100, s100, 0x20000
	s_addc_u32 s101, s101, 0
	global_store_dwordx4 v240, v[232:235], s[100:101]
	v_max_f32_e32 v60, 0, v60
	v_max_f32_e32 v61, 0, v61
	v_max_f32_e32 v62, 0, v62
	v_max_f32_e32 v63, 0, v63
	v_max_f32_e32 v56, 0, v56
	v_max_f32_e32 v57, 0, v57
	v_max_f32_e32 v58, 0, v58
	v_max_f32_e32 v59, 0, v59
	v_pk_mul_f32 v[60:61], v[60:61], v[60:61]
	v_pk_mul_f32 v[62:63], v[62:63], v[62:63]
	v_pk_mul_f32 v[56:57], v[56:57], v[56:57]
	v_pk_mul_f32 v[58:59], v[58:59], v[58:59]
	v_cvt_pk_bf16_f32 v228, v60, v61
	v_cvt_pk_bf16_f32 v229, v62, v63
	v_cvt_pk_bf16_f32 v230, v56, v57
	v_cvt_pk_bf16_f32 v231, v58, v59
	v_max_f32_e32 v52, 0, v52
	v_max_f32_e32 v53, 0, v53
	v_max_f32_e32 v54, 0, v54
	v_max_f32_e32 v55, 0, v55
	v_max_f32_e32 v48, 0, v48
	v_max_f32_e32 v49, 0, v49
	v_max_f32_e32 v50, 0, v50
	v_max_f32_e32 v51, 0, v51
	v_pk_mul_f32 v[52:53], v[52:53], v[52:53]
	v_pk_mul_f32 v[54:55], v[54:55], v[54:55]
	v_pk_mul_f32 v[48:49], v[48:49], v[48:49]
	v_pk_mul_f32 v[50:51], v[50:51], v[50:51]
	v_cvt_pk_bf16_f32 v232, v52, v53
	v_cvt_pk_bf16_f32 v233, v54, v55
	v_cvt_pk_bf16_f32 v234, v48, v49
	v_cvt_pk_bf16_f32 v235, v50, v51
	v_mov_b32_e32 v236, v228
	v_mov_b32_e32 v237, v229
	v_mov_b32_e32 v238, v230
	v_mov_b32_e32 v239, v231
	v_mov_b32_dpp v228, v232 row_ror:8 row_mask:0xf bank_mask:0xc
	v_mov_b32_dpp v229, v233 row_ror:8 row_mask:0xf bank_mask:0xc
	v_mov_b32_dpp v230, v234 row_ror:8 row_mask:0xf bank_mask:0xc
	v_mov_b32_dpp v231, v235 row_ror:8 row_mask:0xf bank_mask:0xc
	v_mov_b32_dpp v232, v236 row_ror:8 row_mask:0xf bank_mask:0x3
	v_mov_b32_dpp v233, v237 row_ror:8 row_mask:0xf bank_mask:0x3
	v_mov_b32_dpp v234, v238 row_ror:8 row_mask:0xf bank_mask:0x3
	v_mov_b32_dpp v235, v239 row_ror:8 row_mask:0xf bank_mask:0x3
	s_add_u32 s100, s100, 0x120000
	s_addc_u32 s101, s101, 0
	global_store_dwordx4 v240, v[228:231], s[100:101]
	s_add_u32 s100, s100, 0x20000
	s_addc_u32 s101, s101, 0
	global_store_dwordx4 v240, v[232:235], s[100:101]
	v_max_f32_e32 v44, 0, v44
	v_max_f32_e32 v45, 0, v45
	v_max_f32_e32 v46, 0, v46
	v_max_f32_e32 v47, 0, v47
	v_max_f32_e32 v40, 0, v40
	v_max_f32_e32 v41, 0, v41
	v_max_f32_e32 v42, 0, v42
	v_max_f32_e32 v43, 0, v43
	v_pk_mul_f32 v[44:45], v[44:45], v[44:45]
	v_pk_mul_f32 v[46:47], v[46:47], v[46:47]
	v_pk_mul_f32 v[40:41], v[40:41], v[40:41]
	v_pk_mul_f32 v[42:43], v[42:43], v[42:43]
	v_cvt_pk_bf16_f32 v228, v44, v45
	v_cvt_pk_bf16_f32 v229, v46, v47
	v_cvt_pk_bf16_f32 v230, v40, v41
	v_cvt_pk_bf16_f32 v231, v42, v43
	v_max_f32_e32 v36, 0, v36
	v_max_f32_e32 v37, 0, v37
	v_max_f32_e32 v38, 0, v38
	v_max_f32_e32 v39, 0, v39
	v_max_f32_e32 v32, 0, v32
	v_max_f32_e32 v33, 0, v33
	v_max_f32_e32 v34, 0, v34
	v_max_f32_e32 v35, 0, v35
	v_pk_mul_f32 v[36:37], v[36:37], v[36:37]
	v_pk_mul_f32 v[38:39], v[38:39], v[38:39]
	v_pk_mul_f32 v[32:33], v[32:33], v[32:33]
	v_pk_mul_f32 v[34:35], v[34:35], v[34:35]
	v_cvt_pk_bf16_f32 v232, v36, v37
	v_cvt_pk_bf16_f32 v233, v38, v39
	v_cvt_pk_bf16_f32 v234, v32, v33
	v_cvt_pk_bf16_f32 v235, v34, v35
	v_mov_b32_e32 v236, v228
	v_mov_b32_e32 v237, v229
	v_mov_b32_e32 v238, v230
	v_mov_b32_e32 v239, v231
	v_mov_b32_dpp v228, v232 row_ror:8 row_mask:0xf bank_mask:0xc
	v_mov_b32_dpp v229, v233 row_ror:8 row_mask:0xf bank_mask:0xc
	v_mov_b32_dpp v230, v234 row_ror:8 row_mask:0xf bank_mask:0xc
	v_mov_b32_dpp v231, v235 row_ror:8 row_mask:0xf bank_mask:0xc
	v_mov_b32_dpp v232, v236 row_ror:8 row_mask:0xf bank_mask:0x3
	v_mov_b32_dpp v233, v237 row_ror:8 row_mask:0xf bank_mask:0x3
	v_mov_b32_dpp v234, v238 row_ror:8 row_mask:0xf bank_mask:0x3
	v_mov_b32_dpp v235, v239 row_ror:8 row_mask:0xf bank_mask:0x3
	s_add_u32 s100, s100, 0x20000
	s_addc_u32 s101, s101, 0
	global_store_dwordx4 v240, v[228:231], s[100:101]
	s_add_u32 s100, s100, 0x20000
	s_addc_u32 s101, s101, 0
	global_store_dwordx4 v240, v[232:235], s[100:101]
	v_max_f32_e32 v28, 0, v28
	v_max_f32_e32 v29, 0, v29
	v_max_f32_e32 v30, 0, v30
	v_max_f32_e32 v31, 0, v31
	v_max_f32_e32 v24, 0, v24
	v_max_f32_e32 v25, 0, v25
	v_max_f32_e32 v26, 0, v26
	v_max_f32_e32 v27, 0, v27
	v_pk_mul_f32 v[28:29], v[28:29], v[28:29]
	v_pk_mul_f32 v[30:31], v[30:31], v[30:31]
	v_pk_mul_f32 v[24:25], v[24:25], v[24:25]
	v_pk_mul_f32 v[26:27], v[26:27], v[26:27]
	v_cvt_pk_bf16_f32 v228, v28, v29
	v_cvt_pk_bf16_f32 v229, v30, v31
	v_cvt_pk_bf16_f32 v230, v24, v25
	v_cvt_pk_bf16_f32 v231, v26, v27
	v_max_f32_e32 v20, 0, v20
	v_max_f32_e32 v21, 0, v21
	v_max_f32_e32 v22, 0, v22
	v_max_f32_e32 v23, 0, v23
	v_max_f32_e32 v16, 0, v16
	v_max_f32_e32 v17, 0, v17
	v_max_f32_e32 v18, 0, v18
	v_max_f32_e32 v19, 0, v19
	v_pk_mul_f32 v[20:21], v[20:21], v[20:21]
	v_pk_mul_f32 v[22:23], v[22:23], v[22:23]
	v_pk_mul_f32 v[16:17], v[16:17], v[16:17]
	v_pk_mul_f32 v[18:19], v[18:19], v[18:19]
	v_cvt_pk_bf16_f32 v232, v20, v21
	v_cvt_pk_bf16_f32 v233, v22, v23
	v_cvt_pk_bf16_f32 v234, v16, v17
	v_cvt_pk_bf16_f32 v235, v18, v19
	v_mov_b32_e32 v236, v228
	v_mov_b32_e32 v237, v229
	v_mov_b32_e32 v238, v230
	v_mov_b32_e32 v239, v231
	v_mov_b32_dpp v228, v232 row_ror:8 row_mask:0xf bank_mask:0xc
	v_mov_b32_dpp v229, v233 row_ror:8 row_mask:0xf bank_mask:0xc
	v_mov_b32_dpp v230, v234 row_ror:8 row_mask:0xf bank_mask:0xc
	v_mov_b32_dpp v231, v235 row_ror:8 row_mask:0xf bank_mask:0xc
	v_mov_b32_dpp v232, v236 row_ror:8 row_mask:0xf bank_mask:0x3
	v_mov_b32_dpp v233, v237 row_ror:8 row_mask:0xf bank_mask:0x3
	v_mov_b32_dpp v234, v238 row_ror:8 row_mask:0xf bank_mask:0x3
	v_mov_b32_dpp v235, v239 row_ror:8 row_mask:0xf bank_mask:0x3
	s_add_u32 s100, s100, 0x20000
	s_addc_u32 s101, s101, 0
	global_store_dwordx4 v240, v[228:231], s[100:101]
	s_add_u32 s100, s100, 0x20000
	s_addc_u32 s101, s101, 0
	global_store_dwordx4 v240, v[232:235], s[100:101]
	v_max_f32_e32 v12, 0, v12
	v_max_f32_e32 v13, 0, v13
	v_max_f32_e32 v14, 0, v14
	v_max_f32_e32 v15, 0, v15
	v_max_f32_e32 v8, 0, v8
	v_max_f32_e32 v9, 0, v9
	v_max_f32_e32 v10, 0, v10
	v_max_f32_e32 v11, 0, v11
	v_pk_mul_f32 v[12:13], v[12:13], v[12:13]
	v_pk_mul_f32 v[14:15], v[14:15], v[14:15]
	v_pk_mul_f32 v[8:9], v[8:9], v[8:9]
	v_pk_mul_f32 v[10:11], v[10:11], v[10:11]
	v_cvt_pk_bf16_f32 v228, v12, v13
	v_cvt_pk_bf16_f32 v229, v14, v15
	v_cvt_pk_bf16_f32 v230, v8, v9
	v_cvt_pk_bf16_f32 v231, v10, v11
	v_max_f32_e32 v4, 0, v4
	v_max_f32_e32 v5, 0, v5
	v_max_f32_e32 v6, 0, v6
	v_max_f32_e32 v7, 0, v7
	v_max_f32_e32 v0, 0, v0
	v_max_f32_e32 v1, 0, v1
	v_max_f32_e32 v2, 0, v2
	v_max_f32_e32 v3, 0, v3
	v_pk_mul_f32 v[4:5], v[4:5], v[4:5]
	v_pk_mul_f32 v[6:7], v[6:7], v[6:7]
	v_pk_mul_f32 v[0:1], v[0:1], v[0:1]
	v_pk_mul_f32 v[2:3], v[2:3], v[2:3]
	v_cvt_pk_bf16_f32 v232, v4, v5
	v_cvt_pk_bf16_f32 v233, v6, v7
	v_cvt_pk_bf16_f32 v234, v0, v1
	v_cvt_pk_bf16_f32 v235, v2, v3
	v_mov_b32_e32 v236, v228
	v_mov_b32_e32 v237, v229
	v_mov_b32_e32 v238, v230
	v_mov_b32_e32 v239, v231
	v_mov_b32_dpp v228, v232 row_ror:8 row_mask:0xf bank_mask:0xc
	v_mov_b32_dpp v229, v233 row_ror:8 row_mask:0xf bank_mask:0xc
	v_mov_b32_dpp v230, v234 row_ror:8 row_mask:0xf bank_mask:0xc
	v_mov_b32_dpp v231, v235 row_ror:8 row_mask:0xf bank_mask:0xc
	v_mov_b32_dpp v232, v236 row_ror:8 row_mask:0xf bank_mask:0x3
	v_mov_b32_dpp v233, v237 row_ror:8 row_mask:0xf bank_mask:0x3
	v_mov_b32_dpp v234, v238 row_ror:8 row_mask:0xf bank_mask:0x3
	v_mov_b32_dpp v235, v239 row_ror:8 row_mask:0xf bank_mask:0x3
	s_add_u32 s100, s100, 0x20000
	s_addc_u32 s101, s101, 0
	global_store_dwordx4 v240, v[228:231], s[100:101]
	s_add_u32 s100, s100, 0x20000
	s_addc_u32 s101, s101, 0
	global_store_dwordx4 v240, v[232:235], s[100:101]
	s_and_b64 vcc, exec, s[2:3]
	s_mov_b32 s40, s8
	s_mov_b32 s20, s14
	s_mov_b64 s[24:25], s[18:19]
	s_mov_b64 s[22:23], s[16:17]
	s_cbranch_vccz .LBB0_528
	s_waitcnt vmcnt(0)
	s_cmpk_gt_u32 s28, 0xff
	s_cbranch_scc1 .LBB0_535
	s_barrier

.LBB0_792:
	s_or_b64 exec, exec, s[0:1]
	s_add_u32 s12, s58, 0x24900000
	s_addc_u32 s13, s59, 0
	v_readlane_b32 s0, v248, 45
	v_mov_b32_e32 v10, v202
	s_waitcnt lgkmcnt(0)
	s_barrier
	s_cmpk_lt_i32 s0, 0x6e4
	s_nop 0
	v_readfirstlane_b32 s26, v10
	s_cbranch_scc0 .LBB0_814
	v_lshlrev_b32_e32 v0, 4, v10
	v_add_u32_e32 v1, 0x2000, v0
	v_ashrrev_i32_e32 v2, 31, v1
	v_lshrrev_b32_e32 v2, 22, v2
	v_add_u32_e32 v2, v1, v2
	v_ashrrev_i32_e32 v8, 10, v2
	v_mul_i32_i24_e32 v2, 0x400, v8
	v_sub_u32_e32 v1, v1, v2
	v_lshrrev_b32_e32 v2, 4, v1
	v_bitop3_b32 v1, v2, v1, 32 bitop3:0x6c
	v_ashrrev_i32_e32 v2, 31, v1
	v_lshrrev_b32_e32 v2, 26, v2
	v_add_u32_e32 v2, v1, v2
	v_lshlrev_b32_e32 v3, 3, v8
	v_ashrrev_i32_e32 v9, 6, v2
	v_and_b32_e32 v3, -16, v3
	v_add_u32_e32 v3, v9, v3
	v_and_b32_e32 v4, 3, v9
	s_mov_b32 s1, 0xfffe0
	v_lshrrev_b32_e32 v5, 2, v3
	v_lshlrev_b32_e32 v6, 1, v3
	v_and_b32_e32 v2, 0xc0, v2
	v_and_or_b32 v4, v3, s1, v4
	v_and_b32_e32 v5, 4, v5
	v_and_b32_e32 v6, 24, v6
	v_sub_u32_e32 v1, v1, v2
	v_mov_b32_e32 v2, 1
	v_or3_b32 v4, v4, v5, v6
	v_lshlrev_b32_e32 v5, 5, v8
	v_ashrrev_i16_sdwa v1, v2, sext(v1) dst_sel:DWORD dst_unused:UNUSED_PAD src0_sel:DWORD src1_sel:BYTE_0
	v_and_b32_e32 v5, 32, v5
	v_bfe_i32 v11, v1, 0, 16
	v_add_lshl_u32 v1, v5, v11, 1
	v_lshl_add_u32 v128, v4, 12, v1
	v_lshl_add_u32 v130, v3, 12, v1
	v_bfe_i32 v1, v10, 27, 1
	v_lshrrev_b32_e32 v1, 22, v1
	v_add_u32_e32 v1, v0, v1
	v_and_b32_e32 v1, 0xfffffc00, v1
	v_sub_u32_e32 v0, v0, v1
	v_lshrrev_b32_e32 v1, 4, v0
	v_ashrrev_i32_e32 v3, 31, v10
	v_bitop3_b32 v0, v1, v0, 32 bitop3:0x6c
	v_lshrrev_b32_e32 v3, 26, v3
	v_ashrrev_i32_e32 v1, 31, v0
	v_add_u32_e32 v3, v10, v3
	v_lshrrev_b32_e32 v1, 26, v1
	v_ashrrev_i32_e32 v13, 6, v3
	v_add_u32_e32 v1, v0, v1
	v_lshlrev_b32_e32 v3, 3, v13
	v_ashrrev_i32_e32 v12, 6, v1
	v_and_b32_e32 v3, -16, v3
	v_add_u32_e32 v3, v12, v3
	v_and_b32_e32 v4, 3, v12
	s_add_u32 s27, s58, 0x6000000
	v_and_or_b32 v4, v3, s1, v4
	v_readlane_b32 s1, v247, 8
	s_addc_u32 s28, s59, 0
	s_lshr_b32 s1, s1, 29
	v_readlane_b32 s4, v248, 45
	s_add_i32 s1, s4, s1
	s_and_b32 s2, s1, -8
	s_sub_i32 s2, s4, s2
	s_ashr_i32 s0, s26, 6
	s_mul_i32 s5, s2, 0xdc
	s_ashr_i32 s3, s26, 8
	s_lshl_b32 s29, s0, 10
	s_add_i32 s5, s5, 4
	s_ashr_i32 s1, s1, 3
	s_mul_i32 s4, s2, 0xdd
	s_cmp_lt_i32 s2, 4
	s_cselect_b32 s2, s4, s5
	s_add_i32 s2, s2, s1
	s_mul_hi_i32 s1, s2, 0x5397829d
	s_lshr_b32 s4, s1, 31
	s_ashr_i32 s1, s1, 7
	v_lshrrev_b32_e32 v5, 2, v3
	v_lshlrev_b32_e32 v6, 1, v3
	v_and_b32_e32 v1, 0xc0, v1
	s_add_i32 s1, s1, s4
	v_and_b32_e32 v5, 4, v5
	v_and_b32_e32 v6, 24, v6
	v_sub_u32_e32 v0, v0, v1
	s_lshl_b32 s6, s1, 3
	v_or3_b32 v4, v4, v5, v6
	v_lshlrev_b32_e32 v5, 5, v13
	v_ashrrev_i16_sdwa v0, v2, sext(v0) dst_sel:DWORD dst_unused:UNUSED_PAD src0_sel:DWORD src1_sel:BYTE_0
	s_sub_i32 s4, 36, s6
	s_mulk_i32 s1, 0x188
	v_and_b32_e32 v5, 32, v5
	v_bfe_i32 v14, v0, 0, 16
	s_min_u32 s7, s4, 8
	s_sub_i32 s1, s2, s1
	v_add_lshl_u32 v0, v5, v14, 1
	s_sext_i32_i16 s2, s1
	v_cvt_f32_ubyte0_e32 v2, s7
	v_lshl_add_u32 v132, v4, 12, v0
	v_cvt_f32_i32_e32 v1, s2
	v_rcp_iflag_f32_e32 v4, v2
	v_lshl_add_u32 v134, v3, 12, v0
	s_ashr_i32 s2, s2, 30
	s_or_b32 s2, s2, 1
	v_mul_f32_e32 v0, v1, v4
	v_trunc_f32_e32 v0, v0
	v_fma_f32 v1, -v0, v2, v1
	v_cvt_i32_f32_e32 v0, v0
	v_cmp_ge_f32_e64 s[4:5], |v1|, v2
	s_and_b64 s[4:5], s[4:5], exec
	s_cselect_b32 s2, s2, 0
	v_readfirstlane_b32 s4, v0
	s_add_i32 s2, s4, s2
	s_mul_i32 s4, s2, s7
	s_sub_i32 s1, s1, s4
	s_sext_i32_i16 s1, s1
	s_add_i32 s16, s6, s1
	s_ashr_i32 s17, s16, 31
	s_bfe_i64 s[6:7], s[2:3], 0x100000
	s_lshl_b64 s[4:5], s[16:17], 20
	s_lshl_b64 s[6:7], s[6:7], 20
	s_add_u32 s22, s27, s6
	s_addc_u32 s23, s28, s7
	s_add_i32 s30, s29, 0
	s_add_i32 m0, s30, 0x10000
	v_readlane_b32 s6, v247, 9
	v_mov_b32_e32 v230, s3
	v_lshlrev_b32_e32 v230, 17, v230
	v_add_u32_e32 v132, v132, v230
	v_add_u32_e32 v230, 0x40000, v230
	v_add_u32_e32 v128, v128, v230
	global_load_lds_dwordx4 v132, s[22:23]
	s_add_i32 m0, s30, 0x12000
	v_readlane_b32 s7, v247, 10
	s_add_u32 s20, s6, s4
	global_load_lds_dwordx4 v128, s[22:23]
	s_addc_u32 s21, s7, s5
	s_mov_b32 m0, s30
	s_add_i32 s31, s30, 0x2000
	global_load_lds_dwordx4 v134, s[20:21]
	s_mov_b32 m0, s31
	s_add_u32 s4, s22, 0x20000
	global_load_lds_dwordx4 v130, s[20:21]
	s_addc_u32 s5, s23, 0
	s_add_i32 m0, s30, 0x14000
	v_mov_b32_e32 v133, 0
	global_load_lds_dwordx4 v132, s[4:5]
	s_add_i32 m0, s30, 0x16000
	v_mov_b32_e32 v129, v133
	global_load_lds_dwordx4 v128, s[4:5]
	s_add_u32 s4, s20, 0x80000
	s_addc_u32 s5, s21, 0
	s_add_i32 s34, s30, 0x4000
	s_mov_b32 m0, s34
	s_add_i32 s35, s30, 0x6000
	global_load_lds_dwordx4 v134, s[4:5]
	s_mov_b32 m0, s35
	v_mov_b32_e32 v135, v133
	global_load_lds_dwordx4 v130, s[4:5]
	v_mov_b32_e32 v131, v133
	s_mov_b32 s36, 0
	v_lshl_add_u64 v[6:7], s[22:23], 0, v[132:133]
	v_lshl_add_u64 v[4:5], s[22:23], 0, v[128:129]
	v_lshl_add_u64 v[2:3], s[20:21], 0, v[134:135]
	s_cmp_lg_u32 s3, 1
	v_lshl_add_u64 v[0:1], s[20:21], 0, v[130:131]
	s_cbranch_scc1 .LBB0_795
	s_barrier
.LBB0_795:
	s_and_b32 s6, s0, 3
	s_mov_b64 s[0:1], 0x80
	s_add_i32 m0, s30, 0x18000
	v_lshl_add_u64 v[6:7], v[6:7], 0, s[0:1]
	s_lshl_b32 s7, s3, 13
	s_lshl_b32 s8, s6, 12
	s_waitcnt vmcnt(4)
	s_barrier
	global_load_lds_dwordx4 v[6:7], off
	v_lshl_add_u64 v[4:5], v[4:5], 0, s[0:1]
	s_add_i32 m0, s30, 0x1a000
	s_add_i32 s37, s30, 0x8000
	s_add_i32 s38, s30, 0xa000
	global_load_lds_dwordx4 v[4:5], off
	v_lshl_add_u64 v[2:3], v[2:3], 0, s[0:1]
	s_mov_b32 m0, s37
	s_add_u32 s4, s22, 0x20080
	global_load_lds_dwordx4 v[2:3], off
	v_lshl_add_u64 v[0:1], v[0:1], 0, s[0:1]
	s_mov_b32 m0, s38
	s_addc_u32 s5, s23, 0
	global_load_lds_dwordx4 v[0:1], off
	s_add_i32 m0, s30, 0x1c000
	v_lshl_add_u64 v[0:1], s[4:5], 0, v[132:133]
	global_load_lds_dwordx4 v[0:1], off
	v_lshl_add_u64 v[0:1], s[4:5], 0, v[128:129]
	s_add_i32 m0, s30, 0x1e000
	s_cmp_lt_u32 s6, 2
	global_load_lds_dwordx4 v[0:1], off
	v_lshrrev_b32_e32 v1, 1, v10
	v_and_b32_e32 v2, 24, v1
	v_and_b32_e32 v0, 15, v10
	v_lshlrev_b32_e32 v1, 1, v2
	v_lshl_or_b32 v148, s3, 6, v0
	v_lshl_or_b32 v0, v0, 6, v1
	v_lshlrev_b32_e32 v1, 2, v10
	s_sext_i32_i16 s41, s2
	s_cselect_b64 s[4:5], -1, 0
	s_lshl_b32 s2, s6, 7
	v_and_b32_e32 v1, 32, v1
	s_add_u32 s2, s12, s2
	v_bitop3_b32 v3, v0, s7, v1 bitop3:0xde
	v_bitop3_b32 v149, v0, s8, v1 bitop3:0xde
	s_addc_u32 s3, s13, 0
	v_lshlrev_b32_e32 v0, 2, v2
	v_mov_b32_e32 v1, v133
	v_lshl_add_u64 v[136:137], s[2:3], 0, v[0:1]
	v_lshlrev_b32_e32 v0, 15, v13
	v_and_b32_e32 v0, 0xffff0000, v0
	v_lshl_add_u32 v0, v12, 12, v0
	v_and_b32_e32 v1, 1, v13
	v_lshl_or_b32 v0, v1, 6, v0
	v_lshl_add_u32 v138, v14, 1, v0
	v_lshlrev_b32_e32 v0, 15, v8
	v_and_b32_e32 v0, 0xffff0000, v0
	s_waitcnt vmcnt(6)
	v_lshl_add_u32 v0, v9, 12, v0
	v_and_b32_e32 v1, 1, v8
	v_lshl_or_b32 v0, v1, 6, v0
	s_add_i32 s39, 0, 0x10000
	s_add_i32 s40, 0, 0x14000
	v_lshl_or_b32 v150, s6, 5, v2
	v_mov_b32_e32 v139, v133
	v_lshl_add_u32 v140, v11, 1, v0
	v_mov_b32_e32 v141, v133
	v_mov_b64_e32 v[142:143], 0x6e4
	v_mov_b64_e32 v[144:145], 0x6e3
	v_add_u32_e32 v151, s39, v149
	v_add_u32_e32 v152, 0, v3
	v_add_u32_e32 v153, s40, v149
	s_barrier
	s_branch .LBB0_797

.LBB0_804:
	ds_read_b128 v[154:157], v151
	ds_read_b128 v[158:161], v151 offset:1024
	ds_read_b128 v[162:165], v151 offset:2048
	ds_read_b128 v[166:169], v151 offset:3072
	s_add_u32 s22, s20, 0xfff80080
	s_addc_u32 s23, s21, -1
	s_cmp_eq_u32 s45, 28
	s_cselect_b32 s25, s9, s23
	s_cselect_b32 s24, s17, s22
	s_cselect_b32 s23, s7, s44
	s_cselect_b32 s22, s42, s43
	v_lshl_add_u64 v[146:147], s[20:21], 0, v[138:139]
	s_add_i32 m0, s30, 0xc000
	ds_read_b128 v[170:173], v152
	ds_read_b128 v[174:177], v152 offset:1024
	ds_read_b128 v[178:181], v152 offset:2048
	ds_read_b128 v[182:185], v152 offset:3072
	ds_read_b128 v[186:189], v152 offset:4096
	ds_read_b128 v[190:193], v152 offset:5120
	ds_read_b128 v[194:197], v152 offset:6144
	ds_read_b128 v[198:201], v152 offset:7168
	global_load_lds_dwordx4 v[146:147], off
	v_lshl_add_u64 v[146:147], s[20:21], 0, v[140:141]
	s_add_i32 m0, s30, 0xe000
	s_nop 0
	global_load_lds_dwordx4 v[146:147], off
	s_waitcnt lgkmcnt(8)
	s_barrier
	s_waitcnt lgkmcnt(0)
	s_setprio 1
	s_waitcnt lgkmcnt(0)
	v_mfma_f32_16x16x32_bf16 v[124:127], v[154:157], v[170:173], v[124:127]
	v_mfma_f32_16x16x32_bf16 v[120:123], v[162:165], v[170:173], v[120:123]
	v_mfma_f32_16x16x32_bf16 v[116:119], v[154:157], v[178:181], v[116:119]
	v_mfma_f32_16x16x32_bf16 v[112:115], v[162:165], v[178:181], v[112:115]
	v_mfma_f32_16x16x32_bf16 v[100:103], v[154:157], v[186:189], v[100:103]
	v_mfma_f32_16x16x32_bf16 v[96:99], v[162:165], v[186:189], v[96:99]
	v_mfma_f32_16x16x32_bf16 v[84:87], v[154:157], v[194:197], v[84:87]
	v_mfma_f32_16x16x32_bf16 v[80:83], v[162:165], v[194:197], v[80:83]
	v_mfma_f32_16x16x32_bf16 v[124:127], v[158:161], v[174:177], v[124:127]
	v_mfma_f32_16x16x32_bf16 v[120:123], v[166:169], v[174:177], v[120:123]
	v_mfma_f32_16x16x32_bf16 v[116:119], v[158:161], v[182:185], v[116:119]
	v_mfma_f32_16x16x32_bf16 v[112:115], v[166:169], v[182:185], v[112:115]
	v_mfma_f32_16x16x32_bf16 v[100:103], v[158:161], v[190:193], v[100:103]
	v_mfma_f32_16x16x32_bf16 v[96:99], v[166:169], v[190:193], v[96:99]
	v_mfma_f32_16x16x32_bf16 v[84:87], v[158:161], v[198:201], v[84:87]
	v_mfma_f32_16x16x32_bf16 v[80:83], v[166:169], v[198:201], v[80:83]
	s_setprio 0
	s_barrier
	s_add_i32 s46, s39, s29
	v_lshl_add_u64 v[146:147], s[22:23], 0, v[132:133]
	s_mov_b32 m0, s46
	ds_read_b128 v[204:207], v153
	ds_read_b128 v[208:211], v153 offset:1024
	ds_read_b128 v[212:215], v153 offset:2048
	ds_read_b128 v[216:219], v153 offset:3072
	global_load_lds_dwordx4 v[146:147], off
	v_lshl_add_u64 v[220:221], s[22:23], 0, v[128:129]
	s_add_i32 m0, s46, 0x2000
	s_nop 0
	global_load_lds_dwordx4 v[220:221], off
	s_barrier
	s_waitcnt lgkmcnt(0)
	s_setprio 1
	s_waitcnt lgkmcnt(0)
	v_mfma_f32_16x16x32_bf16 v[108:111], v[204:207], v[170:173], v[108:111]
	v_mfma_f32_16x16x32_bf16 v[104:107], v[212:215], v[170:173], v[104:107]
	v_mfma_f32_16x16x32_bf16 v[92:95], v[204:207], v[178:181], v[92:95]
	v_mfma_f32_16x16x32_bf16 v[88:91], v[212:215], v[178:181], v[88:91]
	v_mfma_f32_16x16x32_bf16 v[76:79], v[204:207], v[186:189], v[76:79]
	v_mfma_f32_16x16x32_bf16 v[72:75], v[212:215], v[186:189], v[72:75]
	v_mfma_f32_16x16x32_bf16 v[68:71], v[204:207], v[194:197], v[68:71]
	v_mfma_f32_16x16x32_bf16 v[64:67], v[212:215], v[194:197], v[64:67]
	v_mfma_f32_16x16x32_bf16 v[108:111], v[208:211], v[174:177], v[108:111]
	v_mfma_f32_16x16x32_bf16 v[104:107], v[216:219], v[174:177], v[104:107]
	v_mfma_f32_16x16x32_bf16 v[92:95], v[208:211], v[182:185], v[92:95]
	v_mfma_f32_16x16x32_bf16 v[88:91], v[216:219], v[182:185], v[88:91]
	v_mfma_f32_16x16x32_bf16 v[76:79], v[208:211], v[190:193], v[76:79]
	v_mfma_f32_16x16x32_bf16 v[72:75], v[216:219], v[190:193], v[72:75]
	v_mfma_f32_16x16x32_bf16 v[68:71], v[208:211], v[198:201], v[68:71]
	v_mfma_f32_16x16x32_bf16 v[64:67], v[216:219], v[198:201], v[64:67]
	s_setprio 0
	s_mov_b32 m0, s30
	v_lshl_add_u64 v[222:223], s[24:25], 0, v[134:135]
	s_barrier
	ds_read_b128 v[170:173], v152 offset:16384
	ds_read_b128 v[174:177], v152 offset:17408
	ds_read_b128 v[178:181], v152 offset:18432
	ds_read_b128 v[182:185], v152 offset:19456
	ds_read_b128 v[186:189], v152 offset:20480
	ds_read_b128 v[190:193], v152 offset:21504
	ds_read_b128 v[194:197], v152 offset:22528
	ds_read_b128 v[198:201], v152 offset:23552
	global_load_lds_dwordx4 v[222:223], off
	v_lshl_add_u64 v[224:225], s[24:25], 0, v[130:131]
	s_mov_b32 m0, s31
	s_nop 0
	global_load_lds_dwordx4 v[224:225], off
	s_barrier
	s_waitcnt lgkmcnt(0)
	s_setprio 1
	s_waitcnt lgkmcnt(0)
	v_mfma_f32_16x16x32_bf16 v[60:63], v[154:157], v[170:173], v[60:63]
	v_mfma_f32_16x16x32_bf16 v[56:59], v[162:165], v[170:173], v[56:59]
	v_mfma_f32_16x16x32_bf16 v[52:55], v[154:157], v[178:181], v[52:55]
	v_mfma_f32_16x16x32_bf16 v[48:51], v[162:165], v[178:181], v[48:51]
	v_mfma_f32_16x16x32_bf16 v[36:39], v[154:157], v[186:189], v[36:39]
	v_mfma_f32_16x16x32_bf16 v[32:35], v[162:165], v[186:189], v[32:35]
	v_mfma_f32_16x16x32_bf16 v[20:23], v[154:157], v[194:197], v[20:23]
	v_mfma_f32_16x16x32_bf16 v[16:19], v[162:165], v[194:197], v[16:19]
	v_mfma_f32_16x16x32_bf16 v[60:63], v[158:161], v[174:177], v[60:63]
	v_mfma_f32_16x16x32_bf16 v[56:59], v[166:169], v[174:177], v[56:59]
	v_mfma_f32_16x16x32_bf16 v[52:55], v[158:161], v[182:185], v[52:55]
	v_mfma_f32_16x16x32_bf16 v[48:51], v[166:169], v[182:185], v[48:51]
	v_mfma_f32_16x16x32_bf16 v[36:39], v[158:161], v[190:193], v[36:39]
	v_mfma_f32_16x16x32_bf16 v[32:35], v[166:169], v[190:193], v[32:35]
	v_mfma_f32_16x16x32_bf16 v[20:23], v[158:161], v[198:201], v[20:23]
	v_mfma_f32_16x16x32_bf16 v[16:19], v[166:169], v[198:201], v[16:19]
	s_setprio 0
	s_barrier
	s_add_u32 s46, s22, 0x20000
	s_addc_u32 s47, s23, 0
	s_add_i32 s48, s40, s29
	v_lshl_add_u64 v[154:155], s[46:47], 0, v[132:133]
	s_mov_b32 m0, s48
	s_nop 0
	global_load_lds_dwordx4 v[154:155], off
	v_lshl_add_u64 v[154:155], s[46:47], 0, v[128:129]
	s_add_i32 m0, s48, 0x2000
	s_nop 0
	global_load_lds_dwordx4 v[154:155], off
	s_waitcnt vmcnt(6)
	s_barrier
	s_setprio 1
	v_mfma_f32_16x16x32_bf16 v[44:47], v[204:207], v[170:173], v[44:47]
	v_mfma_f32_16x16x32_bf16 v[40:43], v[212:215], v[170:173], v[40:43]
	v_mfma_f32_16x16x32_bf16 v[28:31], v[204:207], v[178:181], v[28:31]
	v_mfma_f32_16x16x32_bf16 v[24:27], v[212:215], v[178:181], v[24:27]
	v_mfma_f32_16x16x32_bf16 v[12:15], v[204:207], v[186:189], v[12:15]
	v_mfma_f32_16x16x32_bf16 v[8:11], v[212:215], v[186:189], v[8:11]
	v_mfma_f32_16x16x32_bf16 v[4:7], v[204:207], v[194:197], v[4:7]
	v_mfma_f32_16x16x32_bf16 v[0:3], v[212:215], v[194:197], v[0:3]
	v_mfma_f32_16x16x32_bf16 v[44:47], v[208:211], v[174:177], v[44:47]
	v_mfma_f32_16x16x32_bf16 v[40:43], v[216:219], v[174:177], v[40:43]
	v_mfma_f32_16x16x32_bf16 v[28:31], v[208:211], v[182:185], v[28:31]
	v_mfma_f32_16x16x32_bf16 v[24:27], v[216:219], v[182:185], v[24:27]
	v_mfma_f32_16x16x32_bf16 v[12:15], v[208:211], v[190:193], v[12:15]
	v_mfma_f32_16x16x32_bf16 v[8:11], v[216:219], v[190:193], v[8:11]
	v_mfma_f32_16x16x32_bf16 v[4:7], v[208:211], v[198:201], v[4:7]
	v_mfma_f32_16x16x32_bf16 v[0:3], v[216:219], v[198:201], v[0:3]
	s_setprio 0
	s_add_i32 s46, 0, 0x18000
	v_add_u32_e32 v166, s46, v149
	s_barrier
	ds_read_b128 v[154:157], v166
	ds_read_b128 v[158:161], v166 offset:1024
	ds_read_b128 v[162:165], v166 offset:2048
	ds_read_b128 v[166:169], v166 offset:3072
	s_add_u32 s24, s24, 0x80000
	s_addc_u32 s25, s25, 0
	s_mov_b32 m0, s34
	v_lshl_add_u64 v[204:205], s[24:25], 0, v[134:135]
	ds_read_b128 v[170:173], v152 offset:32768
	ds_read_b128 v[174:177], v152 offset:33792
	ds_read_b128 v[178:181], v152 offset:34816
	ds_read_b128 v[182:185], v152 offset:35840
	ds_read_b128 v[186:189], v152 offset:36864
	ds_read_b128 v[190:193], v152 offset:37888
	ds_read_b128 v[194:197], v152 offset:38912
	ds_read_b128 v[198:201], v152 offset:39936
	global_load_lds_dwordx4 v[204:205], off
	v_lshl_add_u64 v[204:205], s[24:25], 0, v[130:131]
	s_mov_b32 m0, s35
	s_nop 0
	global_load_lds_dwordx4 v[204:205], off
	s_waitcnt lgkmcnt(8)
	s_barrier
	s_waitcnt lgkmcnt(0)
	s_setprio 1
	s_waitcnt lgkmcnt(0)
	v_mfma_f32_16x16x32_bf16 v[124:127], v[154:157], v[170:173], v[124:127]
	v_mfma_f32_16x16x32_bf16 v[120:123], v[162:165], v[170:173], v[120:123]
	v_mfma_f32_16x16x32_bf16 v[116:119], v[154:157], v[178:181], v[116:119]
	v_mfma_f32_16x16x32_bf16 v[112:115], v[162:165], v[178:181], v[112:115]
	v_mfma_f32_16x16x32_bf16 v[100:103], v[154:157], v[186:189], v[100:103]
	v_mfma_f32_16x16x32_bf16 v[96:99], v[162:165], v[186:189], v[96:99]
	v_mfma_f32_16x16x32_bf16 v[84:87], v[154:157], v[194:197], v[84:87]
	v_mfma_f32_16x16x32_bf16 v[80:83], v[162:165], v[194:197], v[80:83]
	v_mfma_f32_16x16x32_bf16 v[124:127], v[158:161], v[174:177], v[124:127]
	v_mfma_f32_16x16x32_bf16 v[120:123], v[166:169], v[174:177], v[120:123]
	v_mfma_f32_16x16x32_bf16 v[116:119], v[158:161], v[182:185], v[116:119]
	v_mfma_f32_16x16x32_bf16 v[112:115], v[166:169], v[182:185], v[112:115]
	v_mfma_f32_16x16x32_bf16 v[100:103], v[158:161], v[190:193], v[100:103]
	v_mfma_f32_16x16x32_bf16 v[96:99], v[166:169], v[190:193], v[96:99]
	v_mfma_f32_16x16x32_bf16 v[84:87], v[158:161], v[198:201], v[84:87]
	v_mfma_f32_16x16x32_bf16 v[80:83], v[166:169], v[198:201], v[80:83]
	s_setprio 0
	s_barrier
	s_add_i32 s24, 0, 0x1c000
	s_add_i32 s25, s46, s29
	v_add_u32_e32 v216, s24, v149
	v_lshl_add_u64 v[146:147], v[146:147], 0, s[0:1]
	s_mov_b32 m0, s25
	ds_read_b128 v[204:207], v216
	ds_read_b128 v[208:211], v216 offset:1024
	ds_read_b128 v[212:215], v216 offset:2048
	ds_read_b128 v[216:219], v216 offset:3072
	global_load_lds_dwordx4 v[146:147], off
	v_lshl_add_u64 v[146:147], v[220:221], 0, s[0:1]
	s_add_i32 m0, s25, 0x2000
	s_nop 0
	global_load_lds_dwordx4 v[146:147], off
	s_barrier
	s_waitcnt lgkmcnt(0)
	s_setprio 1
	s_waitcnt lgkmcnt(0)
	v_mfma_f32_16x16x32_bf16 v[108:111], v[204:207], v[170:173], v[108:111]
	v_mfma_f32_16x16x32_bf16 v[104:107], v[212:215], v[170:173], v[104:107]
	v_mfma_f32_16x16x32_bf16 v[92:95], v[204:207], v[178:181], v[92:95]
	v_mfma_f32_16x16x32_bf16 v[88:91], v[212:215], v[178:181], v[88:91]
	v_mfma_f32_16x16x32_bf16 v[76:79], v[204:207], v[186:189], v[76:79]
	v_mfma_f32_16x16x32_bf16 v[72:75], v[212:215], v[186:189], v[72:75]
	v_mfma_f32_16x16x32_bf16 v[68:71], v[204:207], v[194:197], v[68:71]
	v_mfma_f32_16x16x32_bf16 v[64:67], v[212:215], v[194:197], v[64:67]
	v_mfma_f32_16x16x32_bf16 v[108:111], v[208:211], v[174:177], v[108:111]
	v_mfma_f32_16x16x32_bf16 v[104:107], v[216:219], v[174:177], v[104:107]
	v_mfma_f32_16x16x32_bf16 v[92:95], v[208:211], v[182:185], v[92:95]
	v_mfma_f32_16x16x32_bf16 v[88:91], v[216:219], v[182:185], v[88:91]
	v_mfma_f32_16x16x32_bf16 v[76:79], v[208:211], v[190:193], v[76:79]
	v_mfma_f32_16x16x32_bf16 v[72:75], v[216:219], v[190:193], v[72:75]
	v_mfma_f32_16x16x32_bf16 v[68:71], v[208:211], v[198:201], v[68:71]
	v_mfma_f32_16x16x32_bf16 v[64:67], v[216:219], v[198:201], v[64:67]
	s_setprio 0
	s_mov_b32 m0, s37
	v_lshl_add_u64 v[146:147], v[222:223], 0, s[0:1]
	s_barrier
	ds_read_b128 v[170:173], v152 offset:49152
	ds_read_b128 v[174:177], v152 offset:50176
	ds_read_b128 v[178:181], v152 offset:51200
	ds_read_b128 v[182:185], v152 offset:52224
	ds_read_b128 v[186:189], v152 offset:53248
	ds_read_b128 v[190:193], v152 offset:54272
	ds_read_b128 v[194:197], v152 offset:55296
	ds_read_b128 v[198:201], v152 offset:56320
	global_load_lds_dwordx4 v[146:147], off
	v_lshl_add_u64 v[146:147], v[224:225], 0, s[0:1]
	s_mov_b32 m0, s38
	s_nop 0
	global_load_lds_dwordx4 v[146:147], off
	s_barrier
	s_waitcnt lgkmcnt(0)
	s_setprio 1
	s_waitcnt lgkmcnt(0)
	v_mfma_f32_16x16x32_bf16 v[60:63], v[154:157], v[170:173], v[60:63]
	v_mfma_f32_16x16x32_bf16 v[56:59], v[162:165], v[170:173], v[56:59]
	v_mfma_f32_16x16x32_bf16 v[52:55], v[154:157], v[178:181], v[52:55]
	v_mfma_f32_16x16x32_bf16 v[48:51], v[162:165], v[178:181], v[48:51]
	v_mfma_f32_16x16x32_bf16 v[36:39], v[154:157], v[186:189], v[36:39]
	v_mfma_f32_16x16x32_bf16 v[32:35], v[162:165], v[186:189], v[32:35]
	v_mfma_f32_16x16x32_bf16 v[20:23], v[154:157], v[194:197], v[20:23]
	v_mfma_f32_16x16x32_bf16 v[16:19], v[162:165], v[194:197], v[16:19]
	v_mfma_f32_16x16x32_bf16 v[60:63], v[158:161], v[174:177], v[60:63]
	v_mfma_f32_16x16x32_bf16 v[56:59], v[166:169], v[174:177], v[56:59]
	v_mfma_f32_16x16x32_bf16 v[52:55], v[158:161], v[182:185], v[52:55]
	v_mfma_f32_16x16x32_bf16 v[48:51], v[166:169], v[182:185], v[48:51]
	v_mfma_f32_16x16x32_bf16 v[36:39], v[158:161], v[190:193], v[36:39]
	v_mfma_f32_16x16x32_bf16 v[32:35], v[166:169], v[190:193], v[32:35]
	v_mfma_f32_16x16x32_bf16 v[20:23], v[158:161], v[198:201], v[20:23]
	v_mfma_f32_16x16x32_bf16 v[16:19], v[166:169], v[198:201], v[16:19]
	s_setprio 0
	s_barrier
	s_add_u32 s22, s22, 0x20080
	s_addc_u32 s23, s23, 0
	s_add_i32 s24, s24, s29
	v_lshl_add_u64 v[146:147], s[22:23], 0, v[132:133]
	s_mov_b32 m0, s24
	s_nop 0
	global_load_lds_dwordx4 v[146:147], off
	v_lshl_add_u64 v[146:147], s[22:23], 0, v[128:129]
	s_add_i32 m0, s24, 0x2000
	s_nop 0
	global_load_lds_dwordx4 v[146:147], off
	s_waitcnt vmcnt(6)
	s_barrier
	s_setprio 1
	v_mfma_f32_16x16x32_bf16 v[44:47], v[204:207], v[170:173], v[44:47]
	v_mfma_f32_16x16x32_bf16 v[40:43], v[212:215], v[170:173], v[40:43]
	v_mfma_f32_16x16x32_bf16 v[28:31], v[204:207], v[178:181], v[28:31]
	v_mfma_f32_16x16x32_bf16 v[24:27], v[212:215], v[178:181], v[24:27]
	v_mfma_f32_16x16x32_bf16 v[12:15], v[204:207], v[186:189], v[12:15]
	v_mfma_f32_16x16x32_bf16 v[8:11], v[212:215], v[186:189], v[8:11]
	v_mfma_f32_16x16x32_bf16 v[4:7], v[204:207], v[194:197], v[4:7]
	v_mfma_f32_16x16x32_bf16 v[0:3], v[212:215], v[194:197], v[0:3]
	v_mfma_f32_16x16x32_bf16 v[44:47], v[208:211], v[174:177], v[44:47]
	v_mfma_f32_16x16x32_bf16 v[40:43], v[216:219], v[174:177], v[40:43]
	v_mfma_f32_16x16x32_bf16 v[28:31], v[208:211], v[182:185], v[28:31]
	v_mfma_f32_16x16x32_bf16 v[24:27], v[216:219], v[182:185], v[24:27]
	v_mfma_f32_16x16x32_bf16 v[12:15], v[208:211], v[190:193], v[12:15]
	v_mfma_f32_16x16x32_bf16 v[8:11], v[216:219], v[190:193], v[8:11]
	v_mfma_f32_16x16x32_bf16 v[4:7], v[208:211], v[198:201], v[4:7]
	v_mfma_f32_16x16x32_bf16 v[0:3], v[216:219], v[198:201], v[0:3]
	s_setprio 0
	s_add_i32 s45, s45, 2
	s_add_u32 s20, s20, 0x100
	s_addc_u32 s21, s21, 0
	s_add_u32 s43, s43, 0x100
	s_addc_u32 s44, s44, 0
	s_cmp_gt_u32 s45, 29
	s_barrier
	s_cbranch_scc0 .LBB0_804
	v_and_b32_e32 v242, 15, v202
	v_bfe_u32 v243, v202, 4, 2
	v_bfe_u32 v244, v202, 6, 2
	v_lshrrev_b32_e32 v245, 8, v202
	s_cmp_gt_i32 s41, 47
	s_cbranch_scc1 .Lfl8_ba
	s_cmp_gt_i32 s41, 31
	s_cbranch_scc1 .Lfl8_z
	v_readlane_b32 s100, v248, 63
	v_readlane_b32 s101, v247, 0
	v_and_b32_e32 v240, 7, v242
	v_lshl_add_u32 v240, v245, 6, v240
	v_lshl_add_u32 v240, s16, 8, v240
	v_lshlrev_b32_e32 v240, 14, v240
	v_lshrrev_b32_e32 v241, 3, v242
	v_lshlrev_b32_e32 v241, 6, v241
	v_lshl_add_u32 v241, v244, 7, v241
	v_lshl_add_u32 v241, v243, 4, v241
	v_add_u32_e32 v240, v240, v241
	s_lshl_b32 s98, s41, 9
	v_add_u32_e32 v240, s98, v240
	v_cvt_pk_bf16_f32 v228, v124, v125
	v_cvt_pk_bf16_f32 v229, v126, v127
	v_cvt_pk_bf16_f32 v230, v120, v121
	v_cvt_pk_bf16_f32 v231, v122, v123
	v_cvt_pk_bf16_f32 v232, v108, v109
	v_cvt_pk_bf16_f32 v233, v110, v111
	v_cvt_pk_bf16_f32 v234, v104, v105
	v_cvt_pk_bf16_f32 v235, v106, v107
	v_mov_b32_e32 v236, v228
	v_mov_b32_e32 v237, v229
	v_mov_b32_e32 v238, v230
	v_mov_b32_e32 v239, v231
	v_mov_b32_dpp v228, v232 row_ror:8 row_mask:0xf bank_mask:0xc
	v_mov_b32_dpp v229, v233 row_ror:8 row_mask:0xf bank_mask:0xc
	v_mov_b32_dpp v230, v234 row_ror:8 row_mask:0xf bank_mask:0xc
	v_mov_b32_dpp v231, v235 row_ror:8 row_mask:0xf bank_mask:0xc
	v_mov_b32_dpp v232, v236 row_ror:8 row_mask:0xf bank_mask:0x3
	v_mov_b32_dpp v233, v237 row_ror:8 row_mask:0xf bank_mask:0x3
	v_mov_b32_dpp v234, v238 row_ror:8 row_mask:0xf bank_mask:0x3
	v_mov_b32_dpp v235, v239 row_ror:8 row_mask:0xf bank_mask:0x3
	global_store_dwordx4 v240, v[228:231], s[100:101]
	s_add_u32 s100, s100, 0x20000
	s_addc_u32 s101, s101, 0
	global_store_dwordx4 v240, v[232:235], s[100:101]
	v_cvt_pk_bf16_f32 v228, v116, v117
	v_cvt_pk_bf16_f32 v229, v118, v119
	v_cvt_pk_bf16_f32 v230, v112, v113
	v_cvt_pk_bf16_f32 v231, v114, v115
	v_cvt_pk_bf16_f32 v232, v92, v93
	v_cvt_pk_bf16_f32 v233, v94, v95
	v_cvt_pk_bf16_f32 v234, v88, v89
	v_cvt_pk_bf16_f32 v235, v90, v91
	v_mov_b32_e32 v236, v228
	v_mov_b32_e32 v237, v229
	v_mov_b32_e32 v238, v230
	v_mov_b32_e32 v239, v231
	v_mov_b32_dpp v228, v232 row_ror:8 row_mask:0xf bank_mask:0xc
	v_mov_b32_dpp v229, v233 row_ror:8 row_mask:0xf bank_mask:0xc
	v_mov_b32_dpp v230, v234 row_ror:8 row_mask:0xf bank_mask:0xc
	v_mov_b32_dpp v231, v235 row_ror:8 row_mask:0xf bank_mask:0xc
	v_mov_b32_dpp v232, v236 row_ror:8 row_mask:0xf bank_mask:0x3
	v_mov_b32_dpp v233, v237 row_ror:8 row_mask:0xf bank_mask:0x3
	v_mov_b32_dpp v234, v238 row_ror:8 row_mask:0xf bank_mask:0x3
	v_mov_b32_dpp v235, v239 row_ror:8 row_mask:0xf bank_mask:0x3
	s_add_u32 s100, s100, 0x20000
	s_addc_u32 s101, s101, 0
	global_store_dwordx4 v240, v[228:231], s[100:101]
	s_add_u32 s100, s100, 0x20000
	s_addc_u32 s101, s101, 0
	global_store_dwordx4 v240, v[232:235], s[100:101]
	v_cvt_pk_bf16_f32 v228, v100, v101
	v_cvt_pk_bf16_f32 v229, v102, v103
	v_cvt_pk_bf16_f32 v230, v96, v97
	v_cvt_pk_bf16_f32 v231, v98, v99
	v_cvt_pk_bf16_f32 v232, v76, v77
	v_cvt_pk_bf16_f32 v233, v78, v79
	v_cvt_pk_bf16_f32 v234, v72, v73
	v_cvt_pk_bf16_f32 v235, v74, v75
	v_mov_b32_e32 v236, v228
	v_mov_b32_e32 v237, v229
	v_mov_b32_e32 v238, v230
	v_mov_b32_e32 v239, v231
	v_mov_b32_dpp v228, v232 row_ror:8 row_mask:0xf bank_mask:0xc
	v_mov_b32_dpp v229, v233 row_ror:8 row_mask:0xf bank_mask:0xc
	v_mov_b32_dpp v230, v234 row_ror:8 row_mask:0xf bank_mask:0xc
	v_mov_b32_dpp v231, v235 row_ror:8 row_mask:0xf bank_mask:0xc
	v_mov_b32_dpp v232, v236 row_ror:8 row_mask:0xf bank_mask:0x3
	v_mov_b32_dpp v233, v237 row_ror:8 row_mask:0xf bank_mask:0x3
	v_mov_b32_dpp v234, v238 row_ror:8 row_mask:0xf bank_mask:0x3
	v_mov_b32_dpp v235, v239 row_ror:8 row_mask:0xf bank_mask:0x3
	s_add_u32 s100, s100, 0x20000
	s_addc_u32 s101, s101, 0
	global_store_dwordx4 v240, v[228:231], s[100:101]
	s_add_u32 s100, s100, 0x20000
	s_addc_u32 s101, s101, 0
	global_store_dwordx4 v240, v[232:235], s[100:101]
	v_cvt_pk_bf16_f32 v228, v84, v85
	v_cvt_pk_bf16_f32 v229, v86, v87
	v_cvt_pk_bf16_f32 v230, v80, v81
	v_cvt_pk_bf16_f32 v231, v82, v83
	v_cvt_pk_bf16_f32 v232, v68, v69
	v_cvt_pk_bf16_f32 v233, v70, v71
	v_cvt_pk_bf16_f32 v234, v64, v65
	v_cvt_pk_bf16_f32 v235, v66, v67
	v_mov_b32_e32 v236, v228
	v_mov_b32_e32 v237, v229
	v_mov_b32_e32 v238, v230
	v_mov_b32_e32 v239, v231
	v_mov_b32_dpp v228, v232 row_ror:8 row_mask:0xf bank_mask:0xc
	v_mov_b32_dpp v229, v233 row_ror:8 row_mask:0xf bank_mask:0xc
	v_mov_b32_dpp v230, v234 row_ror:8 row_mask:0xf bank_mask:0xc
	v_mov_b32_dpp v231, v235 row_ror:8 row_mask:0xf bank_mask:0xc
	v_mov_b32_dpp v232, v236 row_ror:8 row_mask:0xf bank_mask:0x3
	v_mov_b32_dpp v233, v237 row_ror:8 row_mask:0xf bank_mask:0x3
	v_mov_b32_dpp v234, v238 row_ror:8 row_mask:0xf bank_mask:0x3
	v_mov_b32_dpp v235, v239 row_ror:8 row_mask:0xf bank_mask:0x3
	s_add_u32 s100, s100, 0x20000
	s_addc_u32 s101, s101, 0
	global_store_dwordx4 v240, v[228:231], s[100:101]
	s_add_u32 s100, s100, 0x20000
	s_addc_u32 s101, s101, 0
	global_store_dwordx4 v240, v[232:235], s[100:101]
	v_cvt_pk_bf16_f32 v228, v60, v61
	v_cvt_pk_bf16_f32 v229, v62, v63
	v_cvt_pk_bf16_f32 v230, v56, v57
	v_cvt_pk_bf16_f32 v231, v58, v59
	v_cvt_pk_bf16_f32 v232, v44, v45
	v_cvt_pk_bf16_f32 v233, v46, v47
	v_cvt_pk_bf16_f32 v234, v40, v41
	v_cvt_pk_bf16_f32 v235, v42, v43
	v_mov_b32_e32 v236, v228
	v_mov_b32_e32 v237, v229
	v_mov_b32_e32 v238, v230
	v_mov_b32_e32 v239, v231
	v_mov_b32_dpp v228, v232 row_ror:8 row_mask:0xf bank_mask:0xc
	v_mov_b32_dpp v229, v233 row_ror:8 row_mask:0xf bank_mask:0xc
	v_mov_b32_dpp v230, v234 row_ror:8 row_mask:0xf bank_mask:0xc
	v_mov_b32_dpp v231, v235 row_ror:8 row_mask:0xf bank_mask:0xc
	v_mov_b32_dpp v232, v236 row_ror:8 row_mask:0xf bank_mask:0x3
	v_mov_b32_dpp v233, v237 row_ror:8 row_mask:0xf bank_mask:0x3
	v_mov_b32_dpp v234, v238 row_ror:8 row_mask:0xf bank_mask:0x3
	v_mov_b32_dpp v235, v239 row_ror:8 row_mask:0xf bank_mask:0x3
	s_add_u32 s100, s100, 0x120000
	s_addc_u32 s101, s101, 0
	global_store_dwordx4 v240, v[228:231], s[100:101]
	s_add_u32 s100, s100, 0x20000
	s_addc_u32 s101, s101, 0
	global_store_dwordx4 v240, v[232:235], s[100:101]
	v_cvt_pk_bf16_f32 v228, v52, v53
	v_cvt_pk_bf16_f32 v229, v54, v55
	v_cvt_pk_bf16_f32 v230, v48, v49
	v_cvt_pk_bf16_f32 v231, v50, v51
	v_cvt_pk_bf16_f32 v232, v28, v29
	v_cvt_pk_bf16_f32 v233, v30, v31
	v_cvt_pk_bf16_f32 v234, v24, v25
	v_cvt_pk_bf16_f32 v235, v26, v27
	v_mov_b32_e32 v236, v228
	v_mov_b32_e32 v237, v229
	v_mov_b32_e32 v238, v230
	v_mov_b32_e32 v239, v231
	v_mov_b32_dpp v228, v232 row_ror:8 row_mask:0xf bank_mask:0xc
	v_mov_b32_dpp v229, v233 row_ror:8 row_mask:0xf bank_mask:0xc
	v_mov_b32_dpp v230, v234 row_ror:8 row_mask:0xf bank_mask:0xc
	v_mov_b32_dpp v231, v235 row_ror:8 row_mask:0xf bank_mask:0xc
	v_mov_b32_dpp v232, v236 row_ror:8 row_mask:0xf bank_mask:0x3
	v_mov_b32_dpp v233, v237 row_ror:8 row_mask:0xf bank_mask:0x3
	v_mov_b32_dpp v234, v238 row_ror:8 row_mask:0xf bank_mask:0x3
	v_mov_b32_dpp v235, v239 row_ror:8 row_mask:0xf bank_mask:0x3
	s_add_u32 s100, s100, 0x20000
	s_addc_u32 s101, s101, 0
	global_store_dwordx4 v240, v[228:231], s[100:101]
	s_add_u32 s100, s100, 0x20000
	s_addc_u32 s101, s101, 0
	global_store_dwordx4 v240, v[232:235], s[100:101]
	v_cvt_pk_bf16_f32 v228, v36, v37
	v_cvt_pk_bf16_f32 v229, v38, v39
	v_cvt_pk_bf16_f32 v230, v32, v33
	v_cvt_pk_bf16_f32 v231, v34, v35
	v_cvt_pk_bf16_f32 v232, v12, v13
	v_cvt_pk_bf16_f32 v233, v14, v15
	v_cvt_pk_bf16_f32 v234, v8, v9
	v_cvt_pk_bf16_f32 v235, v10, v11
	v_mov_b32_e32 v236, v228
	v_mov_b32_e32 v237, v229
	v_mov_b32_e32 v238, v230
	v_mov_b32_e32 v239, v231
	v_mov_b32_dpp v228, v232 row_ror:8 row_mask:0xf bank_mask:0xc
	v_mov_b32_dpp v229, v233 row_ror:8 row_mask:0xf bank_mask:0xc
	v_mov_b32_dpp v230, v234 row_ror:8 row_mask:0xf bank_mask:0xc
	v_mov_b32_dpp v231, v235 row_ror:8 row_mask:0xf bank_mask:0xc
	v_mov_b32_dpp v232, v236 row_ror:8 row_mask:0xf bank_mask:0x3
	v_mov_b32_dpp v233, v237 row_ror:8 row_mask:0xf bank_mask:0x3
	v_mov_b32_dpp v234, v238 row_ror:8 row_mask:0xf bank_mask:0x3
	v_mov_b32_dpp v235, v239 row_ror:8 row_mask:0xf bank_mask:0x3
	s_add_u32 s100, s100, 0x20000
	s_addc_u32 s101, s101, 0
	global_store_dwordx4 v240, v[228:231], s[100:101]
	s_add_u32 s100, s100, 0x20000
	s_addc_u32 s101, s101, 0
	global_store_dwordx4 v240, v[232:235], s[100:101]
	v_cvt_pk_bf16_f32 v228, v20, v21
	v_cvt_pk_bf16_f32 v229, v22, v23
	v_cvt_pk_bf16_f32 v230, v16, v17
	v_cvt_pk_bf16_f32 v231, v18, v19
	v_cvt_pk_bf16_f32 v232, v4, v5
	v_cvt_pk_bf16_f32 v233, v6, v7
	v_cvt_pk_bf16_f32 v234, v0, v1
	v_cvt_pk_bf16_f32 v235, v2, v3
	v_mov_b32_e32 v236, v228
	v_mov_b32_e32 v237, v229
	v_mov_b32_e32 v238, v230
	v_mov_b32_e32 v239, v231
	v_mov_b32_dpp v228, v232 row_ror:8 row_mask:0xf bank_mask:0xc
	v_mov_b32_dpp v229, v233 row_ror:8 row_mask:0xf bank_mask:0xc
	v_mov_b32_dpp v230, v234 row_ror:8 row_mask:0xf bank_mask:0xc
	v_mov_b32_dpp v231, v235 row_ror:8 row_mask:0xf bank_mask:0xc
	v_mov_b32_dpp v232, v236 row_ror:8 row_mask:0xf bank_mask:0x3
	v_mov_b32_dpp v233, v237 row_ror:8 row_mask:0xf bank_mask:0x3
	v_mov_b32_dpp v234, v238 row_ror:8 row_mask:0xf bank_mask:0x3
	v_mov_b32_dpp v235, v239 row_ror:8 row_mask:0xf bank_mask:0x3
	s_add_u32 s100, s100, 0x20000
	s_addc_u32 s101, s101, 0
	global_store_dwordx4 v240, v[228:231], s[100:101]
	s_add_u32 s100, s100, 0x20000
	s_addc_u32 s101, s101, 0
	global_store_dwordx4 v240, v[232:235], s[100:101]
	s_branch .Lfl8_done
.Lfl8_z:
	s_add_u32 s100, s58, 0x20100000
	s_addc_u32 s101, s59, 0
	v_and_b32_e32 v240, 7, v242
	v_lshl_add_u32 v240, v245, 6, v240
	v_lshl_add_u32 v240, s16, 8, v240
	v_lshlrev_b32_e32 v240, 13, v240
	v_lshrrev_b32_e32 v241, 3, v242
	v_lshlrev_b32_e32 v241, 6, v241
	v_lshl_add_u32 v241, v244, 7, v241
	v_lshl_add_u32 v241, v243, 4, v241
	v_add_u32_e32 v240, v240, v241
	s_add_i32 s98, s41, -32
	s_lshl_b32 s98, s98, 9
	v_add_u32_e32 v240, s98, v240
	v_cvt_pk_bf16_f32 v228, v124, v125
	v_cvt_pk_bf16_f32 v229, v126, v127
	v_cvt_pk_bf16_f32 v230, v120, v121
	v_cvt_pk_bf16_f32 v231, v122, v123
	v_cvt_pk_bf16_f32 v232, v108, v109
	v_cvt_pk_bf16_f32 v233, v110, v111
	v_cvt_pk_bf16_f32 v234, v104, v105
	v_cvt_pk_bf16_f32 v235, v106, v107
	v_mov_b32_e32 v236, v228
	v_mov_b32_e32 v237, v229
	v_mov_b32_e32 v238, v230
	v_mov_b32_e32 v239, v231
	v_mov_b32_dpp v228, v232 row_ror:8 row_mask:0xf bank_mask:0xc
	v_mov_b32_dpp v229, v233 row_ror:8 row_mask:0xf bank_mask:0xc
	v_mov_b32_dpp v230, v234 row_ror:8 row_mask:0xf bank_mask:0xc
	v_mov_b32_dpp v231, v235 row_ror:8 row_mask:0xf bank_mask:0xc
	v_mov_b32_dpp v232, v236 row_ror:8 row_mask:0xf bank_mask:0x3
	v_mov_b32_dpp v233, v237 row_ror:8 row_mask:0xf bank_mask:0x3
	v_mov_b32_dpp v234, v238 row_ror:8 row_mask:0xf bank_mask:0x3
	v_mov_b32_dpp v235, v239 row_ror:8 row_mask:0xf bank_mask:0x3
	global_store_dwordx4 v240, v[228:231], s[100:101]
	s_add_u32 s100, s100, 0x10000
	s_addc_u32 s101, s101, 0
	global_store_dwordx4 v240, v[232:235], s[100:101]
	v_cvt_pk_bf16_f32 v228, v116, v117
	v_cvt_pk_bf16_f32 v229, v118, v119
	v_cvt_pk_bf16_f32 v230, v112, v113
	v_cvt_pk_bf16_f32 v231, v114, v115
	v_cvt_pk_bf16_f32 v232, v92, v93
	v_cvt_pk_bf16_f32 v233, v94, v95
	v_cvt_pk_bf16_f32 v234, v88, v89
	v_cvt_pk_bf16_f32 v235, v90, v91
	v_mov_b32_e32 v236, v228
	v_mov_b32_e32 v237, v229
	v_mov_b32_e32 v238, v230
	v_mov_b32_e32 v239, v231
	v_mov_b32_dpp v228, v232 row_ror:8 row_mask:0xf bank_mask:0xc
	v_mov_b32_dpp v229, v233 row_ror:8 row_mask:0xf bank_mask:0xc
	v_mov_b32_dpp v230, v234 row_ror:8 row_mask:0xf bank_mask:0xc
	v_mov_b32_dpp v231, v235 row_ror:8 row_mask:0xf bank_mask:0xc
	v_mov_b32_dpp v232, v236 row_ror:8 row_mask:0xf bank_mask:0x3
	v_mov_b32_dpp v233, v237 row_ror:8 row_mask:0xf bank_mask:0x3
	v_mov_b32_dpp v234, v238 row_ror:8 row_mask:0xf bank_mask:0x3
	v_mov_b32_dpp v235, v239 row_ror:8 row_mask:0xf bank_mask:0x3
	s_add_u32 s100, s100, 0x10000
	s_addc_u32 s101, s101, 0
	global_store_dwordx4 v240, v[228:231], s[100:101]
	s_add_u32 s100, s100, 0x10000
	s_addc_u32 s101, s101, 0
	global_store_dwordx4 v240, v[232:235], s[100:101]
	v_cvt_pk_bf16_f32 v228, v100, v101
	v_cvt_pk_bf16_f32 v229, v102, v103
	v_cvt_pk_bf16_f32 v230, v96, v97
	v_cvt_pk_bf16_f32 v231, v98, v99
	v_cvt_pk_bf16_f32 v232, v76, v77
	v_cvt_pk_bf16_f32 v233, v78, v79
	v_cvt_pk_bf16_f32 v234, v72, v73
	v_cvt_pk_bf16_f32 v235, v74, v75
	v_mov_b32_e32 v236, v228
	v_mov_b32_e32 v237, v229
	v_mov_b32_e32 v238, v230
	v_mov_b32_e32 v239, v231
	v_mov_b32_dpp v228, v232 row_ror:8 row_mask:0xf bank_mask:0xc
	v_mov_b32_dpp v229, v233 row_ror:8 row_mask:0xf bank_mask:0xc
	v_mov_b32_dpp v230, v234 row_ror:8 row_mask:0xf bank_mask:0xc
	v_mov_b32_dpp v231, v235 row_ror:8 row_mask:0xf bank_mask:0xc
	v_mov_b32_dpp v232, v236 row_ror:8 row_mask:0xf bank_mask:0x3
	v_mov_b32_dpp v233, v237 row_ror:8 row_mask:0xf bank_mask:0x3
	v_mov_b32_dpp v234, v238 row_ror:8 row_mask:0xf bank_mask:0x3
	v_mov_b32_dpp v235, v239 row_ror:8 row_mask:0xf bank_mask:0x3
	s_add_u32 s100, s100, 0x10000
	s_addc_u32 s101, s101, 0
	global_store_dwordx4 v240, v[228:231], s[100:101]
	s_add_u32 s100, s100, 0x10000
	s_addc_u32 s101, s101, 0
	global_store_dwordx4 v240, v[232:235], s[100:101]
	v_cvt_pk_bf16_f32 v228, v84, v85
	v_cvt_pk_bf16_f32 v229, v86, v87
	v_cvt_pk_bf16_f32 v230, v80, v81
	v_cvt_pk_bf16_f32 v231, v82, v83
	v_cvt_pk_bf16_f32 v232, v68, v69
	v_cvt_pk_bf16_f32 v233, v70, v71
	v_cvt_pk_bf16_f32 v234, v64, v65
	v_cvt_pk_bf16_f32 v235, v66, v67
	v_mov_b32_e32 v236, v228
	v_mov_b32_e32 v237, v229
	v_mov_b32_e32 v238, v230
	v_mov_b32_e32 v239, v231
	v_mov_b32_dpp v228, v232 row_ror:8 row_mask:0xf bank_mask:0xc
	v_mov_b32_dpp v229, v233 row_ror:8 row_mask:0xf bank_mask:0xc
	v_mov_b32_dpp v230, v234 row_ror:8 row_mask:0xf bank_mask:0xc
	v_mov_b32_dpp v231, v235 row_ror:8 row_mask:0xf bank_mask:0xc
	v_mov_b32_dpp v232, v236 row_ror:8 row_mask:0xf bank_mask:0x3
	v_mov_b32_dpp v233, v237 row_ror:8 row_mask:0xf bank_mask:0x3
	v_mov_b32_dpp v234, v238 row_ror:8 row_mask:0xf bank_mask:0x3
	v_mov_b32_dpp v235, v239 row_ror:8 row_mask:0xf bank_mask:0x3
	s_add_u32 s100, s100, 0x10000
	s_addc_u32 s101, s101, 0
	global_store_dwordx4 v240, v[228:231], s[100:101]
	s_add_u32 s100, s100, 0x10000
	s_addc_u32 s101, s101, 0
	global_store_dwordx4 v240, v[232:235], s[100:101]
	v_cvt_pk_bf16_f32 v228, v60, v61
	v_cvt_pk_bf16_f32 v229, v62, v63
	v_cvt_pk_bf16_f32 v230, v56, v57
	v_cvt_pk_bf16_f32 v231, v58, v59
	v_cvt_pk_bf16_f32 v232, v44, v45
	v_cvt_pk_bf16_f32 v233, v46, v47
	v_cvt_pk_bf16_f32 v234, v40, v41
	v_cvt_pk_bf16_f32 v235, v42, v43
	v_mov_b32_e32 v236, v228
	v_mov_b32_e32 v237, v229
	v_mov_b32_e32 v238, v230
	v_mov_b32_e32 v239, v231
	v_mov_b32_dpp v228, v232 row_ror:8 row_mask:0xf bank_mask:0xc
	v_mov_b32_dpp v229, v233 row_ror:8 row_mask:0xf bank_mask:0xc
	v_mov_b32_dpp v230, v234 row_ror:8 row_mask:0xf bank_mask:0xc
	v_mov_b32_dpp v231, v235 row_ror:8 row_mask:0xf bank_mask:0xc
	v_mov_b32_dpp v232, v236 row_ror:8 row_mask:0xf bank_mask:0x3
	v_mov_b32_dpp v233, v237 row_ror:8 row_mask:0xf bank_mask:0x3
	v_mov_b32_dpp v234, v238 row_ror:8 row_mask:0xf bank_mask:0x3
	v_mov_b32_dpp v235, v239 row_ror:8 row_mask:0xf bank_mask:0x3
	s_add_u32 s100, s100, 0x90000
	s_addc_u32 s101, s101, 0
	global_store_dwordx4 v240, v[228:231], s[100:101]
	s_add_u32 s100, s100, 0x10000
	s_addc_u32 s101, s101, 0
	global_store_dwordx4 v240, v[232:235], s[100:101]
	v_cvt_pk_bf16_f32 v228, v52, v53
	v_cvt_pk_bf16_f32 v229, v54, v55
	v_cvt_pk_bf16_f32 v230, v48, v49
	v_cvt_pk_bf16_f32 v231, v50, v51
	v_cvt_pk_bf16_f32 v232, v28, v29
	v_cvt_pk_bf16_f32 v233, v30, v31
	v_cvt_pk_bf16_f32 v234, v24, v25
	v_cvt_pk_bf16_f32 v235, v26, v27
	v_mov_b32_e32 v236, v228
	v_mov_b32_e32 v237, v229
	v_mov_b32_e32 v238, v230
	v_mov_b32_e32 v239, v231
	v_mov_b32_dpp v228, v232 row_ror:8 row_mask:0xf bank_mask:0xc
	v_mov_b32_dpp v229, v233 row_ror:8 row_mask:0xf bank_mask:0xc
	v_mov_b32_dpp v230, v234 row_ror:8 row_mask:0xf bank_mask:0xc
	v_mov_b32_dpp v231, v235 row_ror:8 row_mask:0xf bank_mask:0xc
	v_mov_b32_dpp v232, v236 row_ror:8 row_mask:0xf bank_mask:0x3
	v_mov_b32_dpp v233, v237 row_ror:8 row_mask:0xf bank_mask:0x3
	v_mov_b32_dpp v234, v238 row_ror:8 row_mask:0xf bank_mask:0x3
	v_mov_b32_dpp v235, v239 row_ror:8 row_mask:0xf bank_mask:0x3
	s_add_u32 s100, s100, 0x10000
	s_addc_u32 s101, s101, 0
	global_store_dwordx4 v240, v[228:231], s[100:101]
	s_add_u32 s100, s100, 0x10000
	s_addc_u32 s101, s101, 0
	global_store_dwordx4 v240, v[232:235], s[100:101]
	v_cvt_pk_bf16_f32 v228, v36, v37
	v_cvt_pk_bf16_f32 v229, v38, v39
	v_cvt_pk_bf16_f32 v230, v32, v33
	v_cvt_pk_bf16_f32 v231, v34, v35
	v_cvt_pk_bf16_f32 v232, v12, v13
	v_cvt_pk_bf16_f32 v233, v14, v15
	v_cvt_pk_bf16_f32 v234, v8, v9
	v_cvt_pk_bf16_f32 v235, v10, v11
	v_mov_b32_e32 v236, v228
	v_mov_b32_e32 v237, v229
	v_mov_b32_e32 v238, v230
	v_mov_b32_e32 v239, v231
	v_mov_b32_dpp v228, v232 row_ror:8 row_mask:0xf bank_mask:0xc
	v_mov_b32_dpp v229, v233 row_ror:8 row_mask:0xf bank_mask:0xc
	v_mov_b32_dpp v230, v234 row_ror:8 row_mask:0xf bank_mask:0xc
	v_mov_b32_dpp v231, v235 row_ror:8 row_mask:0xf bank_mask:0xc
	v_mov_b32_dpp v232, v236 row_ror:8 row_mask:0xf bank_mask:0x3
	v_mov_b32_dpp v233, v237 row_ror:8 row_mask:0xf bank_mask:0x3
	v_mov_b32_dpp v234, v238 row_ror:8 row_mask:0xf bank_mask:0x3
	v_mov_b32_dpp v235, v239 row_ror:8 row_mask:0xf bank_mask:0x3
	s_add_u32 s100, s100, 0x10000
	s_addc_u32 s101, s101, 0
	global_store_dwordx4 v240, v[228:231], s[100:101]
	s_add_u32 s100, s100, 0x10000
	s_addc_u32 s101, s101, 0
	global_store_dwordx4 v240, v[232:235], s[100:101]
	v_cvt_pk_bf16_f32 v228, v20, v21
	v_cvt_pk_bf16_f32 v229, v22, v23
	v_cvt_pk_bf16_f32 v230, v16, v17
	v_cvt_pk_bf16_f32 v231, v18, v19
	v_cvt_pk_bf16_f32 v232, v4, v5
	v_cvt_pk_bf16_f32 v233, v6, v7
	v_cvt_pk_bf16_f32 v234, v0, v1
	v_cvt_pk_bf16_f32 v235, v2, v3
	v_mov_b32_e32 v236, v228
	v_mov_b32_e32 v237, v229
	v_mov_b32_e32 v238, v230
	v_mov_b32_e32 v239, v231
	v_mov_b32_dpp v228, v232 row_ror:8 row_mask:0xf bank_mask:0xc
	v_mov_b32_dpp v229, v233 row_ror:8 row_mask:0xf bank_mask:0xc
	v_mov_b32_dpp v230, v234 row_ror:8 row_mask:0xf bank_mask:0xc
	v_mov_b32_dpp v231, v235 row_ror:8 row_mask:0xf bank_mask:0xc
	v_mov_b32_dpp v232, v236 row_ror:8 row_mask:0xf bank_mask:0x3
	v_mov_b32_dpp v233, v237 row_ror:8 row_mask:0xf bank_mask:0x3
	v_mov_b32_dpp v234, v238 row_ror:8 row_mask:0xf bank_mask:0x3
	v_mov_b32_dpp v235, v239 row_ror:8 row_mask:0xf bank_mask:0x3
	s_add_u32 s100, s100, 0x10000
	s_addc_u32 s101, s101, 0
	global_store_dwordx4 v240, v[228:231], s[100:101]
	s_add_u32 s100, s100, 0x10000
	s_addc_u32 s101, s101, 0
	global_store_dwordx4 v240, v[232:235], s[100:101]
	s_branch .Lfl8_done
.Lfl8_ba:
	v_readfirstlane_b32 s98, v244
	s_nop 3
	s_cmp_lg_u32 s98, 0
	s_cbranch_scc1 .Lfl8_done
	s_add_u32 s100, s58, 0x24900000
	s_addc_u32 s101, s59, 0
	v_lshl_add_u32 v240, v245, 6, v242
	v_lshl_add_u32 v240, s16, 8, v240
	v_lshlrev_b32_e32 v240, 8, v240
	v_lshl_add_u32 v240, v243, 5, v240
	global_store_dwordx4 v240, v[124:127], s[100:101] offset:0
	global_store_dwordx4 v240, v[120:123], s[100:101] offset:16
	global_store_dwordx4 v240, v[108:111], s[100:101] offset:128
	global_store_dwordx4 v240, v[104:107], s[100:101] offset:144
	s_add_u32 s100, s100, 0x1000
	s_addc_u32 s101, s101, 0
	global_store_dwordx4 v240, v[116:119], s[100:101] offset:0
	global_store_dwordx4 v240, v[112:115], s[100:101] offset:16
	global_store_dwordx4 v240, v[92:95], s[100:101] offset:128
	global_store_dwordx4 v240, v[88:91], s[100:101] offset:144
	s_add_u32 s100, s100, 0x1000
	s_addc_u32 s101, s101, 0
	global_store_dwordx4 v240, v[100:103], s[100:101] offset:0
	global_store_dwordx4 v240, v[96:99], s[100:101] offset:16
	global_store_dwordx4 v240, v[76:79], s[100:101] offset:128
	global_store_dwordx4 v240, v[72:75], s[100:101] offset:144
	s_add_u32 s100, s100, 0x1000
	s_addc_u32 s101, s101, 0
	global_store_dwordx4 v240, v[84:87], s[100:101] offset:0
	global_store_dwordx4 v240, v[80:83], s[100:101] offset:16
	global_store_dwordx4 v240, v[68:71], s[100:101] offset:128
	global_store_dwordx4 v240, v[64:67], s[100:101] offset:144
	s_add_u32 s100, s100, 0x5000
	s_addc_u32 s101, s101, 0
	global_store_dwordx4 v240, v[60:63], s[100:101] offset:0
	global_store_dwordx4 v240, v[56:59], s[100:101] offset:16
	global_store_dwordx4 v240, v[44:47], s[100:101] offset:128
	global_store_dwordx4 v240, v[40:43], s[100:101] offset:144
	s_add_u32 s100, s100, 0x1000
	s_addc_u32 s101, s101, 0
	global_store_dwordx4 v240, v[52:55], s[100:101] offset:0
	global_store_dwordx4 v240, v[48:51], s[100:101] offset:16
	global_store_dwordx4 v240, v[28:31], s[100:101] offset:128
	global_store_dwordx4 v240, v[24:27], s[100:101] offset:144
	s_add_u32 s100, s100, 0x1000
	s_addc_u32 s101, s101, 0
	global_store_dwordx4 v240, v[36:39], s[100:101] offset:0
	global_store_dwordx4 v240, v[32:35], s[100:101] offset:16
	global_store_dwordx4 v240, v[12:15], s[100:101] offset:128
	global_store_dwordx4 v240, v[8:11], s[100:101] offset:144
	s_add_u32 s100, s100, 0x1000
	s_addc_u32 s101, s101, 0
	global_store_dwordx4 v240, v[20:23], s[100:101] offset:0
	global_store_dwordx4 v240, v[16:19], s[100:101] offset:16
	global_store_dwordx4 v240, v[4:7], s[100:101] offset:128
	global_store_dwordx4 v240, v[0:3], s[100:101] offset:144
.Lfl8_done:
	s_branch .LBB0_796

.LBB0_1557:
	s_or_b64 exec, exec, s[0:1]
	v_readlane_b32 s0, v247, 14
	v_mov_b32_e32 v8, v202
	v_readlane_b32 s1, v247, 15
	s_waitcnt lgkmcnt(0)
	s_barrier
	s_and_b64 vcc, exec, s[0:1]
	v_readfirstlane_b32 s28, v8
	s_cbranch_vccz .LBB0_1569
	v_lshlrev_b32_e32 v0, 4, v8
	s_add_u32 s29, s58, 0xa100000
	v_readlane_b32 s1, v247, 8
	v_add_u32_e32 v1, 0x2000, v0
	s_addc_u32 s30, s59, 0
	s_lshr_b32 s1, s1, 29
	v_readlane_b32 s4, v248, 45
	v_ashrrev_i32_e32 v2, 31, v1
	s_add_i32 s1, s4, s1
	v_lshrrev_b32_e32 v2, 22, v2
	s_ashr_i32 s0, s28, 6
	s_and_b32 s2, s1, -8
	v_add_u32_e32 v2, v1, v2
	s_ashr_i32 s3, s28, 8
	s_lshl_b32 s31, s0, 10
	s_sub_i32 s2, s4, s2
	v_ashrrev_i32_e32 v9, 10, v2
	s_cmp_lt_i32 s2, 0
	s_movk_i32 s34, 0x91
	v_mul_i32_i24_e32 v2, 0x400, v9
	s_cselect_b32 s4, s34, 0x90
	v_sub_u32_e32 v1, v1, v2
	s_mul_i32 s2, s4, s2
	s_ashr_i32 s1, s1, 3
	v_lshrrev_b32_e32 v2, 4, v1
	s_add_i32 s1, s2, s1
	v_bitop3_b32 v1, v2, v1, 32 bitop3:0x6c
	s_ashr_i32 s2, s1, 31
	v_ashrrev_i32_e32 v2, 31, v1
	s_lshr_b32 s2, s2, 24
	v_lshrrev_b32_e32 v2, 26, v2
	s_add_i32 s2, s1, s2
	v_add_u32_e32 v2, v1, v2
	v_lshlrev_b32_e32 v3, 3, v9
	s_ashr_i32 s2, s2, 8
	v_ashrrev_i32_e32 v10, 6, v2
	v_and_b32_e32 v3, -16, v3
	s_lshl_b32 s6, s2, 3
	s_lshl_b32 s2, s2, 8
	v_add_u32_e32 v3, v10, v3
	s_sub_i32 s1, s1, s2
	v_and_b32_e32 v4, 3, v10
	s_mov_b32 s2, 0xfffe0
	v_lshrrev_b32_e32 v5, 2, v3
	v_lshlrev_b32_e32 v6, 1, v3
	v_and_b32_e32 v2, 0xc0, v2
	v_and_or_b32 v4, v3, s2, v4
	v_and_b32_e32 v5, 4, v5
	v_and_b32_e32 v6, 24, v6
	v_sub_u32_e32 v1, v1, v2
	v_mov_b32_e32 v2, 1
	v_or3_b32 v4, v4, v5, v6
	v_lshlrev_b32_e32 v5, 5, v9
	v_ashrrev_i16_sdwa v1, v2, sext(v1) dst_sel:DWORD dst_unused:UNUSED_PAD src0_sel:DWORD src1_sel:BYTE_0
	v_and_b32_e32 v5, 32, v5
	v_bfe_i32 v11, v1, 0, 16
	v_add_lshl_u32 v1, v5, v11, 1
	v_lshl_add_u32 v128, v4, 12, v1
	v_lshl_add_u32 v130, v3, 12, v1
	v_bfe_i32 v1, v8, 27, 1
	v_lshrrev_b32_e32 v1, 22, v1
	v_add_u32_e32 v1, v0, v1
	v_and_b32_e32 v1, 0xfffffc00, v1
	v_sub_u32_e32 v0, v0, v1
	v_lshrrev_b32_e32 v1, 4, v0
	v_ashrrev_i32_e32 v3, 31, v8
	v_bitop3_b32 v0, v1, v0, 32 bitop3:0x6c
	v_lshrrev_b32_e32 v3, 26, v3
	v_ashrrev_i32_e32 v1, 31, v0
	v_add_u32_e32 v3, v8, v3
	v_lshrrev_b32_e32 v1, 26, v1
	v_ashrrev_i32_e32 v13, 6, v3
	v_add_u32_e32 v1, v0, v1
	v_lshlrev_b32_e32 v3, 3, v13
	v_ashrrev_i32_e32 v12, 6, v1
	v_and_b32_e32 v3, -16, v3
	v_add_u32_e32 v3, v12, v3
	v_and_b32_e32 v4, 3, v12
	v_lshrrev_b32_e32 v5, 2, v3
	v_lshlrev_b32_e32 v6, 1, v3
	v_and_b32_e32 v1, 0xc0, v1
	v_and_or_b32 v4, v3, s2, v4
	v_and_b32_e32 v5, 4, v5
	v_and_b32_e32 v6, 24, v6
	v_sub_u32_e32 v0, v0, v1
	s_sub_i32 s4, 36, s6
	v_or3_b32 v4, v4, v5, v6
	v_lshlrev_b32_e32 v5, 5, v13
	v_ashrrev_i16_sdwa v0, v2, sext(v0) dst_sel:DWORD dst_unused:UNUSED_PAD src0_sel:DWORD src1_sel:BYTE_0
	s_min_u32 s7, s4, 8
	v_and_b32_e32 v5, 32, v5
	v_bfe_i32 v14, v0, 0, 16
	v_add_lshl_u32 v0, v5, v14, 1
	s_sext_i32_i16 s2, s1
	v_cvt_f32_ubyte0_e32 v2, s7
	v_lshl_add_u32 v132, v4, 12, v0
	v_cvt_f32_i32_e32 v1, s2
	v_rcp_iflag_f32_e32 v4, v2
	v_lshl_add_u32 v134, v3, 12, v0
	s_ashr_i32 s2, s2, 30
	s_or_b32 s2, s2, 1
	v_mul_f32_e32 v0, v1, v4
	v_trunc_f32_e32 v0, v0
	v_fma_f32 v1, -v0, v2, v1
	v_cvt_i32_f32_e32 v0, v0
	v_cmp_ge_f32_e64 s[4:5], |v1|, v2
	s_and_b64 s[4:5], s[4:5], exec
	s_cselect_b32 s2, s2, 0
	v_readfirstlane_b32 s4, v0
	s_add_i32 s2, s4, s2
	s_mul_i32 s4, s2, s7
	s_sub_i32 s1, s1, s4
	s_sext_i32_i16 s1, s1
	s_add_i32 s20, s6, s1
	s_ashr_i32 s21, s20, 31
	s_bfe_i64 s[6:7], s[2:3], 0x100000
	s_lshl_b64 s[4:5], s[20:21], 20
	s_lshl_b64 s[6:7], s[6:7], 20
	s_add_u32 s24, s29, s6
	s_addc_u32 s25, s30, s7
	s_add_i32 s21, s31, 0
	s_add_i32 m0, s21, 0x10000
	v_readlane_b32 s6, v247, 9
	v_mov_b32_e32 v230, s3
	v_lshlrev_b32_e32 v230, 17, v230
	v_add_u32_e32 v132, v132, v230
	v_add_u32_e32 v230, 0x40000, v230
	v_add_u32_e32 v128, v128, v230
	global_load_lds_dwordx4 v132, s[24:25]
	s_add_i32 m0, s21, 0x12000
	v_readlane_b32 s7, v247, 10
	s_add_u32 s22, s6, s4
	global_load_lds_dwordx4 v128, s[24:25]
	s_addc_u32 s23, s7, s5
	s_mov_b32 m0, s21
	s_add_i32 s35, s21, 0x2000
	global_load_lds_dwordx4 v134, s[22:23]
	s_mov_b32 m0, s35
	s_add_u32 s4, s24, 0x20000
	global_load_lds_dwordx4 v130, s[22:23]
	s_addc_u32 s5, s25, 0
	s_add_i32 m0, s21, 0x14000
	v_mov_b32_e32 v133, 0
	global_load_lds_dwordx4 v132, s[4:5]
	s_add_i32 m0, s21, 0x16000
	v_mov_b32_e32 v129, v133
	global_load_lds_dwordx4 v128, s[4:5]
	s_add_u32 s4, s22, 0x80000
	s_addc_u32 s5, s23, 0
	s_add_i32 s36, s21, 0x4000
	s_mov_b32 m0, s36
	s_add_i32 s37, s21, 0x6000
	global_load_lds_dwordx4 v134, s[4:5]
	s_mov_b32 m0, s37
	v_mov_b32_e32 v135, v133
	global_load_lds_dwordx4 v130, s[4:5]
	v_mov_b32_e32 v131, v133
	s_mov_b32 s38, 0
	v_lshl_add_u64 v[6:7], s[24:25], 0, v[132:133]
	v_lshl_add_u64 v[4:5], s[24:25], 0, v[128:129]
	v_lshl_add_u64 v[2:3], s[22:23], 0, v[134:135]
	s_cmp_lg_u32 s3, 1
	v_lshl_add_u64 v[0:1], s[22:23], 0, v[130:131]
	s_cbranch_scc1 .LBB0_1560
	s_barrier

.LBB0_1564:
	ds_read_b128 v[152:155], v149
	ds_read_b128 v[156:159], v149 offset:1024
	ds_read_b128 v[160:163], v149 offset:2048
	ds_read_b128 v[164:167], v149 offset:3072
	s_add_u32 s24, s22, 0xfff80080
	s_addc_u32 s25, s23, -1
	s_cmp_eq_u32 s52, 28
	s_cselect_b32 s27, s15, s25
	s_cselect_b32 s26, s48, s24
	s_cselect_b32 s25, s13, s51
	s_cselect_b32 s24, s49, s50
	v_lshl_add_u64 v[144:145], s[22:23], 0, v[136:137]
	s_add_i32 m0, s21, 0xc000
	ds_read_b128 v[168:171], v150
	ds_read_b128 v[172:175], v150 offset:1024
	ds_read_b128 v[176:179], v150 offset:2048
	ds_read_b128 v[180:183], v150 offset:3072
	ds_read_b128 v[184:187], v150 offset:4096
	ds_read_b128 v[188:191], v150 offset:5120
	ds_read_b128 v[192:195], v150 offset:6144
	ds_read_b128 v[196:199], v150 offset:7168
	global_load_lds_dwordx4 v[144:145], off
	v_lshl_add_u64 v[144:145], s[22:23], 0, v[138:139]
	s_add_i32 m0, s21, 0xe000
	s_nop 0
	global_load_lds_dwordx4 v[144:145], off
	s_waitcnt lgkmcnt(8)
	s_barrier
	s_waitcnt lgkmcnt(0)
	s_setprio 1
	s_waitcnt lgkmcnt(0)
	v_mfma_f32_16x16x32_bf16 v[124:127], v[152:155], v[168:171], v[124:127]
	v_mfma_f32_16x16x32_bf16 v[120:123], v[160:163], v[168:171], v[120:123]
	v_mfma_f32_16x16x32_bf16 v[108:111], v[152:155], v[176:179], v[108:111]
	v_mfma_f32_16x16x32_bf16 v[104:107], v[160:163], v[176:179], v[104:107]
	v_mfma_f32_16x16x32_bf16 v[92:95], v[152:155], v[184:187], v[92:95]
	v_mfma_f32_16x16x32_bf16 v[88:91], v[160:163], v[184:187], v[88:91]
	v_mfma_f32_16x16x32_bf16 v[76:79], v[152:155], v[192:195], v[76:79]
	v_mfma_f32_16x16x32_bf16 v[72:75], v[160:163], v[192:195], v[72:75]
	v_mfma_f32_16x16x32_bf16 v[124:127], v[156:159], v[172:175], v[124:127]
	v_mfma_f32_16x16x32_bf16 v[120:123], v[164:167], v[172:175], v[120:123]
	v_mfma_f32_16x16x32_bf16 v[108:111], v[156:159], v[180:183], v[108:111]
	v_mfma_f32_16x16x32_bf16 v[104:107], v[164:167], v[180:183], v[104:107]
	v_mfma_f32_16x16x32_bf16 v[92:95], v[156:159], v[188:191], v[92:95]
	v_mfma_f32_16x16x32_bf16 v[88:91], v[164:167], v[188:191], v[88:91]
	v_mfma_f32_16x16x32_bf16 v[76:79], v[156:159], v[196:199], v[76:79]
	v_mfma_f32_16x16x32_bf16 v[72:75], v[164:167], v[196:199], v[72:75]
	s_setprio 0
	s_barrier
	s_add_i32 s53, s41, s31
	v_lshl_add_u64 v[144:145], s[24:25], 0, v[132:133]
	s_mov_b32 m0, s53
	ds_read_b128 v[204:207], v151
	ds_read_b128 v[208:211], v151 offset:1024
	ds_read_b128 v[212:215], v151 offset:2048
	ds_read_b128 v[216:219], v151 offset:3072
	global_load_lds_dwordx4 v[144:145], off
	v_lshl_add_u64 v[200:201], s[24:25], 0, v[128:129]
	s_add_i32 m0, s53, 0x2000
	s_nop 0
	global_load_lds_dwordx4 v[200:201], off
	s_barrier
	s_waitcnt lgkmcnt(0)
	s_setprio 1
	s_waitcnt lgkmcnt(0)
	v_mfma_f32_16x16x32_bf16 v[116:119], v[204:207], v[168:171], v[116:119]
	v_mfma_f32_16x16x32_bf16 v[112:115], v[212:215], v[168:171], v[112:115]
	v_mfma_f32_16x16x32_bf16 v[100:103], v[204:207], v[176:179], v[100:103]
	v_mfma_f32_16x16x32_bf16 v[96:99], v[212:215], v[176:179], v[96:99]
	v_mfma_f32_16x16x32_bf16 v[84:87], v[204:207], v[184:187], v[84:87]
	v_mfma_f32_16x16x32_bf16 v[80:83], v[212:215], v[184:187], v[80:83]
	v_mfma_f32_16x16x32_bf16 v[68:71], v[204:207], v[192:195], v[68:71]
	v_mfma_f32_16x16x32_bf16 v[64:67], v[212:215], v[192:195], v[64:67]
	v_mfma_f32_16x16x32_bf16 v[116:119], v[208:211], v[172:175], v[116:119]
	v_mfma_f32_16x16x32_bf16 v[112:115], v[216:219], v[172:175], v[112:115]
	v_mfma_f32_16x16x32_bf16 v[100:103], v[208:211], v[180:183], v[100:103]
	v_mfma_f32_16x16x32_bf16 v[96:99], v[216:219], v[180:183], v[96:99]
	v_mfma_f32_16x16x32_bf16 v[84:87], v[208:211], v[188:191], v[84:87]
	v_mfma_f32_16x16x32_bf16 v[80:83], v[216:219], v[188:191], v[80:83]
	v_mfma_f32_16x16x32_bf16 v[68:71], v[208:211], v[196:199], v[68:71]
	v_mfma_f32_16x16x32_bf16 v[64:67], v[216:219], v[196:199], v[64:67]
	s_setprio 0
	s_mov_b32 m0, s21
	v_lshl_add_u64 v[220:221], s[26:27], 0, v[134:135]
	s_barrier
	ds_read_b128 v[168:171], v150 offset:16384
	ds_read_b128 v[172:175], v150 offset:17408
	ds_read_b128 v[176:179], v150 offset:18432
	ds_read_b128 v[180:183], v150 offset:19456
	ds_read_b128 v[184:187], v150 offset:20480
	ds_read_b128 v[188:191], v150 offset:21504
	ds_read_b128 v[192:195], v150 offset:22528
	ds_read_b128 v[196:199], v150 offset:23552
	global_load_lds_dwordx4 v[220:221], off
	v_lshl_add_u64 v[222:223], s[26:27], 0, v[130:131]
	s_mov_b32 m0, s35
	s_nop 0
	global_load_lds_dwordx4 v[222:223], off
	s_barrier
	s_waitcnt lgkmcnt(0)
	s_setprio 1
	s_waitcnt lgkmcnt(0)
	v_mfma_f32_16x16x32_bf16 v[60:63], v[152:155], v[168:171], v[60:63]
	v_mfma_f32_16x16x32_bf16 v[56:59], v[160:163], v[168:171], v[56:59]
	v_mfma_f32_16x16x32_bf16 v[44:47], v[152:155], v[176:179], v[44:47]
	v_mfma_f32_16x16x32_bf16 v[40:43], v[160:163], v[176:179], v[40:43]
	v_mfma_f32_16x16x32_bf16 v[28:31], v[152:155], v[184:187], v[28:31]
	v_mfma_f32_16x16x32_bf16 v[24:27], v[160:163], v[184:187], v[24:27]
	v_mfma_f32_16x16x32_bf16 v[12:15], v[152:155], v[192:195], v[12:15]
	v_mfma_f32_16x16x32_bf16 v[8:11], v[160:163], v[192:195], v[8:11]
	v_mfma_f32_16x16x32_bf16 v[60:63], v[156:159], v[172:175], v[60:63]
	v_mfma_f32_16x16x32_bf16 v[56:59], v[164:167], v[172:175], v[56:59]
	v_mfma_f32_16x16x32_bf16 v[44:47], v[156:159], v[180:183], v[44:47]
	v_mfma_f32_16x16x32_bf16 v[40:43], v[164:167], v[180:183], v[40:43]
	v_mfma_f32_16x16x32_bf16 v[28:31], v[156:159], v[188:191], v[28:31]
	v_mfma_f32_16x16x32_bf16 v[24:27], v[164:167], v[188:191], v[24:27]
	v_mfma_f32_16x16x32_bf16 v[12:15], v[156:159], v[196:199], v[12:15]
	v_mfma_f32_16x16x32_bf16 v[8:11], v[164:167], v[196:199], v[8:11]
	s_setprio 0
	s_barrier
	s_add_u32 s54, s24, 0x20000
	s_addc_u32 s55, s25, 0
	s_add_i32 s53, s42, s31
	v_lshl_add_u64 v[152:153], s[54:55], 0, v[132:133]
	s_mov_b32 m0, s53
	s_nop 0
	global_load_lds_dwordx4 v[152:153], off
	v_lshl_add_u64 v[152:153], s[54:55], 0, v[128:129]
	s_add_i32 m0, s53, 0x2000
	s_nop 0
	global_load_lds_dwordx4 v[152:153], off
	s_waitcnt vmcnt(6)
	s_barrier
	s_setprio 1
	v_mfma_f32_16x16x32_bf16 v[52:55], v[204:207], v[168:171], v[52:55]
	v_mfma_f32_16x16x32_bf16 v[48:51], v[212:215], v[168:171], v[48:51]
	v_mfma_f32_16x16x32_bf16 v[36:39], v[204:207], v[176:179], v[36:39]
	v_mfma_f32_16x16x32_bf16 v[32:35], v[212:215], v[176:179], v[32:35]
	v_mfma_f32_16x16x32_bf16 v[20:23], v[204:207], v[184:187], v[20:23]
	v_mfma_f32_16x16x32_bf16 v[16:19], v[212:215], v[184:187], v[16:19]
	v_mfma_f32_16x16x32_bf16 v[4:7], v[204:207], v[192:195], v[4:7]
	v_mfma_f32_16x16x32_bf16 v[0:3], v[212:215], v[192:195], v[0:3]
	v_mfma_f32_16x16x32_bf16 v[52:55], v[208:211], v[172:175], v[52:55]
	v_mfma_f32_16x16x32_bf16 v[48:51], v[216:219], v[172:175], v[48:51]
	v_mfma_f32_16x16x32_bf16 v[36:39], v[208:211], v[180:183], v[36:39]
	v_mfma_f32_16x16x32_bf16 v[32:35], v[216:219], v[180:183], v[32:35]
	v_mfma_f32_16x16x32_bf16 v[20:23], v[208:211], v[188:191], v[20:23]
	v_mfma_f32_16x16x32_bf16 v[16:19], v[216:219], v[188:191], v[16:19]
	v_mfma_f32_16x16x32_bf16 v[4:7], v[208:211], v[196:199], v[4:7]
	v_mfma_f32_16x16x32_bf16 v[0:3], v[216:219], v[196:199], v[0:3]
	s_setprio 0
	s_add_i32 s53, 0, 0x18000
	v_add_u32_e32 v164, s53, v147
	s_barrier
	ds_read_b128 v[152:155], v164
	ds_read_b128 v[156:159], v164 offset:1024
	ds_read_b128 v[160:163], v164 offset:2048
	ds_read_b128 v[164:167], v164 offset:3072
	s_add_u32 s26, s26, 0x80000
	s_addc_u32 s27, s27, 0
	s_mov_b32 m0, s36
	v_lshl_add_u64 v[204:205], s[26:27], 0, v[134:135]
	ds_read_b128 v[168:171], v150 offset:32768
	ds_read_b128 v[172:175], v150 offset:33792
	ds_read_b128 v[176:179], v150 offset:34816
	ds_read_b128 v[180:183], v150 offset:35840
	ds_read_b128 v[184:187], v150 offset:36864
	ds_read_b128 v[188:191], v150 offset:37888
	ds_read_b128 v[192:195], v150 offset:38912
	ds_read_b128 v[196:199], v150 offset:39936
	global_load_lds_dwordx4 v[204:205], off
	v_lshl_add_u64 v[204:205], s[26:27], 0, v[130:131]
	s_mov_b32 m0, s37
	s_nop 0
	global_load_lds_dwordx4 v[204:205], off
	s_waitcnt lgkmcnt(8)
	s_barrier
	s_waitcnt lgkmcnt(0)
	s_setprio 1
	s_waitcnt lgkmcnt(0)
	v_mfma_f32_16x16x32_bf16 v[124:127], v[152:155], v[168:171], v[124:127]
	v_mfma_f32_16x16x32_bf16 v[120:123], v[160:163], v[168:171], v[120:123]
	v_mfma_f32_16x16x32_bf16 v[108:111], v[152:155], v[176:179], v[108:111]
	v_mfma_f32_16x16x32_bf16 v[104:107], v[160:163], v[176:179], v[104:107]
	v_mfma_f32_16x16x32_bf16 v[92:95], v[152:155], v[184:187], v[92:95]
	v_mfma_f32_16x16x32_bf16 v[88:91], v[160:163], v[184:187], v[88:91]
	v_mfma_f32_16x16x32_bf16 v[76:79], v[152:155], v[192:195], v[76:79]
	v_mfma_f32_16x16x32_bf16 v[72:75], v[160:163], v[192:195], v[72:75]
	v_mfma_f32_16x16x32_bf16 v[124:127], v[156:159], v[172:175], v[124:127]
	v_mfma_f32_16x16x32_bf16 v[120:123], v[164:167], v[172:175], v[120:123]
	v_mfma_f32_16x16x32_bf16 v[108:111], v[156:159], v[180:183], v[108:111]
	v_mfma_f32_16x16x32_bf16 v[104:107], v[164:167], v[180:183], v[104:107]
	v_mfma_f32_16x16x32_bf16 v[92:95], v[156:159], v[188:191], v[92:95]
	v_mfma_f32_16x16x32_bf16 v[88:91], v[164:167], v[188:191], v[88:91]
	v_mfma_f32_16x16x32_bf16 v[76:79], v[156:159], v[196:199], v[76:79]
	v_mfma_f32_16x16x32_bf16 v[72:75], v[164:167], v[196:199], v[72:75]
	s_setprio 0
	s_barrier
	s_add_i32 s26, 0, 0x1c000
	s_add_i32 s27, s53, s31
	v_add_u32_e32 v216, s26, v147
	v_lshl_add_u64 v[144:145], v[144:145], 0, s[0:1]
	s_mov_b32 m0, s27
	ds_read_b128 v[204:207], v216
	ds_read_b128 v[208:211], v216 offset:1024
	ds_read_b128 v[212:215], v216 offset:2048
	ds_read_b128 v[216:219], v216 offset:3072
	global_load_lds_dwordx4 v[144:145], off
	v_lshl_add_u64 v[144:145], v[200:201], 0, s[0:1]
	s_add_i32 m0, s27, 0x2000
	s_nop 0
	global_load_lds_dwordx4 v[144:145], off
	s_barrier
	s_waitcnt lgkmcnt(0)
	s_setprio 1
	s_waitcnt lgkmcnt(0)
	v_mfma_f32_16x16x32_bf16 v[116:119], v[204:207], v[168:171], v[116:119]
	v_mfma_f32_16x16x32_bf16 v[112:115], v[212:215], v[168:171], v[112:115]
	v_mfma_f32_16x16x32_bf16 v[100:103], v[204:207], v[176:179], v[100:103]
	v_mfma_f32_16x16x32_bf16 v[96:99], v[212:215], v[176:179], v[96:99]
	v_mfma_f32_16x16x32_bf16 v[84:87], v[204:207], v[184:187], v[84:87]
	v_mfma_f32_16x16x32_bf16 v[80:83], v[212:215], v[184:187], v[80:83]
	v_mfma_f32_16x16x32_bf16 v[68:71], v[204:207], v[192:195], v[68:71]
	v_mfma_f32_16x16x32_bf16 v[64:67], v[212:215], v[192:195], v[64:67]
	v_mfma_f32_16x16x32_bf16 v[116:119], v[208:211], v[172:175], v[116:119]
	v_mfma_f32_16x16x32_bf16 v[112:115], v[216:219], v[172:175], v[112:115]
	v_mfma_f32_16x16x32_bf16 v[100:103], v[208:211], v[180:183], v[100:103]
	v_mfma_f32_16x16x32_bf16 v[96:99], v[216:219], v[180:183], v[96:99]
	v_mfma_f32_16x16x32_bf16 v[84:87], v[208:211], v[188:191], v[84:87]
	v_mfma_f32_16x16x32_bf16 v[80:83], v[216:219], v[188:191], v[80:83]
	v_mfma_f32_16x16x32_bf16 v[68:71], v[208:211], v[196:199], v[68:71]
	v_mfma_f32_16x16x32_bf16 v[64:67], v[216:219], v[196:199], v[64:67]
	s_setprio 0
	s_mov_b32 m0, s39
	v_lshl_add_u64 v[144:145], v[220:221], 0, s[0:1]
	s_barrier
	ds_read_b128 v[168:171], v150 offset:49152
	ds_read_b128 v[172:175], v150 offset:50176
	ds_read_b128 v[176:179], v150 offset:51200
	ds_read_b128 v[180:183], v150 offset:52224
	ds_read_b128 v[184:187], v150 offset:53248
	ds_read_b128 v[188:191], v150 offset:54272
	ds_read_b128 v[192:195], v150 offset:55296
	ds_read_b128 v[196:199], v150 offset:56320
	global_load_lds_dwordx4 v[144:145], off
	v_lshl_add_u64 v[144:145], v[222:223], 0, s[0:1]
	s_mov_b32 m0, s40
	s_nop 0
	global_load_lds_dwordx4 v[144:145], off
	s_barrier
	s_waitcnt lgkmcnt(0)
	s_setprio 1
	s_waitcnt lgkmcnt(0)
	v_mfma_f32_16x16x32_bf16 v[60:63], v[152:155], v[168:171], v[60:63]
	v_mfma_f32_16x16x32_bf16 v[56:59], v[160:163], v[168:171], v[56:59]
	v_mfma_f32_16x16x32_bf16 v[44:47], v[152:155], v[176:179], v[44:47]
	v_mfma_f32_16x16x32_bf16 v[40:43], v[160:163], v[176:179], v[40:43]
	v_mfma_f32_16x16x32_bf16 v[28:31], v[152:155], v[184:187], v[28:31]
	v_mfma_f32_16x16x32_bf16 v[24:27], v[160:163], v[184:187], v[24:27]
	v_mfma_f32_16x16x32_bf16 v[12:15], v[152:155], v[192:195], v[12:15]
	v_mfma_f32_16x16x32_bf16 v[8:11], v[160:163], v[192:195], v[8:11]
	v_mfma_f32_16x16x32_bf16 v[60:63], v[156:159], v[172:175], v[60:63]
	v_mfma_f32_16x16x32_bf16 v[56:59], v[164:167], v[172:175], v[56:59]
	v_mfma_f32_16x16x32_bf16 v[44:47], v[156:159], v[180:183], v[44:47]
	v_mfma_f32_16x16x32_bf16 v[40:43], v[164:167], v[180:183], v[40:43]
	v_mfma_f32_16x16x32_bf16 v[28:31], v[156:159], v[188:191], v[28:31]
	v_mfma_f32_16x16x32_bf16 v[24:27], v[164:167], v[188:191], v[24:27]
	v_mfma_f32_16x16x32_bf16 v[12:15], v[156:159], v[196:199], v[12:15]
	v_mfma_f32_16x16x32_bf16 v[8:11], v[164:167], v[196:199], v[8:11]
	s_setprio 0
	s_barrier
	s_add_u32 s24, s24, 0x20080
	s_addc_u32 s25, s25, 0
	s_add_i32 s26, s26, s31
	v_lshl_add_u64 v[144:145], s[24:25], 0, v[132:133]
	s_mov_b32 m0, s26
	s_nop 0
	global_load_lds_dwordx4 v[144:145], off
	v_lshl_add_u64 v[144:145], s[24:25], 0, v[128:129]
	s_add_i32 m0, s26, 0x2000
	s_nop 0
	global_load_lds_dwordx4 v[144:145], off
	s_waitcnt vmcnt(6)
	s_barrier
	s_setprio 1
	v_mfma_f32_16x16x32_bf16 v[52:55], v[204:207], v[168:171], v[52:55]
	v_mfma_f32_16x16x32_bf16 v[48:51], v[212:215], v[168:171], v[48:51]
	v_mfma_f32_16x16x32_bf16 v[36:39], v[204:207], v[176:179], v[36:39]
	v_mfma_f32_16x16x32_bf16 v[32:35], v[212:215], v[176:179], v[32:35]
	v_mfma_f32_16x16x32_bf16 v[20:23], v[204:207], v[184:187], v[20:23]
	v_mfma_f32_16x16x32_bf16 v[16:19], v[212:215], v[184:187], v[16:19]
	v_mfma_f32_16x16x32_bf16 v[4:7], v[204:207], v[192:195], v[4:7]
	v_mfma_f32_16x16x32_bf16 v[0:3], v[212:215], v[192:195], v[0:3]
	v_mfma_f32_16x16x32_bf16 v[52:55], v[208:211], v[172:175], v[52:55]
	v_mfma_f32_16x16x32_bf16 v[48:51], v[216:219], v[172:175], v[48:51]
	v_mfma_f32_16x16x32_bf16 v[36:39], v[208:211], v[180:183], v[36:39]
	v_mfma_f32_16x16x32_bf16 v[32:35], v[216:219], v[180:183], v[32:35]
	v_mfma_f32_16x16x32_bf16 v[20:23], v[208:211], v[188:191], v[20:23]
	v_mfma_f32_16x16x32_bf16 v[16:19], v[216:219], v[188:191], v[16:19]
	v_mfma_f32_16x16x32_bf16 v[4:7], v[208:211], v[196:199], v[4:7]
	v_mfma_f32_16x16x32_bf16 v[0:3], v[216:219], v[196:199], v[0:3]
	s_setprio 0
	s_add_i32 s52, s52, 2
	s_add_u32 s22, s22, 0x100
	s_addc_u32 s23, s23, 0
	s_add_u32 s50, s50, 0x100
	s_addc_u32 s51, s51, 0
	s_cmp_gt_u32 s52, 29
	s_barrier
	s_cbranch_scc0 .LBB0_1564
	v_readlane_b32 s100, v248, 63
	v_readlane_b32 s101, v247, 0
	v_and_b32_e32 v242, 15, v202
	v_bfe_u32 v243, v202, 4, 2
	v_bfe_u32 v244, v202, 6, 2
	v_lshrrev_b32_e32 v245, 8, v202
	v_and_b32_e32 v240, 7, v242
	v_lshl_add_u32 v240, v245, 6, v240
	v_lshl_add_u32 v240, s20, 8, v240
	v_lshlrev_b32_e32 v240, 14, v240
	v_lshrrev_b32_e32 v241, 3, v242
	v_lshlrev_b32_e32 v241, 6, v241
	v_lshl_add_u32 v241, v244, 7, v241
	v_lshl_add_u32 v241, v243, 4, v241
	v_add_u32_e32 v240, v240, v241
	s_lshl_b32 s98, s47, 9
	v_add_u32_e32 v240, s98, v240
	v_max_f32_e32 v124, 0, v124
	v_max_f32_e32 v125, 0, v125
	v_max_f32_e32 v126, 0, v126
	v_max_f32_e32 v127, 0, v127
	v_max_f32_e32 v120, 0, v120
	v_max_f32_e32 v121, 0, v121
	v_max_f32_e32 v122, 0, v122
	v_max_f32_e32 v123, 0, v123
	v_pk_mul_f32 v[124:125], v[124:125], v[124:125]
	v_pk_mul_f32 v[126:127], v[126:127], v[126:127]
	v_pk_mul_f32 v[120:121], v[120:121], v[120:121]
	v_pk_mul_f32 v[122:123], v[122:123], v[122:123]
	v_cvt_pk_bf16_f32 v228, v124, v125
	v_cvt_pk_bf16_f32 v229, v126, v127
	v_cvt_pk_bf16_f32 v230, v120, v121
	v_cvt_pk_bf16_f32 v231, v122, v123
	v_max_f32_e32 v116, 0, v116
	v_max_f32_e32 v117, 0, v117
	v_max_f32_e32 v118, 0, v118
	v_max_f32_e32 v119, 0, v119
	v_max_f32_e32 v112, 0, v112
	v_max_f32_e32 v113, 0, v113
	v_max_f32_e32 v114, 0, v114
	v_max_f32_e32 v115, 0, v115
	v_pk_mul_f32 v[116:117], v[116:117], v[116:117]
	v_pk_mul_f32 v[118:119], v[118:119], v[118:119]
	v_pk_mul_f32 v[112:113], v[112:113], v[112:113]
	v_pk_mul_f32 v[114:115], v[114:115], v[114:115]
	v_cvt_pk_bf16_f32 v232, v116, v117
	v_cvt_pk_bf16_f32 v233, v118, v119
	v_cvt_pk_bf16_f32 v234, v112, v113
	v_cvt_pk_bf16_f32 v235, v114, v115
	v_mov_b32_e32 v236, v228
	v_mov_b32_e32 v237, v229
	v_mov_b32_e32 v238, v230
	v_mov_b32_e32 v239, v231
	v_mov_b32_dpp v228, v232 row_ror:8 row_mask:0xf bank_mask:0xc
	v_mov_b32_dpp v229, v233 row_ror:8 row_mask:0xf bank_mask:0xc
	v_mov_b32_dpp v230, v234 row_ror:8 row_mask:0xf bank_mask:0xc
	v_mov_b32_dpp v231, v235 row_ror:8 row_mask:0xf bank_mask:0xc
	v_mov_b32_dpp v232, v236 row_ror:8 row_mask:0xf bank_mask:0x3
	v_mov_b32_dpp v233, v237 row_ror:8 row_mask:0xf bank_mask:0x3
	v_mov_b32_dpp v234, v238 row_ror:8 row_mask:0xf bank_mask:0x3
	v_mov_b32_dpp v235, v239 row_ror:8 row_mask:0xf bank_mask:0x3
	global_store_dwordx4 v240, v[228:231], s[100:101]
	s_add_u32 s100, s100, 0x20000
	s_addc_u32 s101, s101, 0
	global_store_dwordx4 v240, v[232:235], s[100:101]
	v_max_f32_e32 v108, 0, v108
	v_max_f32_e32 v109, 0, v109
	v_max_f32_e32 v110, 0, v110
	v_max_f32_e32 v111, 0, v111
	v_max_f32_e32 v104, 0, v104
	v_max_f32_e32 v105, 0, v105
	v_max_f32_e32 v106, 0, v106
	v_max_f32_e32 v107, 0, v107
	v_pk_mul_f32 v[108:109], v[108:109], v[108:109]
	v_pk_mul_f32 v[110:111], v[110:111], v[110:111]
	v_pk_mul_f32 v[104:105], v[104:105], v[104:105]
	v_pk_mul_f32 v[106:107], v[106:107], v[106:107]
	v_cvt_pk_bf16_f32 v228, v108, v109
	v_cvt_pk_bf16_f32 v229, v110, v111
	v_cvt_pk_bf16_f32 v230, v104, v105
	v_cvt_pk_bf16_f32 v231, v106, v107
	v_max_f32_e32 v100, 0, v100
	v_max_f32_e32 v101, 0, v101
	v_max_f32_e32 v102, 0, v102
	v_max_f32_e32 v103, 0, v103
	v_max_f32_e32 v96, 0, v96
	v_max_f32_e32 v97, 0, v97
	v_max_f32_e32 v98, 0, v98
	v_max_f32_e32 v99, 0, v99
	v_pk_mul_f32 v[100:101], v[100:101], v[100:101]
	v_pk_mul_f32 v[102:103], v[102:103], v[102:103]
	v_pk_mul_f32 v[96:97], v[96:97], v[96:97]
	v_pk_mul_f32 v[98:99], v[98:99], v[98:99]
	v_cvt_pk_bf16_f32 v232, v100, v101
	v_cvt_pk_bf16_f32 v233, v102, v103
	v_cvt_pk_bf16_f32 v234, v96, v97
	v_cvt_pk_bf16_f32 v235, v98, v99
	v_mov_b32_e32 v236, v228
	v_mov_b32_e32 v237, v229
	v_mov_b32_e32 v238, v230
	v_mov_b32_e32 v239, v231
	v_mov_b32_dpp v228, v232 row_ror:8 row_mask:0xf bank_mask:0xc
	v_mov_b32_dpp v229, v233 row_ror:8 row_mask:0xf bank_mask:0xc
	v_mov_b32_dpp v230, v234 row_ror:8 row_mask:0xf bank_mask:0xc
	v_mov_b32_dpp v231, v235 row_ror:8 row_mask:0xf bank_mask:0xc
	v_mov_b32_dpp v232, v236 row_ror:8 row_mask:0xf bank_mask:0x3
	v_mov_b32_dpp v233, v237 row_ror:8 row_mask:0xf bank_mask:0x3
	v_mov_b32_dpp v234, v238 row_ror:8 row_mask:0xf bank_mask:0x3
	v_mov_b32_dpp v235, v239 row_ror:8 row_mask:0xf bank_mask:0x3
	s_add_u32 s100, s100, 0x20000
	s_addc_u32 s101, s101, 0
	global_store_dwordx4 v240, v[228:231], s[100:101]
	s_add_u32 s100, s100, 0x20000
	s_addc_u32 s101, s101, 0
	global_store_dwordx4 v240, v[232:235], s[100:101]
	v_max_f32_e32 v92, 0, v92
	v_max_f32_e32 v93, 0, v93
	v_max_f32_e32 v94, 0, v94
	v_max_f32_e32 v95, 0, v95
	v_max_f32_e32 v88, 0, v88
	v_max_f32_e32 v89, 0, v89
	v_max_f32_e32 v90, 0, v90
	v_max_f32_e32 v91, 0, v91
	v_pk_mul_f32 v[92:93], v[92:93], v[92:93]
	v_pk_mul_f32 v[94:95], v[94:95], v[94:95]
	v_pk_mul_f32 v[88:89], v[88:89], v[88:89]
	v_pk_mul_f32 v[90:91], v[90:91], v[90:91]
	v_cvt_pk_bf16_f32 v228, v92, v93
	v_cvt_pk_bf16_f32 v229, v94, v95
	v_cvt_pk_bf16_f32 v230, v88, v89
	v_cvt_pk_bf16_f32 v231, v90, v91
	v_max_f32_e32 v84, 0, v84
	v_max_f32_e32 v85, 0, v85
	v_max_f32_e32 v86, 0, v86
	v_max_f32_e32 v87, 0, v87
	v_max_f32_e32 v80, 0, v80
	v_max_f32_e32 v81, 0, v81
	v_max_f32_e32 v82, 0, v82
	v_max_f32_e32 v83, 0, v83
	v_pk_mul_f32 v[84:85], v[84:85], v[84:85]
	v_pk_mul_f32 v[86:87], v[86:87], v[86:87]
	v_pk_mul_f32 v[80:81], v[80:81], v[80:81]
	v_pk_mul_f32 v[82:83], v[82:83], v[82:83]
	v_cvt_pk_bf16_f32 v232, v84, v85
	v_cvt_pk_bf16_f32 v233, v86, v87
	v_cvt_pk_bf16_f32 v234, v80, v81
	v_cvt_pk_bf16_f32 v235, v82, v83
	v_mov_b32_e32 v236, v228
	v_mov_b32_e32 v237, v229
	v_mov_b32_e32 v238, v230
	v_mov_b32_e32 v239, v231
	v_mov_b32_dpp v228, v232 row_ror:8 row_mask:0xf bank_mask:0xc
	v_mov_b32_dpp v229, v233 row_ror:8 row_mask:0xf bank_mask:0xc
	v_mov_b32_dpp v230, v234 row_ror:8 row_mask:0xf bank_mask:0xc
	v_mov_b32_dpp v231, v235 row_ror:8 row_mask:0xf bank_mask:0xc
	v_mov_b32_dpp v232, v236 row_ror:8 row_mask:0xf bank_mask:0x3
	v_mov_b32_dpp v233, v237 row_ror:8 row_mask:0xf bank_mask:0x3
	v_mov_b32_dpp v234, v238 row_ror:8 row_mask:0xf bank_mask:0x3
	v_mov_b32_dpp v235, v239 row_ror:8 row_mask:0xf bank_mask:0x3
	s_add_u32 s100, s100, 0x20000
	s_addc_u32 s101, s101, 0
	global_store_dwordx4 v240, v[228:231], s[100:101]
	s_add_u32 s100, s100, 0x20000
	s_addc_u32 s101, s101, 0
	global_store_dwordx4 v240, v[232:235], s[100:101]
	v_max_f32_e32 v76, 0, v76
	v_max_f32_e32 v77, 0, v77
	v_max_f32_e32 v78, 0, v78
	v_max_f32_e32 v79, 0, v79
	v_max_f32_e32 v72, 0, v72
	v_max_f32_e32 v73, 0, v73
	v_max_f32_e32 v74, 0, v74
	v_max_f32_e32 v75, 0, v75
	v_pk_mul_f32 v[76:77], v[76:77], v[76:77]
	v_pk_mul_f32 v[78:79], v[78:79], v[78:79]
	v_pk_mul_f32 v[72:73], v[72:73], v[72:73]
	v_pk_mul_f32 v[74:75], v[74:75], v[74:75]
	v_cvt_pk_bf16_f32 v228, v76, v77
	v_cvt_pk_bf16_f32 v229, v78, v79
	v_cvt_pk_bf16_f32 v230, v72, v73
	v_cvt_pk_bf16_f32 v231, v74, v75
	v_max_f32_e32 v68, 0, v68
	v_max_f32_e32 v69, 0, v69
	v_max_f32_e32 v70, 0, v70
	v_max_f32_e32 v71, 0, v71
	v_max_f32_e32 v64, 0, v64
	v_max_f32_e32 v65, 0, v65
	v_max_f32_e32 v66, 0, v66
	v_max_f32_e32 v67, 0, v67
	v_pk_mul_f32 v[68:69], v[68:69], v[68:69]
	v_pk_mul_f32 v[70:71], v[70:71], v[70:71]
	v_pk_mul_f32 v[64:65], v[64:65], v[64:65]
	v_pk_mul_f32 v[66:67], v[66:67], v[66:67]
	v_cvt_pk_bf16_f32 v232, v68, v69
	v_cvt_pk_bf16_f32 v233, v70, v71
	v_cvt_pk_bf16_f32 v234, v64, v65
	v_cvt_pk_bf16_f32 v235, v66, v67
	v_mov_b32_e32 v236, v228
	v_mov_b32_e32 v237, v229
	v_mov_b32_e32 v238, v230
	v_mov_b32_e32 v239, v231
	v_mov_b32_dpp v228, v232 row_ror:8 row_mask:0xf bank_mask:0xc
	v_mov_b32_dpp v229, v233 row_ror:8 row_mask:0xf bank_mask:0xc
	v_mov_b32_dpp v230, v234 row_ror:8 row_mask:0xf bank_mask:0xc
	v_mov_b32_dpp v231, v235 row_ror:8 row_mask:0xf bank_mask:0xc
	v_mov_b32_dpp v232, v236 row_ror:8 row_mask:0xf bank_mask:0x3
	v_mov_b32_dpp v233, v237 row_ror:8 row_mask:0xf bank_mask:0x3
	v_mov_b32_dpp v234, v238 row_ror:8 row_mask:0xf bank_mask:0x3
	v_mov_b32_dpp v235, v239 row_ror:8 row_mask:0xf bank_mask:0x3
	s_add_u32 s100, s100, 0x20000
	s_addc_u32 s101, s101, 0
	global_store_dwordx4 v240, v[228:231], s[100:101]
	s_add_u32 s100, s100, 0x20000
	s_addc_u32 s101, s101, 0
	global_store_dwordx4 v240, v[232:235], s[100:101]
	v_max_f32_e32 v60, 0, v60
	v_max_f32_e32 v61, 0, v61
	v_max_f32_e32 v62, 0, v62
	v_max_f32_e32 v63, 0, v63
	v_max_f32_e32 v56, 0, v56
	v_max_f32_e32 v57, 0, v57
	v_max_f32_e32 v58, 0, v58
	v_max_f32_e32 v59, 0, v59
	v_pk_mul_f32 v[60:61], v[60:61], v[60:61]
	v_pk_mul_f32 v[62:63], v[62:63], v[62:63]
	v_pk_mul_f32 v[56:57], v[56:57], v[56:57]
	v_pk_mul_f32 v[58:59], v[58:59], v[58:59]
	v_cvt_pk_bf16_f32 v228, v60, v61
	v_cvt_pk_bf16_f32 v229, v62, v63
	v_cvt_pk_bf16_f32 v230, v56, v57
	v_cvt_pk_bf16_f32 v231, v58, v59
	v_max_f32_e32 v52, 0, v52
	v_max_f32_e32 v53, 0, v53
	v_max_f32_e32 v54, 0, v54
	v_max_f32_e32 v55, 0, v55
	v_max_f32_e32 v48, 0, v48
	v_max_f32_e32 v49, 0, v49
	v_max_f32_e32 v50, 0, v50
	v_max_f32_e32 v51, 0, v51
	v_pk_mul_f32 v[52:53], v[52:53], v[52:53]
	v_pk_mul_f32 v[54:55], v[54:55], v[54:55]
	v_pk_mul_f32 v[48:49], v[48:49], v[48:49]
	v_pk_mul_f32 v[50:51], v[50:51], v[50:51]
	v_cvt_pk_bf16_f32 v232, v52, v53
	v_cvt_pk_bf16_f32 v233, v54, v55
	v_cvt_pk_bf16_f32 v234, v48, v49
	v_cvt_pk_bf16_f32 v235, v50, v51
	v_mov_b32_e32 v236, v228
	v_mov_b32_e32 v237, v229
	v_mov_b32_e32 v238, v230
	v_mov_b32_e32 v239, v231
	v_mov_b32_dpp v228, v232 row_ror:8 row_mask:0xf bank_mask:0xc
	v_mov_b32_dpp v229, v233 row_ror:8 row_mask:0xf bank_mask:0xc
	v_mov_b32_dpp v230, v234 row_ror:8 row_mask:0xf bank_mask:0xc
	v_mov_b32_dpp v231, v235 row_ror:8 row_mask:0xf bank_mask:0xc
	v_mov_b32_dpp v232, v236 row_ror:8 row_mask:0xf bank_mask:0x3
	v_mov_b32_dpp v233, v237 row_ror:8 row_mask:0xf bank_mask:0x3
	v_mov_b32_dpp v234, v238 row_ror:8 row_mask:0xf bank_mask:0x3
	v_mov_b32_dpp v235, v239 row_ror:8 row_mask:0xf bank_mask:0x3
	s_add_u32 s100, s100, 0x120000
	s_addc_u32 s101, s101, 0
	global_store_dwordx4 v240, v[228:231], s[100:101]
	s_add_u32 s100, s100, 0x20000
	s_addc_u32 s101, s101, 0
	global_store_dwordx4 v240, v[232:235], s[100:101]
	v_max_f32_e32 v44, 0, v44
	v_max_f32_e32 v45, 0, v45
	v_max_f32_e32 v46, 0, v46
	v_max_f32_e32 v47, 0, v47
	v_max_f32_e32 v40, 0, v40
	v_max_f32_e32 v41, 0, v41
	v_max_f32_e32 v42, 0, v42
	v_max_f32_e32 v43, 0, v43
	v_pk_mul_f32 v[44:45], v[44:45], v[44:45]
	v_pk_mul_f32 v[46:47], v[46:47], v[46:47]
	v_pk_mul_f32 v[40:41], v[40:41], v[40:41]
	v_pk_mul_f32 v[42:43], v[42:43], v[42:43]
	v_cvt_pk_bf16_f32 v228, v44, v45
	v_cvt_pk_bf16_f32 v229, v46, v47
	v_cvt_pk_bf16_f32 v230, v40, v41
	v_cvt_pk_bf16_f32 v231, v42, v43
	v_max_f32_e32 v36, 0, v36
	v_max_f32_e32 v37, 0, v37
	v_max_f32_e32 v38, 0, v38
	v_max_f32_e32 v39, 0, v39
	v_max_f32_e32 v32, 0, v32
	v_max_f32_e32 v33, 0, v33
	v_max_f32_e32 v34, 0, v34
	v_max_f32_e32 v35, 0, v35
	v_pk_mul_f32 v[36:37], v[36:37], v[36:37]
	v_pk_mul_f32 v[38:39], v[38:39], v[38:39]
	v_pk_mul_f32 v[32:33], v[32:33], v[32:33]
	v_pk_mul_f32 v[34:35], v[34:35], v[34:35]
	v_cvt_pk_bf16_f32 v232, v36, v37
	v_cvt_pk_bf16_f32 v233, v38, v39
	v_cvt_pk_bf16_f32 v234, v32, v33
	v_cvt_pk_bf16_f32 v235, v34, v35
	v_mov_b32_e32 v236, v228
	v_mov_b32_e32 v237, v229
	v_mov_b32_e32 v238, v230
	v_mov_b32_e32 v239, v231
	v_mov_b32_dpp v228, v232 row_ror:8 row_mask:0xf bank_mask:0xc
	v_mov_b32_dpp v229, v233 row_ror:8 row_mask:0xf bank_mask:0xc
	v_mov_b32_dpp v230, v234 row_ror:8 row_mask:0xf bank_mask:0xc
	v_mov_b32_dpp v231, v235 row_ror:8 row_mask:0xf bank_mask:0xc
	v_mov_b32_dpp v232, v236 row_ror:8 row_mask:0xf bank_mask:0x3
	v_mov_b32_dpp v233, v237 row_ror:8 row_mask:0xf bank_mask:0x3
	v_mov_b32_dpp v234, v238 row_ror:8 row_mask:0xf bank_mask:0x3
	v_mov_b32_dpp v235, v239 row_ror:8 row_mask:0xf bank_mask:0x3
	s_add_u32 s100, s100, 0x20000
	s_addc_u32 s101, s101, 0
	global_store_dwordx4 v240, v[228:231], s[100:101]
	s_add_u32 s100, s100, 0x20000
	s_addc_u32 s101, s101, 0
	global_store_dwordx4 v240, v[232:235], s[100:101]
	v_max_f32_e32 v28, 0, v28
	v_max_f32_e32 v29, 0, v29
	v_max_f32_e32 v30, 0, v30
	v_max_f32_e32 v31, 0, v31
	v_max_f32_e32 v24, 0, v24
	v_max_f32_e32 v25, 0, v25
	v_max_f32_e32 v26, 0, v26
	v_max_f32_e32 v27, 0, v27
	v_pk_mul_f32 v[28:29], v[28:29], v[28:29]
	v_pk_mul_f32 v[30:31], v[30:31], v[30:31]
	v_pk_mul_f32 v[24:25], v[24:25], v[24:25]
	v_pk_mul_f32 v[26:27], v[26:27], v[26:27]
	v_cvt_pk_bf16_f32 v228, v28, v29
	v_cvt_pk_bf16_f32 v229, v30, v31
	v_cvt_pk_bf16_f32 v230, v24, v25
	v_cvt_pk_bf16_f32 v231, v26, v27
	v_max_f32_e32 v20, 0, v20
	v_max_f32_e32 v21, 0, v21
	v_max_f32_e32 v22, 0, v22
	v_max_f32_e32 v23, 0, v23
	v_max_f32_e32 v16, 0, v16
	v_max_f32_e32 v17, 0, v17
	v_max_f32_e32 v18, 0, v18
	v_max_f32_e32 v19, 0, v19
	v_pk_mul_f32 v[20:21], v[20:21], v[20:21]
	v_pk_mul_f32 v[22:23], v[22:23], v[22:23]
	v_pk_mul_f32 v[16:17], v[16:17], v[16:17]
	v_pk_mul_f32 v[18:19], v[18:19], v[18:19]
	v_cvt_pk_bf16_f32 v232, v20, v21
	v_cvt_pk_bf16_f32 v233, v22, v23
	v_cvt_pk_bf16_f32 v234, v16, v17
	v_cvt_pk_bf16_f32 v235, v18, v19
	v_mov_b32_e32 v236, v228
	v_mov_b32_e32 v237, v229
	v_mov_b32_e32 v238, v230
	v_mov_b32_e32 v239, v231
	v_mov_b32_dpp v228, v232 row_ror:8 row_mask:0xf bank_mask:0xc
	v_mov_b32_dpp v229, v233 row_ror:8 row_mask:0xf bank_mask:0xc
	v_mov_b32_dpp v230, v234 row_ror:8 row_mask:0xf bank_mask:0xc
	v_mov_b32_dpp v231, v235 row_ror:8 row_mask:0xf bank_mask:0xc
	v_mov_b32_dpp v232, v236 row_ror:8 row_mask:0xf bank_mask:0x3
	v_mov_b32_dpp v233, v237 row_ror:8 row_mask:0xf bank_mask:0x3
	v_mov_b32_dpp v234, v238 row_ror:8 row_mask:0xf bank_mask:0x3
	v_mov_b32_dpp v235, v239 row_ror:8 row_mask:0xf bank_mask:0x3
	s_add_u32 s100, s100, 0x20000
	s_addc_u32 s101, s101, 0
	global_store_dwordx4 v240, v[228:231], s[100:101]
	s_add_u32 s100, s100, 0x20000
	s_addc_u32 s101, s101, 0
	global_store_dwordx4 v240, v[232:235], s[100:101]
	v_max_f32_e32 v12, 0, v12
	v_max_f32_e32 v13, 0, v13
	v_max_f32_e32 v14, 0, v14
	v_max_f32_e32 v15, 0, v15
	v_max_f32_e32 v8, 0, v8
	v_max_f32_e32 v9, 0, v9
	v_max_f32_e32 v10, 0, v10
	v_max_f32_e32 v11, 0, v11
	v_pk_mul_f32 v[12:13], v[12:13], v[12:13]
	v_pk_mul_f32 v[14:15], v[14:15], v[14:15]
	v_pk_mul_f32 v[8:9], v[8:9], v[8:9]
	v_pk_mul_f32 v[10:11], v[10:11], v[10:11]
	v_cvt_pk_bf16_f32 v228, v12, v13
	v_cvt_pk_bf16_f32 v229, v14, v15
	v_cvt_pk_bf16_f32 v230, v8, v9
	v_cvt_pk_bf16_f32 v231, v10, v11
	v_max_f32_e32 v4, 0, v4
	v_max_f32_e32 v5, 0, v5
	v_max_f32_e32 v6, 0, v6
	v_max_f32_e32 v7, 0, v7
	v_max_f32_e32 v0, 0, v0
	v_max_f32_e32 v1, 0, v1
	v_max_f32_e32 v2, 0, v2
	v_max_f32_e32 v3, 0, v3
	v_pk_mul_f32 v[4:5], v[4:5], v[4:5]
	v_pk_mul_f32 v[6:7], v[6:7], v[6:7]
	v_pk_mul_f32 v[0:1], v[0:1], v[0:1]
	v_pk_mul_f32 v[2:3], v[2:3], v[2:3]
	v_cvt_pk_bf16_f32 v232, v4, v5
	v_cvt_pk_bf16_f32 v233, v6, v7
	v_cvt_pk_bf16_f32 v234, v0, v1
	v_cvt_pk_bf16_f32 v235, v2, v3
	v_mov_b32_e32 v236, v228
	v_mov_b32_e32 v237, v229
	v_mov_b32_e32 v238, v230
	v_mov_b32_e32 v239, v231
	v_mov_b32_dpp v228, v232 row_ror:8 row_mask:0xf bank_mask:0xc
	v_mov_b32_dpp v229, v233 row_ror:8 row_mask:0xf bank_mask:0xc
	v_mov_b32_dpp v230, v234 row_ror:8 row_mask:0xf bank_mask:0xc
	v_mov_b32_dpp v231, v235 row_ror:8 row_mask:0xf bank_mask:0xc
	v_mov_b32_dpp v232, v236 row_ror:8 row_mask:0xf bank_mask:0x3
	v_mov_b32_dpp v233, v237 row_ror:8 row_mask:0xf bank_mask:0x3
	v_mov_b32_dpp v234, v238 row_ror:8 row_mask:0xf bank_mask:0x3
	v_mov_b32_dpp v235, v239 row_ror:8 row_mask:0xf bank_mask:0x3
	s_add_u32 s100, s100, 0x20000
	s_addc_u32 s101, s101, 0
	global_store_dwordx4 v240, v[228:231], s[100:101]
	s_add_u32 s100, s100, 0x20000
	s_addc_u32 s101, s101, 0
	global_store_dwordx4 v240, v[232:235], s[100:101]
	s_and_b64 vcc, exec, s[2:3]
	s_mov_b32 s47, s12
	s_mov_b32 s20, s14
	s_mov_b64 s[24:25], s[18:19]
	s_mov_b64 s[22:23], s[16:17]
	s_cbranch_vccz .LBB0_1561
	s_waitcnt vmcnt(0)
	s_cmpk_gt_u32 s28, 0xff
	s_cbranch_scc1 .LBB0_1568
	s_barrier
